# baseline (speedup 1.0000x reference)
.LBB0_110:
	ds_read_b128 v[156:159], v192
	ds_read_b128 v[160:163], v192 offset:1024
	ds_read_b128 v[194:197], v191
	ds_read_b128 v[198:201], v191 offset:1024
	ds_read_b128 v[202:205], v190
	ds_read_b128 v[206:209], v190 offset:1024
	ds_read_b128 v[210:213], v189
	ds_read_b128 v[214:217], v189 offset:1024
	s_waitcnt lgkmcnt(8)
	s_waitcnt vmcnt(10)
	s_barrier
	s_waitcnt lgkmcnt(0)
	s_waitcnt lgkmcnt(0)
	v_mfma_f32_16x16x32_bf16 v[124:127], v[140:143], v[156:159], v[124:127]
	v_mfma_f32_16x16x32_bf16 v[120:123], v[148:151], v[156:159], v[120:123]
	v_mfma_f32_16x16x32_bf16 v[116:119], v[140:143], v[194:197], v[116:119]
	v_mfma_f32_16x16x32_bf16 v[112:115], v[148:151], v[194:197], v[112:115]
	v_mfma_f32_16x16x32_bf16 v[108:111], v[140:143], v[202:205], v[108:111]
	v_mfma_f32_16x16x32_bf16 v[104:107], v[148:151], v[202:205], v[104:107]
	v_mfma_f32_16x16x32_bf16 v[100:103], v[140:143], v[210:213], v[100:103]
	v_mfma_f32_16x16x32_bf16 v[96:99], v[148:151], v[210:213], v[96:99]
	v_mfma_f32_16x16x32_bf16 v[124:127], v[144:147], v[160:163], v[124:127]
	v_mfma_f32_16x16x32_bf16 v[120:123], v[152:155], v[160:163], v[120:123]
	v_mfma_f32_16x16x32_bf16 v[116:119], v[144:147], v[198:201], v[116:119]
	v_mfma_f32_16x16x32_bf16 v[112:115], v[152:155], v[198:201], v[112:115]
	v_mfma_f32_16x16x32_bf16 v[108:111], v[144:147], v[206:209], v[108:111]
	v_mfma_f32_16x16x32_bf16 v[104:107], v[152:155], v[206:209], v[104:107]
	v_mfma_f32_16x16x32_bf16 v[100:103], v[144:147], v[214:217], v[100:103]
	v_mfma_f32_16x16x32_bf16 v[96:99], v[152:155], v[214:217], v[96:99]
	s_barrier
	s_add_i32 s63, s98, 0x10000
	v_lshl_add_u64 v[234:235], s[66:67], 0, v[164:165]
	s_mov_b32 m0, s63
	s_add_i32 s63, s98, 0x12000
	ds_read_b128 v[218:221], v135
	ds_read_b128 v[222:225], v135 offset:1024
	ds_read_b128 v[226:229], v135 offset:2048
	ds_read_b128 v[230:233], v135 offset:3072
	global_load_lds_dwordx4 v[234:235], off
	v_lshl_add_u64 v[236:237], v[234:235], 0, s[10:11]
	s_mov_b32 m0, s63
	s_nop 0
	global_load_lds_dwordx4 v[236:237], off
	s_mov_b32 s63, s98
	v_lshl_add_u64 v[236:237], v[128:129], 0, s[26:27]
	s_mov_b32 m0, s63
	s_add_i32 s63, s98, 0x2000
	global_load_lds_dwordx4 v[236:237], off
	v_lshl_add_u64 v[236:237], v[128:129], 0, s[28:29]
	s_mov_b32 m0, s63
	s_nop 0
	global_load_lds_dwordx4 v[236:237], off
	s_waitcnt vmcnt(12)
	s_barrier
	s_waitcnt lgkmcnt(0)
	s_waitcnt lgkmcnt(0)
	v_mfma_f32_16x16x32_bf16 v[92:95], v[218:221], v[156:159], v[92:95]
	v_mfma_f32_16x16x32_bf16 v[88:91], v[226:229], v[156:159], v[88:91]
	v_mfma_f32_16x16x32_bf16 v[84:87], v[218:221], v[194:197], v[84:87]
	v_mfma_f32_16x16x32_bf16 v[80:83], v[226:229], v[194:197], v[80:83]
	v_mfma_f32_16x16x32_bf16 v[76:79], v[218:221], v[202:205], v[76:79]
	v_mfma_f32_16x16x32_bf16 v[72:75], v[226:229], v[202:205], v[72:75]
	v_mfma_f32_16x16x32_bf16 v[68:71], v[218:221], v[210:213], v[68:71]
	v_mfma_f32_16x16x32_bf16 v[64:67], v[226:229], v[210:213], v[64:67]
	v_mfma_f32_16x16x32_bf16 v[92:95], v[222:225], v[160:163], v[92:95]
	v_mfma_f32_16x16x32_bf16 v[88:91], v[230:233], v[160:163], v[88:91]
	v_mfma_f32_16x16x32_bf16 v[84:87], v[222:225], v[198:201], v[84:87]
	v_mfma_f32_16x16x32_bf16 v[80:83], v[230:233], v[198:201], v[80:83]
	v_mfma_f32_16x16x32_bf16 v[76:79], v[222:225], v[206:209], v[76:79]
	v_mfma_f32_16x16x32_bf16 v[72:75], v[230:233], v[206:209], v[72:75]
	v_mfma_f32_16x16x32_bf16 v[68:71], v[222:225], v[214:217], v[68:71]
	v_mfma_f32_16x16x32_bf16 v[64:67], v[230:233], v[214:217], v[64:67]
	s_barrier
	ds_read_b128 v[156:159], v192 offset:16384
	ds_read_b128 v[160:163], v192 offset:17408
	ds_read_b128 v[194:197], v191 offset:16384
	ds_read_b128 v[198:201], v191 offset:17408
	ds_read_b128 v[202:205], v190 offset:16384
	ds_read_b128 v[206:209], v190 offset:17408
	ds_read_b128 v[210:213], v189 offset:16384
	ds_read_b128 v[214:217], v189 offset:17408
	s_add_i32 s63, s98, 0x14000
	v_lshl_add_u64 v[236:237], v[234:235], 0, s[30:31]
	s_mov_b32 m0, s63
	s_add_i32 s63, s98, 0x16000
	global_load_lds_dwordx4 v[236:237], off
	v_lshl_add_u64 v[236:237], v[234:235], 0, s[34:35]
	s_mov_b32 m0, s63
	s_nop 0
	global_load_lds_dwordx4 v[236:237], off
	s_waitcnt vmcnt(12)
	s_barrier
	s_waitcnt lgkmcnt(0)
	s_waitcnt lgkmcnt(0)
	v_mfma_f32_16x16x32_bf16 v[60:63], v[140:143], v[156:159], v[60:63]
	v_mfma_f32_16x16x32_bf16 v[56:59], v[148:151], v[156:159], v[56:59]
	v_mfma_f32_16x16x32_bf16 v[52:55], v[140:143], v[194:197], v[52:55]
	v_mfma_f32_16x16x32_bf16 v[48:51], v[148:151], v[194:197], v[48:51]
	v_mfma_f32_16x16x32_bf16 v[44:47], v[140:143], v[202:205], v[44:47]
	v_mfma_f32_16x16x32_bf16 v[40:43], v[148:151], v[202:205], v[40:43]
	v_mfma_f32_16x16x32_bf16 v[36:39], v[140:143], v[210:213], v[36:39]
	v_mfma_f32_16x16x32_bf16 v[32:35], v[148:151], v[210:213], v[32:35]
	v_mfma_f32_16x16x32_bf16 v[60:63], v[144:147], v[160:163], v[60:63]
	v_mfma_f32_16x16x32_bf16 v[56:59], v[152:155], v[160:163], v[56:59]
	v_mfma_f32_16x16x32_bf16 v[52:55], v[144:147], v[198:201], v[52:55]
	v_mfma_f32_16x16x32_bf16 v[48:51], v[152:155], v[198:201], v[48:51]
	v_mfma_f32_16x16x32_bf16 v[44:47], v[144:147], v[206:209], v[44:47]
	v_mfma_f32_16x16x32_bf16 v[40:43], v[152:155], v[206:209], v[40:43]
	v_mfma_f32_16x16x32_bf16 v[36:39], v[144:147], v[214:217], v[36:39]
	v_mfma_f32_16x16x32_bf16 v[32:35], v[152:155], v[214:217], v[32:35]
	s_barrier
	s_add_i32 s63, s98, 0x4000
	v_lshl_add_u64 v[142:143], v[128:129], 0, s[40:41]
	s_mov_b32 m0, s63
	s_add_i32 s63, s98, 0x6000
	global_load_lds_dwordx4 v[142:143], off
	s_mov_b32 m0, s63
	s_nop 0
	global_load_lds_dwordx4 v[128:129], off
	ds_read_b128 v[140:143], v130
	ds_read_b128 v[144:147], v130 offset:1024
	ds_read_b128 v[148:151], v130 offset:2048
	ds_read_b128 v[152:155], v130 offset:3072
	s_waitcnt vmcnt(12)
	s_barrier
	v_mfma_f32_16x16x32_bf16 v[28:31], v[218:221], v[156:159], v[28:31]
	v_mfma_f32_16x16x32_bf16 v[24:27], v[226:229], v[156:159], v[24:27]
	v_mfma_f32_16x16x32_bf16 v[20:23], v[218:221], v[194:197], v[20:23]
	v_mfma_f32_16x16x32_bf16 v[16:19], v[226:229], v[194:197], v[16:19]
	v_mfma_f32_16x16x32_bf16 v[12:15], v[218:221], v[202:205], v[12:15]
	v_mfma_f32_16x16x32_bf16 v[8:11], v[226:229], v[202:205], v[8:11]
	v_mfma_f32_16x16x32_bf16 v[4:7], v[218:221], v[210:213], v[4:7]
	v_mfma_f32_16x16x32_bf16 v[0:3], v[226:229], v[210:213], v[0:3]
	v_mfma_f32_16x16x32_bf16 v[28:31], v[222:225], v[160:163], v[28:31]
	v_mfma_f32_16x16x32_bf16 v[24:27], v[230:233], v[160:163], v[24:27]
	v_mfma_f32_16x16x32_bf16 v[20:23], v[222:225], v[198:201], v[20:23]
	v_mfma_f32_16x16x32_bf16 v[16:19], v[230:233], v[198:201], v[16:19]
	v_mfma_f32_16x16x32_bf16 v[12:15], v[222:225], v[206:209], v[12:15]
	v_mfma_f32_16x16x32_bf16 v[8:11], v[230:233], v[206:209], v[8:11]
	v_mfma_f32_16x16x32_bf16 v[4:7], v[222:225], v[214:217], v[4:7]
	v_mfma_f32_16x16x32_bf16 v[0:3], v[230:233], v[214:217], v[0:3]
	s_barrier
	ds_read_b128 v[156:159], v192 offset:32768
	ds_read_b128 v[160:163], v192 offset:33792
	ds_read_b128 v[194:197], v191 offset:32768
	ds_read_b128 v[198:201], v191 offset:33792
	ds_read_b128 v[202:205], v190 offset:32768
	ds_read_b128 v[206:209], v190 offset:33792
	ds_read_b128 v[210:213], v189 offset:32768
	ds_read_b128 v[214:217], v189 offset:33792
	s_waitcnt lgkmcnt(8)
	s_waitcnt vmcnt(10)
	s_barrier
	s_waitcnt lgkmcnt(0)
	s_waitcnt lgkmcnt(0)
	v_mfma_f32_16x16x32_bf16 v[124:127], v[140:143], v[156:159], v[124:127]
	v_mfma_f32_16x16x32_bf16 v[120:123], v[148:151], v[156:159], v[120:123]
	v_mfma_f32_16x16x32_bf16 v[116:119], v[140:143], v[194:197], v[116:119]
	v_mfma_f32_16x16x32_bf16 v[112:115], v[148:151], v[194:197], v[112:115]
	v_mfma_f32_16x16x32_bf16 v[108:111], v[140:143], v[202:205], v[108:111]
	v_mfma_f32_16x16x32_bf16 v[104:107], v[148:151], v[202:205], v[104:107]
	v_mfma_f32_16x16x32_bf16 v[100:103], v[140:143], v[210:213], v[100:103]
	v_mfma_f32_16x16x32_bf16 v[96:99], v[148:151], v[210:213], v[96:99]
	v_mfma_f32_16x16x32_bf16 v[124:127], v[144:147], v[160:163], v[124:127]
	v_mfma_f32_16x16x32_bf16 v[120:123], v[152:155], v[160:163], v[120:123]
	v_mfma_f32_16x16x32_bf16 v[116:119], v[144:147], v[198:201], v[116:119]
	v_mfma_f32_16x16x32_bf16 v[112:115], v[152:155], v[198:201], v[112:115]
	v_mfma_f32_16x16x32_bf16 v[108:111], v[144:147], v[206:209], v[108:111]
	v_mfma_f32_16x16x32_bf16 v[104:107], v[152:155], v[206:209], v[104:107]
	v_mfma_f32_16x16x32_bf16 v[100:103], v[144:147], v[214:217], v[100:103]
	v_mfma_f32_16x16x32_bf16 v[96:99], v[152:155], v[214:217], v[96:99]
	s_barrier
	s_add_i32 s63, s98, 0x18000
	v_lshl_add_u64 v[234:235], s[64:65], 0, v[164:165]
	s_mov_b32 m0, s63
	s_add_i32 s63, s98, 0x1a000
	ds_read_b128 v[218:221], v132
	ds_read_b128 v[222:225], v132 offset:1024
	ds_read_b128 v[226:229], v132 offset:2048
	ds_read_b128 v[230:233], v132 offset:3072
	global_load_lds_dwordx4 v[234:235], off
	v_lshl_add_u64 v[236:237], v[234:235], 0, s[10:11]
	s_mov_b32 m0, s63
	s_nop 0
	global_load_lds_dwordx4 v[236:237], off
	s_add_i32 s63, s98, 0x8000
	v_lshl_add_u64 v[236:237], v[128:129], 0, s[44:45]
	s_mov_b32 m0, s63
	s_add_i32 s63, s98, 0xa000
	global_load_lds_dwordx4 v[236:237], off
	v_lshl_add_u64 v[236:237], v[128:129], 0, s[46:47]
	s_mov_b32 m0, s63
	s_nop 0
	global_load_lds_dwordx4 v[236:237], off
	s_waitcnt vmcnt(12)
	s_barrier
	s_waitcnt lgkmcnt(0)
	s_waitcnt lgkmcnt(0)
	v_mfma_f32_16x16x32_bf16 v[92:95], v[218:221], v[156:159], v[92:95]
	v_mfma_f32_16x16x32_bf16 v[88:91], v[226:229], v[156:159], v[88:91]
	v_mfma_f32_16x16x32_bf16 v[84:87], v[218:221], v[194:197], v[84:87]
	v_mfma_f32_16x16x32_bf16 v[80:83], v[226:229], v[194:197], v[80:83]
	v_mfma_f32_16x16x32_bf16 v[76:79], v[218:221], v[202:205], v[76:79]
	v_mfma_f32_16x16x32_bf16 v[72:75], v[226:229], v[202:205], v[72:75]
	v_mfma_f32_16x16x32_bf16 v[68:71], v[218:221], v[210:213], v[68:71]
	v_mfma_f32_16x16x32_bf16 v[64:67], v[226:229], v[210:213], v[64:67]
	v_mfma_f32_16x16x32_bf16 v[92:95], v[222:225], v[160:163], v[92:95]
	v_mfma_f32_16x16x32_bf16 v[88:91], v[230:233], v[160:163], v[88:91]
	v_mfma_f32_16x16x32_bf16 v[84:87], v[222:225], v[198:201], v[84:87]
	v_mfma_f32_16x16x32_bf16 v[80:83], v[230:233], v[198:201], v[80:83]
	v_mfma_f32_16x16x32_bf16 v[76:79], v[222:225], v[206:209], v[76:79]
	v_mfma_f32_16x16x32_bf16 v[72:75], v[230:233], v[206:209], v[72:75]
	v_mfma_f32_16x16x32_bf16 v[68:71], v[222:225], v[214:217], v[68:71]
	v_mfma_f32_16x16x32_bf16 v[64:67], v[230:233], v[214:217], v[64:67]
	s_barrier
	ds_read_b128 v[156:159], v192 offset:49152
	ds_read_b128 v[160:163], v192 offset:50176
	ds_read_b128 v[194:197], v191 offset:49152
	ds_read_b128 v[198:201], v191 offset:50176
	ds_read_b128 v[202:205], v190 offset:49152
	ds_read_b128 v[206:209], v190 offset:50176
	ds_read_b128 v[210:213], v189 offset:49152
	ds_read_b128 v[214:217], v189 offset:50176
	s_add_i32 s63, s98, 0x1c000
	v_lshl_add_u64 v[236:237], v[234:235], 0, s[30:31]
	s_mov_b32 m0, s63
	s_add_i32 s63, s98, 0x1e000
	global_load_lds_dwordx4 v[236:237], off
	v_lshl_add_u64 v[236:237], v[234:235], 0, s[34:35]
	s_mov_b32 m0, s63
	s_nop 0
	global_load_lds_dwordx4 v[236:237], off
	s_waitcnt vmcnt(12)
	s_barrier
	s_waitcnt lgkmcnt(0)
	s_waitcnt lgkmcnt(0)
	v_mfma_f32_16x16x32_bf16 v[60:63], v[140:143], v[156:159], v[60:63]
	v_mfma_f32_16x16x32_bf16 v[56:59], v[148:151], v[156:159], v[56:59]
	v_mfma_f32_16x16x32_bf16 v[52:55], v[140:143], v[194:197], v[52:55]
	v_mfma_f32_16x16x32_bf16 v[48:51], v[148:151], v[194:197], v[48:51]
	v_mfma_f32_16x16x32_bf16 v[44:47], v[140:143], v[202:205], v[44:47]
	v_mfma_f32_16x16x32_bf16 v[40:43], v[148:151], v[202:205], v[40:43]
	v_mfma_f32_16x16x32_bf16 v[36:39], v[140:143], v[210:213], v[36:39]
	v_mfma_f32_16x16x32_bf16 v[32:35], v[148:151], v[210:213], v[32:35]
	v_mfma_f32_16x16x32_bf16 v[60:63], v[144:147], v[160:163], v[60:63]
	v_mfma_f32_16x16x32_bf16 v[56:59], v[152:155], v[160:163], v[56:59]
	v_mfma_f32_16x16x32_bf16 v[52:55], v[144:147], v[198:201], v[52:55]
	v_mfma_f32_16x16x32_bf16 v[48:51], v[152:155], v[198:201], v[48:51]
	v_mfma_f32_16x16x32_bf16 v[44:47], v[144:147], v[206:209], v[44:47]
	v_mfma_f32_16x16x32_bf16 v[40:43], v[152:155], v[206:209], v[40:43]
	v_mfma_f32_16x16x32_bf16 v[36:39], v[144:147], v[214:217], v[36:39]
	v_mfma_f32_16x16x32_bf16 v[32:35], v[152:155], v[214:217], v[32:35]
	s_barrier
	v_lshl_add_u64 v[128:129], v[128:129], 0, s[56:57]
	s_add_i32 s63, s98, 0xc000
	v_lshl_add_u64 v[142:143], v[128:129], 0, s[22:23]
	s_mov_b32 m0, s63
	s_add_i32 s63, s98, 0xe000
	global_load_lds_dwordx4 v[142:143], off
	v_lshl_add_u64 v[142:143], v[128:129], 0, s[24:25]
	s_mov_b32 m0, s63
	s_nop 0
	global_load_lds_dwordx4 v[142:143], off
	ds_read_b128 v[140:143], v138
	ds_read_b128 v[144:147], v138 offset:1024
	ds_read_b128 v[148:151], v138 offset:2048
	ds_read_b128 v[152:155], v138 offset:3072
	s_waitcnt vmcnt(12)
	s_barrier
	v_mfma_f32_16x16x32_bf16 v[28:31], v[218:221], v[156:159], v[28:31]
	v_mfma_f32_16x16x32_bf16 v[24:27], v[226:229], v[156:159], v[24:27]
	v_mfma_f32_16x16x32_bf16 v[20:23], v[218:221], v[194:197], v[20:23]
	v_mfma_f32_16x16x32_bf16 v[16:19], v[226:229], v[194:197], v[16:19]
	v_mfma_f32_16x16x32_bf16 v[12:15], v[218:221], v[202:205], v[12:15]
	v_mfma_f32_16x16x32_bf16 v[8:11], v[226:229], v[202:205], v[8:11]
	v_mfma_f32_16x16x32_bf16 v[4:7], v[218:221], v[210:213], v[4:7]
	v_mfma_f32_16x16x32_bf16 v[0:3], v[226:229], v[210:213], v[0:3]
	v_mfma_f32_16x16x32_bf16 v[28:31], v[222:225], v[160:163], v[28:31]
	v_mfma_f32_16x16x32_bf16 v[24:27], v[230:233], v[160:163], v[24:27]
	v_mfma_f32_16x16x32_bf16 v[20:23], v[222:225], v[198:201], v[20:23]
	v_mfma_f32_16x16x32_bf16 v[16:19], v[230:233], v[198:201], v[16:19]
	v_mfma_f32_16x16x32_bf16 v[12:15], v[222:225], v[206:209], v[12:15]
	v_mfma_f32_16x16x32_bf16 v[8:11], v[230:233], v[206:209], v[8:11]
	v_mfma_f32_16x16x32_bf16 v[4:7], v[222:225], v[214:217], v[4:7]
	v_mfma_f32_16x16x32_bf16 v[0:3], v[230:233], v[214:217], v[0:3]
	s_add_i32 s4, s4, 2
	s_add_u32 s64, s64, s68
	s_addc_u32 s65, s65, s69
	s_add_u32 s66, s66, s68
	s_addc_u32 s67, s67, s69
	s_cmp_lt_u32 s4, 28
	s_barrier
	s_cbranch_scc1 .LBB0_110
	s_lshl_b32 s4, s70, 11
	s_or_b32 s64, s71, s4
	s_or_b32 s66, s64, 0x80
	v_lshlrev_b32_e32 v128, 3, v131
	v_lshlrev_b32_e32 v129, 5, v131
	s_ashr_i32 s67, s66, 31
	v_and_b32_e32 v128, 0xffff0, v128
	v_and_b32_e32 v129, 32, v129
	s_lshl_b64 s[66:67], s[66:67], 12
	v_add_u32_e32 v129, v129, v134
	v_add_lshl_u32 v128, v133, v128, 12
	s_add_u32 s66, s54, s66
	v_lshl_add_u32 v164, v129, 1, v128
	s_addc_u32 s67, s55, s67
	v_lshl_add_u64 v[128:129], s[66:67], 0, v[164:165]
	v_readfirstlane_b32 s4, v137
	ds_read_b128 v[140:143], v138
	ds_read_b128 v[144:147], v138 offset:1024
	ds_read_b128 v[148:151], v138 offset:2048
	ds_read_b128 v[152:155], v138 offset:3072
	ds_read_b128 v[156:159], v192
	ds_read_b128 v[160:163], v192 offset:1024
	ds_read_b128 v[194:197], v191
	ds_read_b128 v[198:201], v191 offset:1024
	ds_read_b128 v[202:205], v190
	ds_read_b128 v[206:209], v190 offset:1024
	ds_read_b128 v[210:213], v189
	ds_read_b128 v[214:217], v189 offset:1024
	v_lshl_add_u64 v[138:139], v[128:129], 0, s[58:59]
	s_mov_b32 m0, s4
	v_readfirstlane_b32 s4, v136
	v_lshl_add_u64 v[128:129], v[128:129], 0, s[60:61]
	s_mov_b32 m0, s4
	s_ashr_i32 s65, s64, 31
	s_waitcnt vmcnt(8)
	s_barrier
	s_waitcnt lgkmcnt(0)
	s_setprio 1
	s_waitcnt lgkmcnt(0)
	v_mfma_f32_16x16x32_bf16 v[124:127], v[140:143], v[156:159], v[124:127]
	v_mfma_f32_16x16x32_bf16 v[120:123], v[148:151], v[156:159], v[120:123]
	v_mfma_f32_16x16x32_bf16 v[116:119], v[140:143], v[194:197], v[116:119]
	v_mfma_f32_16x16x32_bf16 v[112:115], v[148:151], v[194:197], v[112:115]
	v_mfma_f32_16x16x32_bf16 v[108:111], v[140:143], v[202:205], v[108:111]
	v_mfma_f32_16x16x32_bf16 v[104:107], v[148:151], v[202:205], v[104:107]
	v_mfma_f32_16x16x32_bf16 v[100:103], v[140:143], v[210:213], v[100:103]
	v_mfma_f32_16x16x32_bf16 v[96:99], v[148:151], v[210:213], v[96:99]
	v_mfma_f32_16x16x32_bf16 v[124:127], v[144:147], v[160:163], v[124:127]
	v_mfma_f32_16x16x32_bf16 v[120:123], v[152:155], v[160:163], v[120:123]
	v_mfma_f32_16x16x32_bf16 v[116:119], v[144:147], v[198:201], v[116:119]
	v_mfma_f32_16x16x32_bf16 v[112:115], v[152:155], v[198:201], v[112:115]
	v_mfma_f32_16x16x32_bf16 v[108:111], v[144:147], v[206:209], v[108:111]
	v_mfma_f32_16x16x32_bf16 v[104:107], v[152:155], v[206:209], v[104:107]
	v_mfma_f32_16x16x32_bf16 v[100:103], v[144:147], v[214:217], v[100:103]
	v_mfma_f32_16x16x32_bf16 v[96:99], v[152:155], v[214:217], v[96:99]
	s_setprio 0
	s_barrier
	ds_read_b128 v[136:139], v135
	ds_read_b128 v[218:221], v135 offset:1024
	ds_read_b128 v[222:225], v135 offset:2048
	ds_read_b128 v[226:229], v135 offset:3072
	s_barrier
	s_waitcnt lgkmcnt(0)
	s_setprio 1
	s_waitcnt lgkmcnt(0)
	v_mfma_f32_16x16x32_bf16 v[92:95], v[136:139], v[156:159], v[92:95]
	v_mfma_f32_16x16x32_bf16 v[88:91], v[222:225], v[156:159], v[88:91]
	v_mfma_f32_16x16x32_bf16 v[84:87], v[136:139], v[194:197], v[84:87]
	v_mfma_f32_16x16x32_bf16 v[80:83], v[222:225], v[194:197], v[80:83]
	v_mfma_f32_16x16x32_bf16 v[76:79], v[136:139], v[202:205], v[76:79]
	v_mfma_f32_16x16x32_bf16 v[72:75], v[222:225], v[202:205], v[72:75]
	v_mfma_f32_16x16x32_bf16 v[68:71], v[136:139], v[210:213], v[68:71]
	v_mfma_f32_16x16x32_bf16 v[64:67], v[222:225], v[210:213], v[64:67]
	v_mfma_f32_16x16x32_bf16 v[156:159], v[218:221], v[160:163], v[92:95]
	v_mfma_f32_16x16x32_bf16 v[160:163], v[226:229], v[160:163], v[88:91]
	v_mfma_f32_16x16x32_bf16 v[194:197], v[218:221], v[198:201], v[84:87]
	v_mfma_f32_16x16x32_bf16 v[198:201], v[226:229], v[198:201], v[80:83]
	v_mfma_f32_16x16x32_bf16 v[202:205], v[218:221], v[206:209], v[76:79]
	v_mfma_f32_16x16x32_bf16 v[206:209], v[226:229], v[206:209], v[72:75]
	v_mfma_f32_16x16x32_bf16 v[210:213], v[218:221], v[214:217], v[68:71]
	v_mfma_f32_16x16x32_bf16 v[214:217], v[226:229], v[214:217], v[64:67]
	s_setprio 0
	s_barrier
	s_nop 0
	ds_read_b128 v[64:67], v192 offset:16384
	ds_read_b128 v[68:71], v192 offset:17408
	ds_read_b128 v[72:75], v191 offset:16384
	ds_read_b128 v[76:79], v191 offset:17408
	ds_read_b128 v[80:83], v190 offset:16384
	ds_read_b128 v[84:87], v190 offset:17408
	ds_read_b128 v[88:91], v189 offset:16384
	ds_read_b128 v[92:95], v189 offset:17408
	s_waitcnt vmcnt(4)
	s_barrier
	s_waitcnt lgkmcnt(0)
	s_setprio 1
	s_waitcnt lgkmcnt(0)
	v_mfma_f32_16x16x32_bf16 v[60:63], v[140:143], v[64:67], v[60:63]
	v_mfma_f32_16x16x32_bf16 v[56:59], v[148:151], v[64:67], v[56:59]
	v_mfma_f32_16x16x32_bf16 v[52:55], v[140:143], v[72:75], v[52:55]
	v_mfma_f32_16x16x32_bf16 v[48:51], v[148:151], v[72:75], v[48:51]
	v_mfma_f32_16x16x32_bf16 v[230:233], v[140:143], v[80:83], v[44:47]
	v_mfma_f32_16x16x32_bf16 v[234:237], v[148:151], v[80:83], v[40:43]
	v_mfma_f32_16x16x32_bf16 v[140:143], v[140:143], v[88:91], v[36:39]
	v_mfma_f32_16x16x32_bf16 v[148:151], v[148:151], v[88:91], v[32:35]
	v_mfma_f32_16x16x32_bf16 v[32:35], v[144:147], v[68:71], v[60:63]
	v_mfma_f32_16x16x32_bf16 v[36:39], v[152:155], v[68:71], v[56:59]
	v_mfma_f32_16x16x32_bf16 v[40:43], v[144:147], v[76:79], v[52:55]
	v_mfma_f32_16x16x32_bf16 v[44:47], v[152:155], v[76:79], v[48:51]
	v_mfma_f32_16x16x32_bf16 v[48:51], v[144:147], v[84:87], v[230:233]
	v_mfma_f32_16x16x32_bf16 v[52:55], v[152:155], v[84:87], v[234:237]
	v_mfma_f32_16x16x32_bf16 v[56:59], v[144:147], v[92:95], v[140:143]
	v_mfma_f32_16x16x32_bf16 v[60:63], v[152:155], v[92:95], v[148:151]
	s_setprio 0
	s_setprio 1
	v_mfma_f32_16x16x32_bf16 v[28:31], v[136:139], v[64:67], v[28:31]
	v_mfma_f32_16x16x32_bf16 v[24:27], v[222:225], v[64:67], v[24:27]
	v_mfma_f32_16x16x32_bf16 v[20:23], v[136:139], v[72:75], v[20:23]
	v_mfma_f32_16x16x32_bf16 v[64:67], v[222:225], v[72:75], v[16:19]
	v_mfma_f32_16x16x32_bf16 v[12:15], v[136:139], v[80:83], v[12:15]
	v_mfma_f32_16x16x32_bf16 v[8:11], v[222:225], v[80:83], v[8:11]
	v_mfma_f32_16x16x32_bf16 v[72:75], v[136:139], v[88:91], v[4:7]
	v_mfma_f32_16x16x32_bf16 v[80:83], v[222:225], v[88:91], v[0:3]
	v_mfma_f32_16x16x32_bf16 v[0:3], v[218:221], v[68:71], v[28:31]
	v_mfma_f32_16x16x32_bf16 v[4:7], v[226:229], v[68:71], v[24:27]
	v_mfma_f32_16x16x32_bf16 v[16:19], v[218:221], v[76:79], v[20:23]
	v_mfma_f32_16x16x32_bf16 v[20:23], v[226:229], v[76:79], v[64:67]
	v_mfma_f32_16x16x32_bf16 v[64:67], v[218:221], v[84:87], v[12:15]
	v_mfma_f32_16x16x32_bf16 v[68:71], v[226:229], v[84:87], v[8:11]
	v_mfma_f32_16x16x32_bf16 v[72:75], v[218:221], v[92:95], v[72:75]
	v_mfma_f32_16x16x32_bf16 v[76:79], v[226:229], v[92:95], v[80:83]
	s_setprio 0
	s_barrier
	ds_read_b128 v[12:15], v130
	ds_read_b128 v[8:11], v130 offset:1024
	ds_read_b128 v[24:27], v130 offset:2048
	ds_read_b128 v[80:83], v130 offset:3072
	ds_read_b128 v[140:143], v192 offset:32768
	ds_read_b128 v[148:151], v192 offset:33792
	ds_read_b128 v[218:221], v191 offset:32768
	ds_read_b128 v[222:225], v191 offset:33792
	ds_read_b128 v[226:229], v190 offset:32768
	ds_read_b128 v[230:233], v190 offset:33792
	ds_read_b128 v[234:237], v189 offset:32768
	ds_read_b128 v[238:241], v189 offset:33792
	s_waitcnt vmcnt(2)
	s_barrier
	s_waitcnt lgkmcnt(0)
	s_setprio 1
	s_waitcnt lgkmcnt(0)
	v_mfma_f32_16x16x32_bf16 v[28:31], v[12:15], v[140:143], v[124:127]
	v_mfma_f32_16x16x32_bf16 v[84:87], v[24:27], v[140:143], v[120:123]
	v_mfma_f32_16x16x32_bf16 v[88:91], v[12:15], v[218:221], v[116:119]
	v_mfma_f32_16x16x32_bf16 v[92:95], v[24:27], v[218:221], v[112:115]
	v_mfma_f32_16x16x32_bf16 v[108:111], v[12:15], v[226:229], v[108:111]
	v_mfma_f32_16x16x32_bf16 v[104:107], v[24:27], v[226:229], v[104:107]
	v_mfma_f32_16x16x32_bf16 v[100:103], v[12:15], v[234:237], v[100:103]
	v_mfma_f32_16x16x32_bf16 v[96:99], v[24:27], v[234:237], v[96:99]
	v_mfma_f32_16x16x32_bf16 v[152:155], v[8:11], v[148:151], v[28:31]
	v_mfma_f32_16x16x32_bf16 v[144:147], v[80:83], v[148:151], v[84:87]
	v_mfma_f32_16x16x32_bf16 v[136:139], v[8:11], v[222:225], v[88:91]
	v_mfma_f32_16x16x32_bf16 v[128:131], v[80:83], v[222:225], v[92:95]
	v_mfma_f32_16x16x32_bf16 v[120:123], v[8:11], v[230:233], v[108:111]
	v_mfma_f32_16x16x32_bf16 v[112:115], v[80:83], v[230:233], v[104:107]
	v_mfma_f32_16x16x32_bf16 v[104:107], v[8:11], v[238:241], v[100:103]
	v_mfma_f32_16x16x32_bf16 v[28:31], v[80:83], v[238:241], v[96:99]
	s_setprio 0
	s_barrier
	ds_read_b128 v[92:95], v132
	ds_read_b128 v[84:87], v132 offset:1024
	ds_read_b128 v[96:99], v132 offset:2048
	ds_read_b128 v[88:91], v132 offset:3072
	s_waitcnt vmcnt(0)
	s_barrier
	s_waitcnt lgkmcnt(0)
	s_setprio 1
	s_waitcnt lgkmcnt(0)
	v_mfma_f32_16x16x32_bf16 v[100:103], v[92:95], v[140:143], v[156:159]
	v_mfma_f32_16x16x32_bf16 v[108:111], v[96:99], v[140:143], v[160:163]
	v_mfma_f32_16x16x32_bf16 v[116:119], v[92:95], v[218:221], v[194:197]
	v_mfma_f32_16x16x32_bf16 v[124:127], v[96:99], v[218:221], v[198:201]
	v_mfma_f32_16x16x32_bf16 v[160:163], v[92:95], v[226:229], v[202:205]
	v_mfma_f32_16x16x32_bf16 v[194:197], v[96:99], v[226:229], v[206:209]
	v_mfma_f32_16x16x32_bf16 v[198:201], v[92:95], v[234:237], v[210:213]
	v_mfma_f32_16x16x32_bf16 v[202:205], v[96:99], v[234:237], v[214:217]
	v_mfma_f32_16x16x32_bf16 v[156:159], v[84:87], v[148:151], v[100:103]
	v_mfma_f32_16x16x32_bf16 v[148:151], v[88:91], v[148:151], v[108:111]
	v_mfma_f32_16x16x32_bf16 v[140:143], v[84:87], v[222:225], v[116:119]
	v_mfma_f32_16x16x32_bf16 v[132:135], v[88:91], v[222:225], v[124:127]
	v_mfma_f32_16x16x32_bf16 v[124:127], v[84:87], v[230:233], v[160:163]
	v_mfma_f32_16x16x32_bf16 v[116:119], v[88:91], v[230:233], v[194:197]
	v_mfma_f32_16x16x32_bf16 v[108:111], v[84:87], v[238:241], v[198:201]
	v_mfma_f32_16x16x32_bf16 v[100:103], v[88:91], v[238:241], v[202:205]
	s_setprio 0
	s_lshl_b64 s[66:67], s[64:65], 2
	s_barrier
	v_mbcnt_lo_u32_b32 v162, -1, 0
	v_mbcnt_hi_u32_b32 v162, -1, v162
	s_add_u32 s66, s87, s66
	v_add_u32_e32 v160, s76, v162
	s_addc_u32 s67, s88, s67
	v_and_b32_e32 v164, 0x100, v160
	v_and_b32_e32 v162, 15, v162
	v_lshl_add_u64 v[160:161], s[66:67], 0, v[164:165]
	v_lshlrev_b32_e32 v164, 2, v162
	v_lshl_add_u64 v[160:161], v[160:161], 0, v[164:165]
	global_load_dword v178, v[160:161], off
	global_load_dword v176, v[160:161], off offset:64
	global_load_dword v174, v[160:161], off offset:128
	global_load_dword v164, v[160:161], off offset:192
	global_load_dword v172, v[160:161], off offset:512
	global_load_dword v170, v[160:161], off offset:576
	global_load_dword v168, v[160:161], off offset:640
	global_load_dword v166, v[160:161], off offset:704
	v_mbcnt_lo_u32_b32 v194, -1, 0
	v_mbcnt_hi_u32_b32 v194, -1, v194
	s_mov_b64 s[66:67], -1
	v_add_u32_e32 v160, s76, v194
	v_bfe_u32 v161, v160, 8, 1
	v_ashrrev_i32_e32 v196, 6, v160
	v_bfe_u32 v160, v194, 4, 2
	v_and_b32_e32 v198, 3, v196
	v_and_b32_e32 v195, 15, v194
	s_cmp_gt_i32 s74, 1
	v_lshlrev_b32_e32 v193, 6, v161
	v_lshlrev_b32_e32 v197, 4, v160
	s_cbranch_scc0 .LBB0_113
	v_lshlrev_b32_e32 v161, 6, v198
	v_or3_b32 v160, v193, v195, s64
	v_or3_b32 v161, v161, v197, s62
	v_lshl_add_u32 v199, v160, 12, v161
	s_waitcnt vmcnt(0)
	v_mul_f32_e32 v160, v178, v178
	v_pk_mul_f32 v[200:201], v[152:153], v[160:161] op_sel_hi:[1,0]
	v_pk_mul_f32 v[162:163], v[154:155], v[160:161] op_sel_hi:[1,0]
	v_pk_mul_f32 v[202:203], v[158:159], v[160:161] op_sel_hi:[1,0]
	v_pk_mul_f32 v[204:205], v[156:157], v[160:161] op_sel_hi:[1,0]
	v_mul_f32_e32 v160, v144, v200
	v_mul_f32_e32 v161, v145, v201
	v_cvt_pk_bf16_f32 v160, v160, v161
	v_mul_f32_e32 v161, v146, v162
	v_mul_f32_e32 v162, v147, v163
	v_cvt_pk_bf16_f32 v161, v161, v162
	v_mul_f32_e32 v162, v148, v204
	v_mul_f32_e32 v163, v149, v205
	v_cvt_pk_bf16_f32 v162, v162, v163
	v_mul_f32_e32 v163, v150, v202
	v_mul_f32_e32 v200, v151, v203
	v_cvt_pk_bf16_f32 v163, v163, v200
	global_store_dwordx4 v199, v[160:163], s[6:7]
	v_add_u32_e32 v206, 0x10000, v199
	s_mov_b64 s[66:67], 0
	v_mul_f32_e32 v160, v176, v176
	v_pk_mul_f32 v[200:201], v[136:137], v[160:161] op_sel_hi:[1,0]
	v_pk_mul_f32 v[162:163], v[138:139], v[160:161] op_sel_hi:[1,0]
	v_pk_mul_f32 v[202:203], v[142:143], v[160:161] op_sel_hi:[1,0]
	v_pk_mul_f32 v[204:205], v[140:141], v[160:161] op_sel_hi:[1,0]
	v_mul_f32_e32 v160, v128, v200
	v_mul_f32_e32 v161, v129, v201
	v_cvt_pk_bf16_f32 v160, v160, v161
	v_mul_f32_e32 v161, v130, v162
	v_mul_f32_e32 v162, v131, v163
	v_cvt_pk_bf16_f32 v161, v161, v162
	v_mul_f32_e32 v162, v132, v204
	v_mul_f32_e32 v163, v133, v205
	v_cvt_pk_bf16_f32 v162, v162, v163
	v_mul_f32_e32 v163, v134, v202
	v_mul_f32_e32 v200, v135, v203
	v_cvt_pk_bf16_f32 v163, v163, v200
	global_store_dwordx4 v206, v[160:163], s[6:7]
	v_add_u32_e32 v206, 0x20000, v199
	v_add_u32_e32 v199, 0x30000, v199
	v_mul_f32_e32 v160, v174, v174
	v_pk_mul_f32 v[200:201], v[120:121], v[160:161] op_sel_hi:[1,0]
	v_pk_mul_f32 v[162:163], v[122:123], v[160:161] op_sel_hi:[1,0]
	v_pk_mul_f32 v[202:203], v[126:127], v[160:161] op_sel_hi:[1,0]
	v_pk_mul_f32 v[204:205], v[124:125], v[160:161] op_sel_hi:[1,0]
	v_mul_f32_e32 v160, v112, v200
	v_mul_f32_e32 v161, v113, v201
	v_cvt_pk_bf16_f32 v160, v160, v161
	v_mul_f32_e32 v161, v114, v162
	v_mul_f32_e32 v162, v115, v163
	v_cvt_pk_bf16_f32 v161, v161, v162
	v_mul_f32_e32 v162, v116, v204
	v_mul_f32_e32 v163, v117, v205
	v_cvt_pk_bf16_f32 v162, v162, v163
	v_mul_f32_e32 v163, v118, v202
	v_mul_f32_e32 v200, v119, v203
	v_cvt_pk_bf16_f32 v163, v163, v200
	global_store_dwordx4 v206, v[160:163], s[6:7]
	s_nop 1
	v_mul_f32_e32 v160, v164, v164
	v_pk_mul_f32 v[200:201], v[104:105], v[160:161] op_sel_hi:[1,0]
	v_pk_mul_f32 v[162:163], v[106:107], v[160:161] op_sel_hi:[1,0]
	v_pk_mul_f32 v[202:203], v[110:111], v[160:161] op_sel_hi:[1,0]
	v_pk_mul_f32 v[204:205], v[108:109], v[160:161] op_sel_hi:[1,0]
	v_mul_f32_e32 v160, v28, v200
	v_mul_f32_e32 v161, v29, v201
	v_cvt_pk_bf16_f32 v160, v160, v161
	v_mul_f32_e32 v161, v30, v162
	v_mul_f32_e32 v162, v31, v163
	v_cvt_pk_bf16_f32 v161, v161, v162
	v_mul_f32_e32 v162, v100, v204
	v_mul_f32_e32 v163, v101, v205
	v_cvt_pk_bf16_f32 v162, v162, v163
	v_mul_f32_e32 v163, v102, v202
	v_mul_f32_e32 v200, v103, v203
	v_cvt_pk_bf16_f32 v163, v163, v200

.LBB0_178:
	ds_read_b128 v[180:183], v153
	ds_read_b128 v[184:187], v153 offset:1024
	ds_read_b128 v[188:191], v152
	ds_read_b128 v[192:195], v152 offset:1024
	ds_read_b128 v[196:199], v151
	ds_read_b128 v[200:203], v151 offset:1024
	ds_read_b128 v[204:207], v150
	ds_read_b128 v[208:211], v150 offset:1024
	s_waitcnt lgkmcnt(8)
	s_waitcnt vmcnt(10)
	s_barrier
	s_waitcnt lgkmcnt(0)
	s_waitcnt lgkmcnt(0)
	v_mfma_f32_16x16x32_bf16 v[124:127], v[164:167], v[180:183], v[124:127]
	v_mfma_f32_16x16x32_bf16 v[120:123], v[172:175], v[180:183], v[120:123]
	v_mfma_f32_16x16x32_bf16 v[116:119], v[164:167], v[188:191], v[116:119]
	v_mfma_f32_16x16x32_bf16 v[112:115], v[172:175], v[188:191], v[112:115]
	v_mfma_f32_16x16x32_bf16 v[108:111], v[164:167], v[196:199], v[108:111]
	v_mfma_f32_16x16x32_bf16 v[104:107], v[172:175], v[196:199], v[104:107]
	v_mfma_f32_16x16x32_bf16 v[100:103], v[164:167], v[204:207], v[100:103]
	v_mfma_f32_16x16x32_bf16 v[96:99], v[172:175], v[204:207], v[96:99]
	v_mfma_f32_16x16x32_bf16 v[124:127], v[168:171], v[184:187], v[124:127]
	v_mfma_f32_16x16x32_bf16 v[120:123], v[176:179], v[184:187], v[120:123]
	v_mfma_f32_16x16x32_bf16 v[116:119], v[168:171], v[192:195], v[116:119]
	v_mfma_f32_16x16x32_bf16 v[112:115], v[176:179], v[192:195], v[112:115]
	v_mfma_f32_16x16x32_bf16 v[108:111], v[168:171], v[200:203], v[108:111]
	v_mfma_f32_16x16x32_bf16 v[104:107], v[176:179], v[200:203], v[104:107]
	v_mfma_f32_16x16x32_bf16 v[100:103], v[168:171], v[208:211], v[100:103]
	v_mfma_f32_16x16x32_bf16 v[96:99], v[176:179], v[208:211], v[96:99]
	s_barrier
	v_lshl_add_u64 v[230:231], s[50:51], 0, v[130:131]
	s_mov_b64 s[66:67], 0x1880000
	s_add_i32 s65, s98, 0x10000
	v_lshl_add_u64 v[232:233], v[230:231], 0, s[66:67]
	s_mov_b32 m0, s65
	s_mov_b64 s[66:67], 0x1881000
	s_add_i32 s65, s98, 0x12000
	ds_read_b128 v[212:215], v159
	ds_read_b128 v[216:219], v159 offset:1024
	ds_read_b128 v[220:223], v159 offset:2048
	ds_read_b128 v[224:227], v159 offset:3072
	global_load_lds_dwordx4 v[232:233], off
	v_lshl_add_u64 v[232:233], v[230:231], 0, s[66:67]
	s_mov_b32 m0, s65
	s_nop 0
	global_load_lds_dwordx4 v[232:233], off
	s_mov_b64 s[66:67], 0xe000100
	s_mov_b32 s65, s98
	v_lshl_add_u64 v[232:233], v[228:229], 0, s[66:67]
	s_mov_b32 m0, s65
	s_mov_b64 s[66:67], 0xe040100
	s_add_i32 s65, s98, 0x2000
	global_load_lds_dwordx4 v[232:233], off
	v_lshl_add_u64 v[232:233], v[228:229], 0, s[66:67]
	s_mov_b32 m0, s65
	s_nop 0
	global_load_lds_dwordx4 v[232:233], off
	s_waitcnt vmcnt(12)
	s_barrier
	s_waitcnt lgkmcnt(0)
	s_waitcnt lgkmcnt(0)
	v_mfma_f32_16x16x32_bf16 v[92:95], v[212:215], v[180:183], v[92:95]
	v_mfma_f32_16x16x32_bf16 v[88:91], v[220:223], v[180:183], v[88:91]
	v_mfma_f32_16x16x32_bf16 v[84:87], v[212:215], v[188:191], v[84:87]
	v_mfma_f32_16x16x32_bf16 v[80:83], v[220:223], v[188:191], v[80:83]
	v_mfma_f32_16x16x32_bf16 v[76:79], v[212:215], v[196:199], v[76:79]
	v_mfma_f32_16x16x32_bf16 v[72:75], v[220:223], v[196:199], v[72:75]
	v_mfma_f32_16x16x32_bf16 v[68:71], v[212:215], v[204:207], v[68:71]
	v_mfma_f32_16x16x32_bf16 v[64:67], v[220:223], v[204:207], v[64:67]
	v_mfma_f32_16x16x32_bf16 v[92:95], v[216:219], v[184:187], v[92:95]
	v_mfma_f32_16x16x32_bf16 v[88:91], v[224:227], v[184:187], v[88:91]
	v_mfma_f32_16x16x32_bf16 v[84:87], v[216:219], v[192:195], v[84:87]
	v_mfma_f32_16x16x32_bf16 v[80:83], v[224:227], v[192:195], v[80:83]
	v_mfma_f32_16x16x32_bf16 v[76:79], v[216:219], v[200:203], v[76:79]
	v_mfma_f32_16x16x32_bf16 v[72:75], v[224:227], v[200:203], v[72:75]
	v_mfma_f32_16x16x32_bf16 v[68:71], v[216:219], v[208:211], v[68:71]
	v_mfma_f32_16x16x32_bf16 v[64:67], v[224:227], v[208:211], v[64:67]
	s_barrier
	ds_read_b128 v[180:183], v153 offset:16384
	ds_read_b128 v[184:187], v153 offset:17408
	ds_read_b128 v[188:191], v152 offset:16384
	ds_read_b128 v[192:195], v152 offset:17408
	ds_read_b128 v[196:199], v151 offset:16384
	ds_read_b128 v[200:203], v151 offset:17408
	ds_read_b128 v[204:207], v150 offset:16384
	ds_read_b128 v[208:211], v150 offset:17408
	s_mov_b64 s[66:67], 0x1882000
	s_add_i32 s65, s98, 0x14000
	v_lshl_add_u64 v[232:233], v[230:231], 0, s[66:67]
	s_mov_b32 m0, s65
	s_mov_b64 s[66:67], 0x1883000
	s_add_i32 s65, s98, 0x16000
	global_load_lds_dwordx4 v[232:233], off
	v_lshl_add_u64 v[232:233], v[230:231], 0, s[66:67]
	s_mov_b32 m0, s65
	s_nop 0
	global_load_lds_dwordx4 v[232:233], off
	s_waitcnt vmcnt(12)
	s_barrier
	s_waitcnt lgkmcnt(0)
	s_waitcnt lgkmcnt(0)
	v_mfma_f32_16x16x32_bf16 v[60:63], v[164:167], v[180:183], v[60:63]
	v_mfma_f32_16x16x32_bf16 v[56:59], v[172:175], v[180:183], v[56:59]
	v_mfma_f32_16x16x32_bf16 v[52:55], v[164:167], v[188:191], v[52:55]
	v_mfma_f32_16x16x32_bf16 v[48:51], v[172:175], v[188:191], v[48:51]
	v_mfma_f32_16x16x32_bf16 v[44:47], v[164:167], v[196:199], v[44:47]
	v_mfma_f32_16x16x32_bf16 v[40:43], v[172:175], v[196:199], v[40:43]
	v_mfma_f32_16x16x32_bf16 v[36:39], v[164:167], v[204:207], v[36:39]
	v_mfma_f32_16x16x32_bf16 v[32:35], v[172:175], v[204:207], v[32:35]
	v_mfma_f32_16x16x32_bf16 v[60:63], v[168:171], v[184:187], v[60:63]
	v_mfma_f32_16x16x32_bf16 v[56:59], v[176:179], v[184:187], v[56:59]
	v_mfma_f32_16x16x32_bf16 v[52:55], v[168:171], v[192:195], v[52:55]
	v_mfma_f32_16x16x32_bf16 v[48:51], v[176:179], v[192:195], v[48:51]
	v_mfma_f32_16x16x32_bf16 v[44:47], v[168:171], v[200:203], v[44:47]
	v_mfma_f32_16x16x32_bf16 v[40:43], v[176:179], v[200:203], v[40:43]
	v_mfma_f32_16x16x32_bf16 v[36:39], v[168:171], v[208:211], v[36:39]
	v_mfma_f32_16x16x32_bf16 v[32:35], v[176:179], v[208:211], v[32:35]
	s_barrier
	s_add_i32 s65, s98, 0x4000
	v_lshl_add_u64 v[166:167], v[228:229], 0, s[26:27]
	s_mov_b32 m0, s65
	s_add_i32 s65, s98, 0x6000
	global_load_lds_dwordx4 v[166:167], off
	v_lshl_add_u64 v[166:167], v[228:229], 0, s[28:29]
	s_mov_b32 m0, s65
	s_nop 0
	global_load_lds_dwordx4 v[166:167], off
	ds_read_b128 v[164:167], v155
	ds_read_b128 v[168:171], v155 offset:1024
	ds_read_b128 v[172:175], v155 offset:2048
	ds_read_b128 v[176:179], v155 offset:3072
	s_waitcnt vmcnt(12)
	s_barrier
	v_mfma_f32_16x16x32_bf16 v[28:31], v[212:215], v[180:183], v[28:31]
	v_mfma_f32_16x16x32_bf16 v[24:27], v[220:223], v[180:183], v[24:27]
	v_mfma_f32_16x16x32_bf16 v[20:23], v[212:215], v[188:191], v[20:23]
	v_mfma_f32_16x16x32_bf16 v[16:19], v[220:223], v[188:191], v[16:19]
	v_mfma_f32_16x16x32_bf16 v[12:15], v[212:215], v[196:199], v[12:15]
	v_mfma_f32_16x16x32_bf16 v[8:11], v[220:223], v[196:199], v[8:11]
	v_mfma_f32_16x16x32_bf16 v[4:7], v[212:215], v[204:207], v[4:7]
	v_mfma_f32_16x16x32_bf16 v[0:3], v[220:223], v[204:207], v[0:3]
	v_mfma_f32_16x16x32_bf16 v[28:31], v[216:219], v[184:187], v[28:31]
	v_mfma_f32_16x16x32_bf16 v[24:27], v[224:227], v[184:187], v[24:27]
	v_mfma_f32_16x16x32_bf16 v[20:23], v[216:219], v[192:195], v[20:23]
	v_mfma_f32_16x16x32_bf16 v[16:19], v[224:227], v[192:195], v[16:19]
	v_mfma_f32_16x16x32_bf16 v[12:15], v[216:219], v[200:203], v[12:15]
	v_mfma_f32_16x16x32_bf16 v[8:11], v[224:227], v[200:203], v[8:11]
	v_mfma_f32_16x16x32_bf16 v[4:7], v[216:219], v[208:211], v[4:7]
	v_mfma_f32_16x16x32_bf16 v[0:3], v[224:227], v[208:211], v[0:3]
	s_barrier
	ds_read_b128 v[180:183], v153 offset:32768
	ds_read_b128 v[184:187], v153 offset:33792
	ds_read_b128 v[188:191], v152 offset:32768
	ds_read_b128 v[192:195], v152 offset:33792
	ds_read_b128 v[196:199], v151 offset:32768
	ds_read_b128 v[200:203], v151 offset:33792
	ds_read_b128 v[204:207], v150 offset:32768
	ds_read_b128 v[208:211], v150 offset:33792
	s_waitcnt lgkmcnt(8)
	s_waitcnt vmcnt(10)
	s_barrier
	s_waitcnt lgkmcnt(0)
	s_waitcnt lgkmcnt(0)
	v_mfma_f32_16x16x32_bf16 v[124:127], v[164:167], v[180:183], v[124:127]
	v_mfma_f32_16x16x32_bf16 v[120:123], v[172:175], v[180:183], v[120:123]
	v_mfma_f32_16x16x32_bf16 v[116:119], v[164:167], v[188:191], v[116:119]
	v_mfma_f32_16x16x32_bf16 v[112:115], v[172:175], v[188:191], v[112:115]
	v_mfma_f32_16x16x32_bf16 v[108:111], v[164:167], v[196:199], v[108:111]
	v_mfma_f32_16x16x32_bf16 v[104:107], v[172:175], v[196:199], v[104:107]
	v_mfma_f32_16x16x32_bf16 v[100:103], v[164:167], v[204:207], v[100:103]
	v_mfma_f32_16x16x32_bf16 v[96:99], v[172:175], v[204:207], v[96:99]
	v_mfma_f32_16x16x32_bf16 v[124:127], v[168:171], v[184:187], v[124:127]
	v_mfma_f32_16x16x32_bf16 v[120:123], v[176:179], v[184:187], v[120:123]
	v_mfma_f32_16x16x32_bf16 v[116:119], v[168:171], v[192:195], v[116:119]
	v_mfma_f32_16x16x32_bf16 v[112:115], v[176:179], v[192:195], v[112:115]
	v_mfma_f32_16x16x32_bf16 v[108:111], v[168:171], v[200:203], v[108:111]
	v_mfma_f32_16x16x32_bf16 v[104:107], v[176:179], v[200:203], v[104:107]
	v_mfma_f32_16x16x32_bf16 v[100:103], v[168:171], v[208:211], v[100:103]
	v_mfma_f32_16x16x32_bf16 v[96:99], v[176:179], v[208:211], v[96:99]
	s_barrier
	s_add_i32 s65, s98, 0x18000
	v_lshl_add_u64 v[232:233], v[230:231], 0, s[30:31]
	s_mov_b32 m0, s65
	s_add_i32 s65, s98, 0x1a000
	ds_read_b128 v[212:215], v154
	ds_read_b128 v[216:219], v154 offset:1024
	ds_read_b128 v[220:223], v154 offset:2048
	ds_read_b128 v[224:227], v154 offset:3072
	global_load_lds_dwordx4 v[232:233], off
	v_lshl_add_u64 v[232:233], v[230:231], 0, s[34:35]
	s_mov_b32 m0, s65
	s_nop 0
	global_load_lds_dwordx4 v[232:233], off
	s_add_i32 s65, s98, 0x8000
	v_lshl_add_u64 v[232:233], v[228:229], 0, s[40:41]
	s_mov_b32 m0, s65
	s_add_i32 s65, s98, 0xa000
	global_load_lds_dwordx4 v[232:233], off
	v_lshl_add_u64 v[228:229], v[228:229], 0, s[44:45]
	s_mov_b32 m0, s65
	s_nop 0
	global_load_lds_dwordx4 v[228:229], off
	s_waitcnt vmcnt(12)
	s_barrier
	s_waitcnt lgkmcnt(0)
	s_waitcnt lgkmcnt(0)
	v_mfma_f32_16x16x32_bf16 v[92:95], v[212:215], v[180:183], v[92:95]
	v_mfma_f32_16x16x32_bf16 v[88:91], v[220:223], v[180:183], v[88:91]
	v_mfma_f32_16x16x32_bf16 v[84:87], v[212:215], v[188:191], v[84:87]
	v_mfma_f32_16x16x32_bf16 v[80:83], v[220:223], v[188:191], v[80:83]
	v_mfma_f32_16x16x32_bf16 v[76:79], v[212:215], v[196:199], v[76:79]
	v_mfma_f32_16x16x32_bf16 v[72:75], v[220:223], v[196:199], v[72:75]
	v_mfma_f32_16x16x32_bf16 v[68:71], v[212:215], v[204:207], v[68:71]
	v_mfma_f32_16x16x32_bf16 v[64:67], v[220:223], v[204:207], v[64:67]
	v_mfma_f32_16x16x32_bf16 v[92:95], v[216:219], v[184:187], v[92:95]
	v_mfma_f32_16x16x32_bf16 v[88:91], v[224:227], v[184:187], v[88:91]
	v_mfma_f32_16x16x32_bf16 v[84:87], v[216:219], v[192:195], v[84:87]
	v_mfma_f32_16x16x32_bf16 v[80:83], v[224:227], v[192:195], v[80:83]
	v_mfma_f32_16x16x32_bf16 v[76:79], v[216:219], v[200:203], v[76:79]
	v_mfma_f32_16x16x32_bf16 v[72:75], v[224:227], v[200:203], v[72:75]
	v_mfma_f32_16x16x32_bf16 v[68:71], v[216:219], v[208:211], v[68:71]
	v_mfma_f32_16x16x32_bf16 v[64:67], v[224:227], v[208:211], v[64:67]
	s_barrier
	ds_read_b128 v[180:183], v153 offset:49152
	ds_read_b128 v[184:187], v153 offset:50176
	ds_read_b128 v[188:191], v152 offset:49152
	ds_read_b128 v[192:195], v152 offset:50176
	ds_read_b128 v[196:199], v151 offset:49152
	ds_read_b128 v[200:203], v151 offset:50176
	ds_read_b128 v[204:207], v150 offset:49152
	ds_read_b128 v[208:211], v150 offset:50176
	s_add_i32 s65, s98, 0x1c000
	v_lshl_add_u64 v[232:233], v[230:231], 0, s[46:47]
	s_mov_b32 m0, s65
	s_add_i32 s65, s98, 0x1e000
	global_load_lds_dwordx4 v[232:233], off
	v_lshl_add_u64 v[232:233], v[230:231], 0, s[56:57]
	s_mov_b32 m0, s65
	s_nop 0
	global_load_lds_dwordx4 v[232:233], off
	s_waitcnt vmcnt(12)
	s_barrier
	s_waitcnt lgkmcnt(0)
	s_waitcnt lgkmcnt(0)
	v_mfma_f32_16x16x32_bf16 v[60:63], v[164:167], v[180:183], v[60:63]
	v_mfma_f32_16x16x32_bf16 v[56:59], v[172:175], v[180:183], v[56:59]
	v_mfma_f32_16x16x32_bf16 v[52:55], v[164:167], v[188:191], v[52:55]
	v_mfma_f32_16x16x32_bf16 v[48:51], v[172:175], v[188:191], v[48:51]
	v_mfma_f32_16x16x32_bf16 v[44:47], v[164:167], v[196:199], v[44:47]
	v_mfma_f32_16x16x32_bf16 v[40:43], v[172:175], v[196:199], v[40:43]
	v_mfma_f32_16x16x32_bf16 v[36:39], v[164:167], v[204:207], v[36:39]
	v_mfma_f32_16x16x32_bf16 v[32:35], v[172:175], v[204:207], v[32:35]
	v_mfma_f32_16x16x32_bf16 v[60:63], v[168:171], v[184:187], v[60:63]
	v_mfma_f32_16x16x32_bf16 v[56:59], v[176:179], v[184:187], v[56:59]
	v_mfma_f32_16x16x32_bf16 v[52:55], v[168:171], v[192:195], v[52:55]
	v_mfma_f32_16x16x32_bf16 v[48:51], v[176:179], v[192:195], v[48:51]
	v_mfma_f32_16x16x32_bf16 v[44:47], v[168:171], v[200:203], v[44:47]
	v_mfma_f32_16x16x32_bf16 v[40:43], v[176:179], v[200:203], v[40:43]
	v_mfma_f32_16x16x32_bf16 v[36:39], v[168:171], v[208:211], v[36:39]
	v_mfma_f32_16x16x32_bf16 v[32:35], v[176:179], v[208:211], v[32:35]
	s_barrier
	v_lshl_add_u64 v[132:133], v[132:133], 0, s[58:59]
	v_lshl_add_u64 v[228:229], s[50:51], 0, v[132:133]
	s_mov_b64 s[66:67], 0xe080080
	s_add_i32 s65, s98, 0xc000
	v_lshl_add_u64 v[166:167], v[228:229], 0, s[66:67]
	s_mov_b32 m0, s65
	s_mov_b64 s[66:67], 0xe0c0080
	s_add_i32 s65, s98, 0xe000
	global_load_lds_dwordx4 v[166:167], off
	v_lshl_add_u64 v[166:167], v[228:229], 0, s[66:67]
	s_mov_b32 m0, s65
	s_nop 0
	global_load_lds_dwordx4 v[166:167], off
	ds_read_b128 v[164:167], v162
	ds_read_b128 v[168:171], v162 offset:1024
	ds_read_b128 v[172:175], v162 offset:2048
	ds_read_b128 v[176:179], v162 offset:3072
	s_waitcnt vmcnt(12)
	s_barrier
	v_mfma_f32_16x16x32_bf16 v[28:31], v[212:215], v[180:183], v[28:31]
	v_mfma_f32_16x16x32_bf16 v[24:27], v[220:223], v[180:183], v[24:27]
	v_mfma_f32_16x16x32_bf16 v[20:23], v[212:215], v[188:191], v[20:23]
	v_mfma_f32_16x16x32_bf16 v[16:19], v[220:223], v[188:191], v[16:19]
	v_mfma_f32_16x16x32_bf16 v[12:15], v[212:215], v[196:199], v[12:15]
	v_mfma_f32_16x16x32_bf16 v[8:11], v[220:223], v[196:199], v[8:11]
	v_mfma_f32_16x16x32_bf16 v[4:7], v[212:215], v[204:207], v[4:7]
	v_mfma_f32_16x16x32_bf16 v[0:3], v[220:223], v[204:207], v[0:3]
	v_mfma_f32_16x16x32_bf16 v[28:31], v[216:219], v[184:187], v[28:31]
	v_mfma_f32_16x16x32_bf16 v[24:27], v[224:227], v[184:187], v[24:27]
	v_mfma_f32_16x16x32_bf16 v[20:23], v[216:219], v[192:195], v[20:23]
	v_mfma_f32_16x16x32_bf16 v[16:19], v[224:227], v[192:195], v[16:19]
	v_mfma_f32_16x16x32_bf16 v[12:15], v[216:219], v[200:203], v[12:15]
	v_mfma_f32_16x16x32_bf16 v[8:11], v[224:227], v[200:203], v[8:11]
	v_mfma_f32_16x16x32_bf16 v[4:7], v[216:219], v[208:211], v[4:7]
	v_mfma_f32_16x16x32_bf16 v[0:3], v[224:227], v[208:211], v[0:3]
	s_add_i32 s24, s24, 2
	v_lshl_add_u64 v[130:131], v[130:131], 0, s[10:11]
	s_cmp_lt_u32 s24, 28
	s_barrier
	s_cbranch_scc1 .LBB0_178
	s_lshl_b32 s24, s85, 5
	s_lshl_b32 s65, s85, 8
	s_and_b32 s24, s24, 0x1800
	s_and_b32 s65, s65, 0x700
	s_or_b32 s24, s65, s24
	v_lshlrev_b32_e32 v128, 3, v156
	v_lshlrev_b32_e32 v130, 5, v156
	v_and_b32_e32 v128, 0xffff0, v128
	v_and_b32_e32 v130, 32, v130
	s_lshl_b32 s65, s24, 12
	v_add_u32_e32 v130, v130, v158
	v_add_lshl_u32 v128, v157, v128, 12
	s_add_u32 s66, s68, s65
	v_lshl_add_u32 v128, v130, 1, v128
	s_addc_u32 s67, s69, 0
	v_lshl_add_u64 v[156:157], s[66:67], 0, v[128:129]
	v_readfirstlane_b32 s65, v161
	ds_read_b128 v[130:133], v162
	ds_read_b128 v[164:167], v162 offset:1024
	ds_read_b128 v[168:171], v162 offset:2048
	ds_read_b128 v[172:175], v162 offset:3072
	ds_read_b128 v[176:179], v153
	ds_read_b128 v[180:183], v153 offset:1024
	ds_read_b128 v[184:187], v152
	ds_read_b128 v[188:191], v152 offset:1024
	ds_read_b128 v[192:195], v151
	ds_read_b128 v[196:199], v151 offset:1024
	ds_read_b128 v[200:203], v150
	ds_read_b128 v[204:207], v150 offset:1024
	v_lshl_add_u64 v[162:163], v[156:157], 0, s[60:61]
	s_mov_b32 m0, s65
	v_readfirstlane_b32 s65, v160
	v_lshl_add_u64 v[156:157], v[156:157], 0, s[62:63]
	s_mov_b32 m0, s65
	s_nop 0
	s_waitcnt vmcnt(8)
	s_barrier
	s_waitcnt lgkmcnt(0)
	s_setprio 1
	s_waitcnt lgkmcnt(0)
	v_mfma_f32_16x16x32_bf16 v[124:127], v[130:133], v[176:179], v[124:127]
	v_mfma_f32_16x16x32_bf16 v[120:123], v[168:171], v[176:179], v[120:123]
	v_mfma_f32_16x16x32_bf16 v[116:119], v[130:133], v[184:187], v[116:119]
	v_mfma_f32_16x16x32_bf16 v[112:115], v[168:171], v[184:187], v[112:115]
	v_mfma_f32_16x16x32_bf16 v[108:111], v[130:133], v[192:195], v[108:111]
	v_mfma_f32_16x16x32_bf16 v[104:107], v[168:171], v[192:195], v[104:107]
	v_mfma_f32_16x16x32_bf16 v[100:103], v[130:133], v[200:203], v[100:103]
	v_mfma_f32_16x16x32_bf16 v[96:99], v[168:171], v[200:203], v[96:99]
	v_mfma_f32_16x16x32_bf16 v[124:127], v[164:167], v[180:183], v[124:127]
	v_mfma_f32_16x16x32_bf16 v[120:123], v[172:175], v[180:183], v[120:123]
	v_mfma_f32_16x16x32_bf16 v[116:119], v[164:167], v[188:191], v[116:119]
	v_mfma_f32_16x16x32_bf16 v[112:115], v[172:175], v[188:191], v[112:115]
	v_mfma_f32_16x16x32_bf16 v[108:111], v[164:167], v[196:199], v[108:111]
	v_mfma_f32_16x16x32_bf16 v[104:107], v[172:175], v[196:199], v[104:107]
	v_mfma_f32_16x16x32_bf16 v[100:103], v[164:167], v[204:207], v[100:103]
	v_mfma_f32_16x16x32_bf16 v[96:99], v[172:175], v[204:207], v[96:99]
	s_setprio 0
	s_barrier
	ds_read_b128 v[160:163], v159
	ds_read_b128 v[208:211], v159 offset:1024
	ds_read_b128 v[212:215], v159 offset:2048
	ds_read_b128 v[156:159], v159 offset:3072
	s_barrier
	s_waitcnt lgkmcnt(0)
	s_setprio 1
	s_waitcnt lgkmcnt(0)
	v_mfma_f32_16x16x32_bf16 v[92:95], v[160:163], v[176:179], v[92:95]
	v_mfma_f32_16x16x32_bf16 v[88:91], v[212:215], v[176:179], v[88:91]
	v_mfma_f32_16x16x32_bf16 v[84:87], v[160:163], v[184:187], v[84:87]
	v_mfma_f32_16x16x32_bf16 v[80:83], v[212:215], v[184:187], v[80:83]
	v_mfma_f32_16x16x32_bf16 v[76:79], v[160:163], v[192:195], v[76:79]
	v_mfma_f32_16x16x32_bf16 v[72:75], v[212:215], v[192:195], v[72:75]
	v_mfma_f32_16x16x32_bf16 v[68:71], v[160:163], v[200:203], v[68:71]
	v_mfma_f32_16x16x32_bf16 v[64:67], v[212:215], v[200:203], v[64:67]
	v_mfma_f32_16x16x32_bf16 v[176:179], v[208:211], v[180:183], v[92:95]
	v_mfma_f32_16x16x32_bf16 v[180:183], v[156:159], v[180:183], v[88:91]
	v_mfma_f32_16x16x32_bf16 v[184:187], v[208:211], v[188:191], v[84:87]
	v_mfma_f32_16x16x32_bf16 v[188:191], v[156:159], v[188:191], v[80:83]
	v_mfma_f32_16x16x32_bf16 v[192:195], v[208:211], v[196:199], v[76:79]
	v_mfma_f32_16x16x32_bf16 v[196:199], v[156:159], v[196:199], v[72:75]
	v_mfma_f32_16x16x32_bf16 v[200:203], v[208:211], v[204:207], v[68:71]
	v_mfma_f32_16x16x32_bf16 v[204:207], v[156:159], v[204:207], v[64:67]
	s_setprio 0
	s_barrier
	s_nop 0
	ds_read_b128 v[64:67], v153 offset:16384
	ds_read_b128 v[68:71], v153 offset:17408
	ds_read_b128 v[72:75], v152 offset:16384
	ds_read_b128 v[76:79], v152 offset:17408
	ds_read_b128 v[80:83], v151 offset:16384
	ds_read_b128 v[84:87], v151 offset:17408
	ds_read_b128 v[88:91], v150 offset:16384
	ds_read_b128 v[92:95], v150 offset:17408
	s_waitcnt vmcnt(4)
	s_barrier
	s_waitcnt lgkmcnt(0)
	s_setprio 1
	s_waitcnt lgkmcnt(0)
	v_mfma_f32_16x16x32_bf16 v[60:63], v[130:133], v[64:67], v[60:63]
	v_mfma_f32_16x16x32_bf16 v[56:59], v[168:171], v[64:67], v[56:59]
	v_mfma_f32_16x16x32_bf16 v[52:55], v[130:133], v[72:75], v[52:55]
	v_mfma_f32_16x16x32_bf16 v[48:51], v[168:171], v[72:75], v[48:51]
	v_mfma_f32_16x16x32_bf16 v[216:219], v[130:133], v[80:83], v[44:47]
	v_mfma_f32_16x16x32_bf16 v[220:223], v[168:171], v[80:83], v[40:43]
	v_mfma_f32_16x16x32_bf16 v[130:133], v[130:133], v[88:91], v[36:39]
	v_mfma_f32_16x16x32_bf16 v[168:171], v[168:171], v[88:91], v[32:35]
	v_mfma_f32_16x16x32_bf16 v[32:35], v[164:167], v[68:71], v[60:63]
	v_mfma_f32_16x16x32_bf16 v[36:39], v[172:175], v[68:71], v[56:59]
	v_mfma_f32_16x16x32_bf16 v[40:43], v[164:167], v[76:79], v[52:55]
	v_mfma_f32_16x16x32_bf16 v[44:47], v[172:175], v[76:79], v[48:51]
	v_mfma_f32_16x16x32_bf16 v[48:51], v[164:167], v[84:87], v[216:219]
	v_mfma_f32_16x16x32_bf16 v[52:55], v[172:175], v[84:87], v[220:223]
	v_mfma_f32_16x16x32_bf16 v[56:59], v[164:167], v[92:95], v[130:133]
	v_mfma_f32_16x16x32_bf16 v[60:63], v[172:175], v[92:95], v[168:171]
	s_setprio 0
	s_setprio 1
	v_mfma_f32_16x16x32_bf16 v[28:31], v[160:163], v[64:67], v[28:31]
	v_mfma_f32_16x16x32_bf16 v[24:27], v[212:215], v[64:67], v[24:27]
	v_mfma_f32_16x16x32_bf16 v[20:23], v[160:163], v[72:75], v[20:23]
	v_mfma_f32_16x16x32_bf16 v[64:67], v[212:215], v[72:75], v[16:19]
	v_mfma_f32_16x16x32_bf16 v[72:75], v[160:163], v[80:83], v[12:15]
	v_mfma_f32_16x16x32_bf16 v[8:11], v[212:215], v[80:83], v[8:11]
	v_mfma_f32_16x16x32_bf16 v[80:83], v[160:163], v[88:91], v[4:7]
	v_mfma_f32_16x16x32_bf16 v[0:3], v[212:215], v[88:91], v[0:3]
	v_mfma_f32_16x16x32_bf16 v[4:7], v[208:211], v[68:71], v[28:31]
	v_mfma_f32_16x16x32_bf16 v[12:15], v[156:159], v[68:71], v[24:27]
	v_mfma_f32_16x16x32_bf16 v[16:19], v[208:211], v[76:79], v[20:23]
	v_mfma_f32_16x16x32_bf16 v[20:23], v[156:159], v[76:79], v[64:67]
	v_mfma_f32_16x16x32_bf16 v[24:27], v[208:211], v[84:87], v[72:75]
	v_mfma_f32_16x16x32_bf16 v[28:31], v[156:159], v[84:87], v[8:11]
	v_mfma_f32_16x16x32_bf16 v[64:67], v[208:211], v[92:95], v[80:83]
	v_mfma_f32_16x16x32_bf16 v[68:71], v[156:159], v[92:95], v[0:3]
	s_setprio 0
	s_barrier
	ds_read_b128 v[8:11], v155
	ds_read_b128 v[0:3], v155 offset:1024
	ds_read_b128 v[76:79], v155 offset:2048
	ds_read_b128 v[72:75], v155 offset:3072
	ds_read_b128 v[130:133], v153 offset:32768
	ds_read_b128 v[156:159], v153 offset:33792
	ds_read_b128 v[160:163], v152 offset:32768
	ds_read_b128 v[164:167], v152 offset:33792
	ds_read_b128 v[168:171], v151 offset:32768
	ds_read_b128 v[172:175], v151 offset:33792
	ds_read_b128 v[208:211], v150 offset:32768
	ds_read_b128 v[212:215], v150 offset:33792
	s_waitcnt vmcnt(2)
	s_barrier
	s_waitcnt lgkmcnt(0)
	s_setprio 1
	s_waitcnt lgkmcnt(0)
	v_mfma_f32_16x16x32_bf16 v[80:83], v[8:11], v[130:133], v[124:127]
	v_mfma_f32_16x16x32_bf16 v[84:87], v[76:79], v[130:133], v[120:123]
	v_mfma_f32_16x16x32_bf16 v[88:91], v[8:11], v[160:163], v[116:119]
	v_mfma_f32_16x16x32_bf16 v[92:95], v[76:79], v[160:163], v[112:115]
	v_mfma_f32_16x16x32_bf16 v[108:111], v[8:11], v[168:171], v[108:111]
	v_mfma_f32_16x16x32_bf16 v[104:107], v[76:79], v[168:171], v[104:107]
	v_mfma_f32_16x16x32_bf16 v[100:103], v[8:11], v[208:211], v[100:103]
	v_mfma_f32_16x16x32_bf16 v[96:99], v[76:79], v[208:211], v[96:99]
	v_mfma_f32_16x16x32_bf16 v[112:115], v[0:3], v[156:159], v[80:83]
	v_mfma_f32_16x16x32_bf16 v[116:119], v[72:75], v[156:159], v[84:87]
	v_mfma_f32_16x16x32_bf16 v[120:123], v[0:3], v[164:167], v[88:91]
	v_mfma_f32_16x16x32_bf16 v[124:127], v[72:75], v[164:167], v[92:95]
	v_mfma_f32_16x16x32_bf16 v[108:111], v[0:3], v[172:175], v[108:111]
	v_mfma_f32_16x16x32_bf16 v[104:107], v[72:75], v[172:175], v[104:107]
	v_mfma_f32_16x16x32_bf16 v[100:103], v[0:3], v[212:215], v[100:103]
	v_mfma_f32_16x16x32_bf16 v[96:99], v[72:75], v[212:215], v[96:99]
	s_setprio 0
	s_barrier
	ds_read_b128 v[88:91], v154
	ds_read_b128 v[80:83], v154 offset:1024
	ds_read_b128 v[92:95], v154 offset:2048
	ds_read_b128 v[84:87], v154 offset:3072
	s_waitcnt vmcnt(0)
	s_barrier
	s_waitcnt lgkmcnt(0)
	s_setprio 1
	s_waitcnt lgkmcnt(0)
	v_mfma_f32_16x16x32_bf16 v[176:179], v[88:91], v[130:133], v[176:179]
	v_mfma_f32_16x16x32_bf16 v[130:133], v[92:95], v[130:133], v[180:183]
	v_mfma_f32_16x16x32_bf16 v[180:183], v[88:91], v[160:163], v[184:187]
	v_mfma_f32_16x16x32_bf16 v[160:163], v[92:95], v[160:163], v[188:191]
	v_mfma_f32_16x16x32_bf16 v[184:187], v[88:91], v[168:171], v[192:195]
	v_mfma_f32_16x16x32_bf16 v[168:171], v[92:95], v[168:171], v[196:199]
	v_mfma_f32_16x16x32_bf16 v[188:191], v[88:91], v[208:211], v[200:203]
	v_mfma_f32_16x16x32_bf16 v[192:195], v[92:95], v[208:211], v[204:207]
	v_mfma_f32_16x16x32_bf16 v[176:179], v[80:83], v[156:159], v[176:179]
	v_mfma_f32_16x16x32_bf16 v[130:133], v[84:87], v[156:159], v[130:133]
	v_mfma_f32_16x16x32_bf16 v[154:157], v[80:83], v[164:167], v[180:183]
	v_mfma_f32_16x16x32_bf16 v[158:161], v[84:87], v[164:167], v[160:163]
	v_mfma_f32_16x16x32_bf16 v[162:165], v[80:83], v[172:175], v[184:187]
	v_mfma_f32_16x16x32_bf16 v[166:169], v[84:87], v[172:175], v[168:171]
	v_mfma_f32_16x16x32_bf16 v[170:173], v[80:83], v[212:215], v[188:191]
	v_mfma_f32_16x16x32_bf16 v[180:183], v[84:87], v[212:215], v[192:195]
	s_setprio 0
	s_barrier
	v_mbcnt_lo_u32_b32 v128, -1, 0
	v_mbcnt_hi_u32_b32 v128, -1, v128
	v_cvt_pk_bf16_f32 v112, v112, v113
	v_cvt_pk_bf16_f32 v113, v114, v115
	v_cvt_pk_bf16_f32 v114, v116, v117
	v_cvt_pk_bf16_f32 v115, v118, v119
	s_lshl_b32 s66, s64, 9
	v_add_u32_e32 v174, s72, v128
	v_ashrrev_i32_e32 v175, 6, v174
	v_and_b32_e32 v184, 15, v128
	v_and_b32_e32 v185, 48, v128
	v_mul_lo_u32 v186, v175, s77
	v_bfe_u32 v187, v128, 3, 3
	v_lshlrev_b32_e32 v128, 4, v128
	v_add_u32_e32 v186, 0x20000, v186
	v_lshrrev_b32_e32 v174, 2, v174
	v_and_b32_e32 v128, 0x70, v128
	v_mul_u32_u24_e32 v184, 0x90, v184
	v_and_b32_e32 v174, 64, v174
	v_add3_u32 v184, v186, v184, v185
	v_or_b32_e32 v185, v186, v128
	v_or3_b32 v174, s24, v174, v187
	v_mad_u32_u24 v185, v187, s78, v185
	ds_write_b128 v184, v[112:115]
	v_cvt_pk_bf16_f32 v112, v176, v177
	v_cvt_pk_bf16_f32 v113, v178, v179
	v_cvt_pk_bf16_f32 v114, v130, v131
	v_cvt_pk_bf16_f32 v115, v132, v133
	ds_write_b128 v184, v[112:115] offset:64
	v_lshlrev_b32_e32 v175, 7, v175
	ds_read_b128 v[112:115], v185
	v_lshlrev_b32_e32 v116, 12, v174
	v_and_or_b32 v116, v175, s79, v116
	v_or3_b32 v128, v116, s66, v128
	ds_read_b128 v[116:119], v185 offset:1152
	v_lshl_add_u64 v[130:131], s[0:1], 0, v[128:129]
	s_mov_b32 s64, 0x8000
	s_waitcnt lgkmcnt(0)
	global_store_dwordx4 v128, v[112:115], s[0:1]
	v_cvt_pk_bf16_f32 v108, v108, v109
	v_cvt_pk_bf16_f32 v109, v110, v111
	v_cvt_pk_bf16_f32 v110, v104, v105
	v_cvt_pk_bf16_f32 v111, v106, v107
	v_cvt_pk_bf16_f32 v104, v162, v163
	s_nop 1
	v_add_co_u32_e32 v112, vcc, s64, v130
	v_cvt_pk_bf16_f32 v114, v124, v125
	v_cvt_pk_bf16_f32 v115, v126, v127
	v_cvt_pk_bf16_f32 v105, v164, v165
	v_cvt_pk_bf16_f32 v106, v166, v167
	s_nop 1
	v_addc_co_u32_e32 v113, vcc, 0, v131, vcc
	global_store_dwordx4 v[112:113], v[116:119], off
	v_cvt_pk_bf16_f32 v112, v120, v121
	v_cvt_pk_bf16_f32 v113, v122, v123
	ds_write_b128 v184, v[112:115]
	v_cvt_pk_bf16_f32 v112, v154, v155
	v_cvt_pk_bf16_f32 v113, v156, v157
	v_cvt_pk_bf16_f32 v114, v158, v159
	v_cvt_pk_bf16_f32 v115, v160, v161
	ds_write_b128 v184, v[112:115] offset:64
	ds_read_b128 v[112:115], v185
	ds_read_b128 v[116:119], v185 offset:1152
	v_add_co_u32_e32 v120, vcc, s74, v130
	ds_write_b128 v184, v[108:111]
	v_cvt_pk_bf16_f32 v107, v168, v169
	ds_write_b128 v184, v[104:107] offset:64
	v_addc_co_u32_e32 v121, vcc, 0, v131, vcc
	ds_read_b128 v[104:107], v185
	ds_read_b128 v[108:111], v185 offset:1152
	s_waitcnt lgkmcnt(0)
	global_store_dwordx4 v[120:121], v[112:115], off
	v_cvt_pk_bf16_f32 v100, v100, v101
	v_cvt_pk_bf16_f32 v101, v102, v103
	v_cvt_pk_bf16_f32 v102, v96, v97
	v_cvt_pk_bf16_f32 v103, v98, v99
	ds_write_b128 v184, v[100:103]
	s_nop 0
	v_add_co_u32_e32 v112, vcc, s75, v130
	v_cvt_pk_bf16_f32 v96, v170, v171
	v_cvt_pk_bf16_f32 v97, v172, v173
	v_cvt_pk_bf16_f32 v98, v180, v181
	v_cvt_pk_bf16_f32 v99, v182, v183
	s_nop 1
	v_addc_co_u32_e32 v113, vcc, 0, v131, vcc
	global_store_dwordx4 v[112:113], v[116:119], off
	v_add_co_u32_e32 v112, vcc, s76, v130
	ds_write_b128 v184, v[96:99] offset:64
	s_nop 0
	v_addc_co_u32_e32 v113, vcc, 0, v131, vcc
	ds_read_b128 v[96:99], v185
	ds_read_b128 v[100:103], v185 offset:1152
	global_store_dwordx4 v[112:113], v[104:107], off
	s_nop 1
	v_add_co_u32_e32 v104, vcc, s80, v130
	s_nop 1
	v_addc_co_u32_e32 v105, vcc, 0, v131, vcc
	global_store_dwordx4 v[104:105], v[108:111], off
	v_add_co_u32_e32 v104, vcc, s81, v130
	s_nop 1
	v_addc_co_u32_e32 v105, vcc, 0, v131, vcc
	s_waitcnt lgkmcnt(0)
	global_store_dwordx4 v[104:105], v[96:99], off
	s_nop 1
	v_add_co_u32_e32 v96, vcc, s82, v130
	s_nop 1
	v_addc_co_u32_e32 v97, vcc, 0, v131, vcc
	global_store_dwordx4 v[96:97], v[100:103], off
	ds_read_b128 v[96:99], v153 offset:49152
	ds_read_b128 v[100:103], v153 offset:50176
	ds_read_b128 v[104:107], v152 offset:49152
	ds_read_b128 v[108:111], v152 offset:50176
	ds_read_b128 v[112:115], v151 offset:49152
	ds_read_b128 v[116:119], v151 offset:50176
	ds_read_b128 v[120:123], v150 offset:49152
	ds_read_b128 v[124:127], v150 offset:50176
	s_barrier
	s_waitcnt lgkmcnt(0)
	s_setprio 1
	s_waitcnt lgkmcnt(0)
	v_mfma_f32_16x16x32_bf16 v[32:35], v[8:11], v[96:99], v[32:35]
	v_mfma_f32_16x16x32_bf16 v[36:39], v[76:79], v[96:99], v[36:39]
	v_mfma_f32_16x16x32_bf16 v[40:43], v[8:11], v[104:107], v[40:43]
	v_mfma_f32_16x16x32_bf16 v[130:133], v[76:79], v[104:107], v[44:47]
	v_mfma_f32_16x16x32_bf16 v[150:153], v[8:11], v[112:115], v[48:51]
	v_mfma_f32_16x16x32_bf16 v[52:55], v[76:79], v[112:115], v[52:55]
	v_mfma_f32_16x16x32_bf16 v[8:11], v[8:11], v[120:123], v[56:59]
	v_mfma_f32_16x16x32_bf16 v[60:63], v[76:79], v[120:123], v[60:63]
	v_mfma_f32_16x16x32_bf16 v[56:59], v[0:3], v[100:103], v[32:35]
	v_mfma_f32_16x16x32_bf16 v[48:51], v[72:75], v[100:103], v[36:39]
	v_mfma_f32_16x16x32_bf16 v[44:47], v[0:3], v[108:111], v[40:43]
	v_mfma_f32_16x16x32_bf16 v[40:43], v[72:75], v[108:111], v[130:133]
	v_mfma_f32_16x16x32_bf16 v[36:39], v[0:3], v[116:119], v[150:153]
	v_mfma_f32_16x16x32_bf16 v[32:35], v[72:75], v[116:119], v[52:55]
	v_mfma_f32_16x16x32_bf16 v[8:11], v[0:3], v[124:127], v[8:11]
	v_mfma_f32_16x16x32_bf16 v[0:3], v[72:75], v[124:127], v[60:63]
	s_setprio 0
	s_setprio 1
	v_mfma_f32_16x16x32_bf16 v[4:7], v[88:91], v[96:99], v[4:7]
	v_mfma_f32_16x16x32_bf16 v[12:15], v[92:95], v[96:99], v[12:15]
	v_mfma_f32_16x16x32_bf16 v[16:19], v[88:91], v[104:107], v[16:19]
	v_mfma_f32_16x16x32_bf16 v[20:23], v[92:95], v[104:107], v[20:23]
	v_mfma_f32_16x16x32_bf16 v[72:75], v[88:91], v[112:115], v[24:27]
	v_mfma_f32_16x16x32_bf16 v[76:79], v[92:95], v[112:115], v[28:31]
	v_mfma_f32_16x16x32_bf16 v[64:67], v[88:91], v[120:123], v[64:67]
	v_mfma_f32_16x16x32_bf16 v[68:71], v[92:95], v[120:123], v[68:71]
	v_mfma_f32_16x16x32_bf16 v[60:63], v[80:83], v[100:103], v[4:7]
	v_mfma_f32_16x16x32_bf16 v[52:55], v[84:87], v[100:103], v[12:15]
	v_mfma_f32_16x16x32_bf16 v[28:31], v[80:83], v[108:111], v[16:19]
	v_mfma_f32_16x16x32_bf16 v[24:27], v[84:87], v[108:111], v[20:23]
	v_mfma_f32_16x16x32_bf16 v[20:23], v[80:83], v[116:119], v[72:75]
	v_mfma_f32_16x16x32_bf16 v[16:19], v[84:87], v[116:119], v[76:79]
	v_mfma_f32_16x16x32_bf16 v[12:15], v[80:83], v[124:127], v[64:67]
	v_mfma_f32_16x16x32_bf16 v[4:7], v[84:87], v[124:127], v[68:71]
	s_setprio 0
	v_cmp_gt_u32_e32 vcc, s83, v136
	s_barrier
	s_and_saveexec_b64 s[64:65], vcc
	s_cbranch_execz .LBB0_181
	s_barrier

.LBB0_234:
	ds_read_b128 v[156:159], v193
	ds_read_b128 v[160:163], v193 offset:1024
	ds_read_b128 v[194:197], v192
	ds_read_b128 v[198:201], v192 offset:1024
	ds_read_b128 v[202:205], v191
	ds_read_b128 v[206:209], v191 offset:1024
	ds_read_b128 v[210:213], v190
	ds_read_b128 v[214:217], v190 offset:1024
	s_waitcnt lgkmcnt(8)
	s_waitcnt vmcnt(10)
	s_barrier
	s_waitcnt lgkmcnt(0)
	s_waitcnt lgkmcnt(0)
	v_mfma_f32_16x16x32_bf16 v[124:127], v[140:143], v[156:159], v[124:127]
	v_mfma_f32_16x16x32_bf16 v[120:123], v[148:151], v[156:159], v[120:123]
	v_mfma_f32_16x16x32_bf16 v[116:119], v[140:143], v[194:197], v[116:119]
	v_mfma_f32_16x16x32_bf16 v[112:115], v[148:151], v[194:197], v[112:115]
	v_mfma_f32_16x16x32_bf16 v[108:111], v[140:143], v[202:205], v[108:111]
	v_mfma_f32_16x16x32_bf16 v[104:107], v[148:151], v[202:205], v[104:107]
	v_mfma_f32_16x16x32_bf16 v[100:103], v[140:143], v[210:213], v[100:103]
	v_mfma_f32_16x16x32_bf16 v[96:99], v[148:151], v[210:213], v[96:99]
	v_mfma_f32_16x16x32_bf16 v[124:127], v[144:147], v[160:163], v[124:127]
	v_mfma_f32_16x16x32_bf16 v[120:123], v[152:155], v[160:163], v[120:123]
	v_mfma_f32_16x16x32_bf16 v[116:119], v[144:147], v[198:201], v[116:119]
	v_mfma_f32_16x16x32_bf16 v[112:115], v[152:155], v[198:201], v[112:115]
	v_mfma_f32_16x16x32_bf16 v[108:111], v[144:147], v[206:209], v[108:111]
	v_mfma_f32_16x16x32_bf16 v[104:107], v[152:155], v[206:209], v[104:107]
	v_mfma_f32_16x16x32_bf16 v[100:103], v[144:147], v[214:217], v[100:103]
	v_mfma_f32_16x16x32_bf16 v[96:99], v[152:155], v[214:217], v[96:99]
	s_barrier
	s_add_i32 s82, s98, 0x10000
	v_lshl_add_u64 v[234:235], s[60:61], 0, v[164:165]
	s_mov_b32 m0, s82
	s_add_i32 s82, s98, 0x12000
	ds_read_b128 v[218:221], v135
	ds_read_b128 v[222:225], v135 offset:1024
	ds_read_b128 v[226:229], v135 offset:2048
	ds_read_b128 v[230:233], v135 offset:3072
	global_load_lds_dwordx4 v[234:235], off
	v_lshl_add_u64 v[236:237], v[234:235], 0, s[2:3]
	s_mov_b32 m0, s82
	s_nop 0
	global_load_lds_dwordx4 v[236:237], off
	s_mov_b32 s82, s98
	v_lshl_add_u64 v[236:237], v[128:129], 0, s[22:23]
	s_mov_b32 m0, s82
	s_add_i32 s82, s98, 0x2000
	global_load_lds_dwordx4 v[236:237], off
	v_lshl_add_u64 v[236:237], v[128:129], 0, s[24:25]
	s_mov_b32 m0, s82
	s_nop 0
	global_load_lds_dwordx4 v[236:237], off
	s_waitcnt vmcnt(12)
	s_barrier
	s_waitcnt lgkmcnt(0)
	s_waitcnt lgkmcnt(0)
	v_mfma_f32_16x16x32_bf16 v[92:95], v[218:221], v[156:159], v[92:95]
	v_mfma_f32_16x16x32_bf16 v[88:91], v[226:229], v[156:159], v[88:91]
	v_mfma_f32_16x16x32_bf16 v[84:87], v[218:221], v[194:197], v[84:87]
	v_mfma_f32_16x16x32_bf16 v[80:83], v[226:229], v[194:197], v[80:83]
	v_mfma_f32_16x16x32_bf16 v[76:79], v[218:221], v[202:205], v[76:79]
	v_mfma_f32_16x16x32_bf16 v[72:75], v[226:229], v[202:205], v[72:75]
	v_mfma_f32_16x16x32_bf16 v[68:71], v[218:221], v[210:213], v[68:71]
	v_mfma_f32_16x16x32_bf16 v[64:67], v[226:229], v[210:213], v[64:67]
	v_mfma_f32_16x16x32_bf16 v[92:95], v[222:225], v[160:163], v[92:95]
	v_mfma_f32_16x16x32_bf16 v[88:91], v[230:233], v[160:163], v[88:91]
	v_mfma_f32_16x16x32_bf16 v[84:87], v[222:225], v[198:201], v[84:87]
	v_mfma_f32_16x16x32_bf16 v[80:83], v[230:233], v[198:201], v[80:83]
	v_mfma_f32_16x16x32_bf16 v[76:79], v[222:225], v[206:209], v[76:79]
	v_mfma_f32_16x16x32_bf16 v[72:75], v[230:233], v[206:209], v[72:75]
	v_mfma_f32_16x16x32_bf16 v[68:71], v[222:225], v[214:217], v[68:71]
	v_mfma_f32_16x16x32_bf16 v[64:67], v[230:233], v[214:217], v[64:67]
	s_barrier
	ds_read_b128 v[156:159], v193 offset:16384
	ds_read_b128 v[160:163], v193 offset:17408
	ds_read_b128 v[194:197], v192 offset:16384
	ds_read_b128 v[198:201], v192 offset:17408
	ds_read_b128 v[202:205], v191 offset:16384
	ds_read_b128 v[206:209], v191 offset:17408
	ds_read_b128 v[210:213], v190 offset:16384
	ds_read_b128 v[214:217], v190 offset:17408
	s_add_i32 s82, s98, 0x14000
	v_lshl_add_u64 v[236:237], v[234:235], 0, s[6:7]
	s_mov_b32 m0, s82
	s_add_i32 s82, s98, 0x16000
	global_load_lds_dwordx4 v[236:237], off
	v_lshl_add_u64 v[236:237], v[234:235], 0, s[8:9]
	s_mov_b32 m0, s82
	s_nop 0
	global_load_lds_dwordx4 v[236:237], off
	s_waitcnt vmcnt(12)
	s_barrier
	s_waitcnt lgkmcnt(0)
	s_waitcnt lgkmcnt(0)
	v_mfma_f32_16x16x32_bf16 v[60:63], v[140:143], v[156:159], v[60:63]
	v_mfma_f32_16x16x32_bf16 v[56:59], v[148:151], v[156:159], v[56:59]
	v_mfma_f32_16x16x32_bf16 v[52:55], v[140:143], v[194:197], v[52:55]
	v_mfma_f32_16x16x32_bf16 v[48:51], v[148:151], v[194:197], v[48:51]
	v_mfma_f32_16x16x32_bf16 v[44:47], v[140:143], v[202:205], v[44:47]
	v_mfma_f32_16x16x32_bf16 v[40:43], v[148:151], v[202:205], v[40:43]
	v_mfma_f32_16x16x32_bf16 v[36:39], v[140:143], v[210:213], v[36:39]
	v_mfma_f32_16x16x32_bf16 v[32:35], v[148:151], v[210:213], v[32:35]
	v_mfma_f32_16x16x32_bf16 v[60:63], v[144:147], v[160:163], v[60:63]
	v_mfma_f32_16x16x32_bf16 v[56:59], v[152:155], v[160:163], v[56:59]
	v_mfma_f32_16x16x32_bf16 v[52:55], v[144:147], v[198:201], v[52:55]
	v_mfma_f32_16x16x32_bf16 v[48:51], v[152:155], v[198:201], v[48:51]
	v_mfma_f32_16x16x32_bf16 v[44:47], v[144:147], v[206:209], v[44:47]
	v_mfma_f32_16x16x32_bf16 v[40:43], v[152:155], v[206:209], v[40:43]
	v_mfma_f32_16x16x32_bf16 v[36:39], v[144:147], v[214:217], v[36:39]
	v_mfma_f32_16x16x32_bf16 v[32:35], v[152:155], v[214:217], v[32:35]
	s_barrier
	s_add_i32 s82, s98, 0x4000
	v_lshl_add_u64 v[142:143], v[128:129], 0, s[26:27]
	s_mov_b32 m0, s82
	s_add_i32 s82, s98, 0x6000
	global_load_lds_dwordx4 v[142:143], off
	s_mov_b32 m0, s82
	s_nop 0
	global_load_lds_dwordx4 v[128:129], off
	ds_read_b128 v[140:143], v130
	ds_read_b128 v[144:147], v130 offset:1024
	ds_read_b128 v[148:151], v130 offset:2048
	ds_read_b128 v[152:155], v130 offset:3072
	s_waitcnt vmcnt(12)
	s_barrier
	v_mfma_f32_16x16x32_bf16 v[28:31], v[218:221], v[156:159], v[28:31]
	v_mfma_f32_16x16x32_bf16 v[24:27], v[226:229], v[156:159], v[24:27]
	v_mfma_f32_16x16x32_bf16 v[20:23], v[218:221], v[194:197], v[20:23]
	v_mfma_f32_16x16x32_bf16 v[16:19], v[226:229], v[194:197], v[16:19]
	v_mfma_f32_16x16x32_bf16 v[12:15], v[218:221], v[202:205], v[12:15]
	v_mfma_f32_16x16x32_bf16 v[8:11], v[226:229], v[202:205], v[8:11]
	v_mfma_f32_16x16x32_bf16 v[4:7], v[218:221], v[210:213], v[4:7]
	v_mfma_f32_16x16x32_bf16 v[0:3], v[226:229], v[210:213], v[0:3]
	v_mfma_f32_16x16x32_bf16 v[28:31], v[222:225], v[160:163], v[28:31]
	v_mfma_f32_16x16x32_bf16 v[24:27], v[230:233], v[160:163], v[24:27]
	v_mfma_f32_16x16x32_bf16 v[20:23], v[222:225], v[198:201], v[20:23]
	v_mfma_f32_16x16x32_bf16 v[16:19], v[230:233], v[198:201], v[16:19]
	v_mfma_f32_16x16x32_bf16 v[12:15], v[222:225], v[206:209], v[12:15]
	v_mfma_f32_16x16x32_bf16 v[8:11], v[230:233], v[206:209], v[8:11]
	v_mfma_f32_16x16x32_bf16 v[4:7], v[222:225], v[214:217], v[4:7]
	v_mfma_f32_16x16x32_bf16 v[0:3], v[230:233], v[214:217], v[0:3]
	s_barrier
	ds_read_b128 v[156:159], v193 offset:32768
	ds_read_b128 v[160:163], v193 offset:33792
	ds_read_b128 v[194:197], v192 offset:32768
	ds_read_b128 v[198:201], v192 offset:33792
	ds_read_b128 v[202:205], v191 offset:32768
	ds_read_b128 v[206:209], v191 offset:33792
	ds_read_b128 v[210:213], v190 offset:32768
	ds_read_b128 v[214:217], v190 offset:33792
	s_waitcnt lgkmcnt(8)
	s_waitcnt vmcnt(10)
	s_barrier
	s_waitcnt lgkmcnt(0)
	s_waitcnt lgkmcnt(0)
	v_mfma_f32_16x16x32_bf16 v[124:127], v[140:143], v[156:159], v[124:127]
	v_mfma_f32_16x16x32_bf16 v[120:123], v[148:151], v[156:159], v[120:123]
	v_mfma_f32_16x16x32_bf16 v[116:119], v[140:143], v[194:197], v[116:119]
	v_mfma_f32_16x16x32_bf16 v[112:115], v[148:151], v[194:197], v[112:115]
	v_mfma_f32_16x16x32_bf16 v[108:111], v[140:143], v[202:205], v[108:111]
	v_mfma_f32_16x16x32_bf16 v[104:107], v[148:151], v[202:205], v[104:107]
	v_mfma_f32_16x16x32_bf16 v[100:103], v[140:143], v[210:213], v[100:103]
	v_mfma_f32_16x16x32_bf16 v[96:99], v[148:151], v[210:213], v[96:99]
	v_mfma_f32_16x16x32_bf16 v[124:127], v[144:147], v[160:163], v[124:127]
	v_mfma_f32_16x16x32_bf16 v[120:123], v[152:155], v[160:163], v[120:123]
	v_mfma_f32_16x16x32_bf16 v[116:119], v[144:147], v[198:201], v[116:119]
	v_mfma_f32_16x16x32_bf16 v[112:115], v[152:155], v[198:201], v[112:115]
	v_mfma_f32_16x16x32_bf16 v[108:111], v[144:147], v[206:209], v[108:111]
	v_mfma_f32_16x16x32_bf16 v[104:107], v[152:155], v[206:209], v[104:107]
	v_mfma_f32_16x16x32_bf16 v[100:103], v[144:147], v[214:217], v[100:103]
	v_mfma_f32_16x16x32_bf16 v[96:99], v[152:155], v[214:217], v[96:99]
	s_barrier
	s_add_i32 s82, s98, 0x18000
	v_lshl_add_u64 v[234:235], s[56:57], 0, v[164:165]
	s_mov_b32 m0, s82
	s_add_i32 s82, s98, 0x1a000
	ds_read_b128 v[218:221], v132
	ds_read_b128 v[222:225], v132 offset:1024
	ds_read_b128 v[226:229], v132 offset:2048
	ds_read_b128 v[230:233], v132 offset:3072
	global_load_lds_dwordx4 v[234:235], off
	v_lshl_add_u64 v[236:237], v[234:235], 0, s[2:3]
	s_mov_b32 m0, s82
	s_nop 0
	global_load_lds_dwordx4 v[236:237], off
	s_add_i32 s82, s98, 0x8000
	v_lshl_add_u64 v[236:237], v[128:129], 0, s[28:29]
	s_mov_b32 m0, s82
	s_add_i32 s82, s98, 0xa000
	global_load_lds_dwordx4 v[236:237], off
	v_lshl_add_u64 v[236:237], v[128:129], 0, s[30:31]
	s_mov_b32 m0, s82
	s_nop 0
	global_load_lds_dwordx4 v[236:237], off
	s_waitcnt vmcnt(12)
	s_barrier
	s_waitcnt lgkmcnt(0)
	s_waitcnt lgkmcnt(0)
	v_mfma_f32_16x16x32_bf16 v[92:95], v[218:221], v[156:159], v[92:95]
	v_mfma_f32_16x16x32_bf16 v[88:91], v[226:229], v[156:159], v[88:91]
	v_mfma_f32_16x16x32_bf16 v[84:87], v[218:221], v[194:197], v[84:87]
	v_mfma_f32_16x16x32_bf16 v[80:83], v[226:229], v[194:197], v[80:83]
	v_mfma_f32_16x16x32_bf16 v[76:79], v[218:221], v[202:205], v[76:79]
	v_mfma_f32_16x16x32_bf16 v[72:75], v[226:229], v[202:205], v[72:75]
	v_mfma_f32_16x16x32_bf16 v[68:71], v[218:221], v[210:213], v[68:71]
	v_mfma_f32_16x16x32_bf16 v[64:67], v[226:229], v[210:213], v[64:67]
	v_mfma_f32_16x16x32_bf16 v[92:95], v[222:225], v[160:163], v[92:95]
	v_mfma_f32_16x16x32_bf16 v[88:91], v[230:233], v[160:163], v[88:91]
	v_mfma_f32_16x16x32_bf16 v[84:87], v[222:225], v[198:201], v[84:87]
	v_mfma_f32_16x16x32_bf16 v[80:83], v[230:233], v[198:201], v[80:83]
	v_mfma_f32_16x16x32_bf16 v[76:79], v[222:225], v[206:209], v[76:79]
	v_mfma_f32_16x16x32_bf16 v[72:75], v[230:233], v[206:209], v[72:75]
	v_mfma_f32_16x16x32_bf16 v[68:71], v[222:225], v[214:217], v[68:71]
	v_mfma_f32_16x16x32_bf16 v[64:67], v[230:233], v[214:217], v[64:67]
	s_barrier
	ds_read_b128 v[156:159], v193 offset:49152
	ds_read_b128 v[160:163], v193 offset:50176
	ds_read_b128 v[194:197], v192 offset:49152
	ds_read_b128 v[198:201], v192 offset:50176
	ds_read_b128 v[202:205], v191 offset:49152
	ds_read_b128 v[206:209], v191 offset:50176
	ds_read_b128 v[210:213], v190 offset:49152
	ds_read_b128 v[214:217], v190 offset:50176
	s_add_i32 s82, s98, 0x1c000
	v_lshl_add_u64 v[236:237], v[234:235], 0, s[6:7]
	s_mov_b32 m0, s82
	s_add_i32 s82, s98, 0x1e000
	global_load_lds_dwordx4 v[236:237], off
	v_lshl_add_u64 v[236:237], v[234:235], 0, s[8:9]
	s_mov_b32 m0, s82
	s_nop 0
	global_load_lds_dwordx4 v[236:237], off
	s_waitcnt vmcnt(12)
	s_barrier
	s_waitcnt lgkmcnt(0)
	s_waitcnt lgkmcnt(0)
	v_mfma_f32_16x16x32_bf16 v[60:63], v[140:143], v[156:159], v[60:63]
	v_mfma_f32_16x16x32_bf16 v[56:59], v[148:151], v[156:159], v[56:59]
	v_mfma_f32_16x16x32_bf16 v[52:55], v[140:143], v[194:197], v[52:55]
	v_mfma_f32_16x16x32_bf16 v[48:51], v[148:151], v[194:197], v[48:51]
	v_mfma_f32_16x16x32_bf16 v[44:47], v[140:143], v[202:205], v[44:47]
	v_mfma_f32_16x16x32_bf16 v[40:43], v[148:151], v[202:205], v[40:43]
	v_mfma_f32_16x16x32_bf16 v[36:39], v[140:143], v[210:213], v[36:39]
	v_mfma_f32_16x16x32_bf16 v[32:35], v[148:151], v[210:213], v[32:35]
	v_mfma_f32_16x16x32_bf16 v[60:63], v[144:147], v[160:163], v[60:63]
	v_mfma_f32_16x16x32_bf16 v[56:59], v[152:155], v[160:163], v[56:59]
	v_mfma_f32_16x16x32_bf16 v[52:55], v[144:147], v[198:201], v[52:55]
	v_mfma_f32_16x16x32_bf16 v[48:51], v[152:155], v[198:201], v[48:51]
	v_mfma_f32_16x16x32_bf16 v[44:47], v[144:147], v[206:209], v[44:47]
	v_mfma_f32_16x16x32_bf16 v[40:43], v[152:155], v[206:209], v[40:43]
	v_mfma_f32_16x16x32_bf16 v[36:39], v[144:147], v[214:217], v[36:39]
	v_mfma_f32_16x16x32_bf16 v[32:35], v[152:155], v[214:217], v[32:35]
	s_barrier
	v_lshl_add_u64 v[128:129], v[128:129], 0, s[34:35]
	s_add_i32 s82, s98, 0xc000
	v_lshl_add_u64 v[142:143], v[128:129], 0, s[18:19]
	s_mov_b32 m0, s82
	s_add_i32 s82, s98, 0xe000
	global_load_lds_dwordx4 v[142:143], off
	v_lshl_add_u64 v[142:143], v[128:129], 0, s[20:21]
	s_mov_b32 m0, s82
	s_nop 0
	global_load_lds_dwordx4 v[142:143], off
	ds_read_b128 v[140:143], v138
	ds_read_b128 v[144:147], v138 offset:1024
	ds_read_b128 v[148:151], v138 offset:2048
	ds_read_b128 v[152:155], v138 offset:3072
	s_waitcnt vmcnt(12)
	s_barrier
	v_mfma_f32_16x16x32_bf16 v[28:31], v[218:221], v[156:159], v[28:31]
	v_mfma_f32_16x16x32_bf16 v[24:27], v[226:229], v[156:159], v[24:27]
	v_mfma_f32_16x16x32_bf16 v[20:23], v[218:221], v[194:197], v[20:23]
	v_mfma_f32_16x16x32_bf16 v[16:19], v[226:229], v[194:197], v[16:19]
	v_mfma_f32_16x16x32_bf16 v[12:15], v[218:221], v[202:205], v[12:15]
	v_mfma_f32_16x16x32_bf16 v[8:11], v[226:229], v[202:205], v[8:11]
	v_mfma_f32_16x16x32_bf16 v[4:7], v[218:221], v[210:213], v[4:7]
	v_mfma_f32_16x16x32_bf16 v[0:3], v[226:229], v[210:213], v[0:3]
	v_mfma_f32_16x16x32_bf16 v[28:31], v[222:225], v[160:163], v[28:31]
	v_mfma_f32_16x16x32_bf16 v[24:27], v[230:233], v[160:163], v[24:27]
	v_mfma_f32_16x16x32_bf16 v[20:23], v[222:225], v[198:201], v[20:23]
	v_mfma_f32_16x16x32_bf16 v[16:19], v[230:233], v[198:201], v[16:19]
	v_mfma_f32_16x16x32_bf16 v[12:15], v[222:225], v[206:209], v[12:15]
	v_mfma_f32_16x16x32_bf16 v[8:11], v[230:233], v[206:209], v[8:11]
	v_mfma_f32_16x16x32_bf16 v[4:7], v[222:225], v[214:217], v[4:7]
	v_mfma_f32_16x16x32_bf16 v[0:3], v[230:233], v[214:217], v[0:3]
	s_add_i32 s14, s14, 2
	s_add_u32 s56, s56, s58
	s_addc_u32 s57, s57, s59
	s_add_u32 s60, s60, s58
	s_addc_u32 s61, s61, s59
	s_cmp_lt_u32 s14, 28
	s_barrier
	s_cbranch_scc1 .LBB0_234
	s_lshl_b32 s14, s62, 3
	s_or_b32 s82, s63, s14
	s_lshl_b32 s56, s82, 8
	v_lshlrev_b32_e32 v128, 3, v131
	v_lshlrev_b32_e32 v129, 5, v131
	s_or_b32 s14, s56, 0x80
	v_and_b32_e32 v128, 0x7fff0, v128
	v_and_b32_e32 v129, 32, v129
	s_lshl_b64 s[58:59], s[14:15], 13
	v_add_u32_e32 v129, v129, v134
	v_add_lshl_u32 v128, v133, v128, 13
	s_add_u32 s58, s40, s58
	v_lshl_add_u32 v164, v129, 1, v128
	s_addc_u32 s59, s41, s59
	v_lshl_add_u64 v[128:129], s[58:59], 0, v[164:165]
	v_readfirstlane_b32 s14, v137
	ds_read_b128 v[140:143], v138
	ds_read_b128 v[144:147], v138 offset:1024
	ds_read_b128 v[148:151], v138 offset:2048
	ds_read_b128 v[152:155], v138 offset:3072
	ds_read_b128 v[156:159], v193
	ds_read_b128 v[160:163], v193 offset:1024
	ds_read_b128 v[194:197], v192
	ds_read_b128 v[198:201], v192 offset:1024
	ds_read_b128 v[202:205], v191
	ds_read_b128 v[206:209], v191 offset:1024
	ds_read_b128 v[210:213], v190
	ds_read_b128 v[214:217], v190 offset:1024
	v_lshl_add_u64 v[138:139], v[128:129], 0, s[44:45]
	s_mov_b32 m0, s14
	v_readfirstlane_b32 s14, v136
	v_lshl_add_u64 v[128:129], v[128:129], 0, s[46:47]
	s_mov_b32 m0, s14
	s_mov_b32 s57, s15
	s_mul_i32 s99, s78, s84
	s_add_i32 s99, s99, s33
	s_cmpk_lt_u32 s99, 0x400
	s_cbranch_scc1 .Lxt5_has
	s_mov_b32 s99, 0
	s_branch .Lxt5_set

.LBB0_274:
	ds_read_b128 v[178:181], v152
	ds_read_b128 v[182:185], v152 offset:1024
	ds_read_b128 v[186:189], v151
	ds_read_b128 v[190:193], v151 offset:1024
	ds_read_b128 v[194:197], v150
	ds_read_b128 v[198:201], v150 offset:1024
	ds_read_b128 v[202:205], v149
	ds_read_b128 v[206:209], v149 offset:1024
	s_waitcnt lgkmcnt(8)
	s_waitcnt vmcnt(10)
	s_barrier
	s_waitcnt lgkmcnt(0)
	s_waitcnt lgkmcnt(0)
	v_mfma_f32_16x16x32_bf16 v[124:127], v[162:165], v[178:181], v[124:127]
	v_mfma_f32_16x16x32_bf16 v[120:123], v[170:173], v[178:181], v[120:123]
	v_mfma_f32_16x16x32_bf16 v[116:119], v[162:165], v[186:189], v[116:119]
	v_mfma_f32_16x16x32_bf16 v[112:115], v[170:173], v[186:189], v[112:115]
	v_mfma_f32_16x16x32_bf16 v[108:111], v[162:165], v[194:197], v[108:111]
	v_mfma_f32_16x16x32_bf16 v[104:107], v[170:173], v[194:197], v[104:107]
	v_mfma_f32_16x16x32_bf16 v[100:103], v[162:165], v[202:205], v[100:103]
	v_mfma_f32_16x16x32_bf16 v[96:99], v[170:173], v[202:205], v[96:99]
	v_mfma_f32_16x16x32_bf16 v[124:127], v[166:169], v[182:185], v[124:127]
	v_mfma_f32_16x16x32_bf16 v[120:123], v[174:177], v[182:185], v[120:123]
	v_mfma_f32_16x16x32_bf16 v[116:119], v[166:169], v[190:193], v[116:119]
	v_mfma_f32_16x16x32_bf16 v[112:115], v[174:177], v[190:193], v[112:115]
	v_mfma_f32_16x16x32_bf16 v[108:111], v[166:169], v[198:201], v[108:111]
	v_mfma_f32_16x16x32_bf16 v[104:107], v[174:177], v[198:201], v[104:107]
	v_mfma_f32_16x16x32_bf16 v[100:103], v[166:169], v[206:209], v[100:103]
	v_mfma_f32_16x16x32_bf16 v[96:99], v[174:177], v[206:209], v[96:99]
	s_barrier
	s_mov_b32 vcc_lo, 0xfffbd000
	s_mov_b32 vcc_hi, -1
	s_add_i32 s67, s98, 0x10000
	v_lshl_add_u64 v[226:227], v[130:131], 0, vcc
	s_mov_b32 m0, s67
	s_add_i32 s67, s98, 0x12000
	ds_read_b128 v[210:213], v158
	ds_read_b128 v[214:217], v158 offset:1024
	ds_read_b128 v[218:221], v158 offset:2048
	ds_read_b128 v[222:225], v158 offset:3072
	global_load_lds_dwordx4 v[226:227], off
	v_lshl_add_u64 v[226:227], v[130:131], 0, s[22:23]
	s_mov_b32 m0, s67
	s_add_i32 s66, s66, 2
	global_load_lds_dwordx4 v[226:227], off
	s_mov_b32 s67, s98
	v_lshl_add_u64 v[226:227], v[132:133], 0, s[24:25]
	s_mov_b32 m0, s67
	s_add_i32 s67, s98, 0x2000
	global_load_lds_dwordx4 v[226:227], off
	v_lshl_add_u64 v[226:227], v[132:133], 0, s[26:27]
	s_mov_b32 m0, s67
	s_nop 0
	global_load_lds_dwordx4 v[226:227], off
	s_waitcnt vmcnt(12)
	s_barrier
	s_waitcnt lgkmcnt(0)
	s_waitcnt lgkmcnt(0)
	v_mfma_f32_16x16x32_bf16 v[92:95], v[210:213], v[178:181], v[92:95]
	v_mfma_f32_16x16x32_bf16 v[88:91], v[218:221], v[178:181], v[88:91]
	v_mfma_f32_16x16x32_bf16 v[84:87], v[210:213], v[186:189], v[84:87]
	v_mfma_f32_16x16x32_bf16 v[80:83], v[218:221], v[186:189], v[80:83]
	v_mfma_f32_16x16x32_bf16 v[76:79], v[210:213], v[194:197], v[76:79]
	v_mfma_f32_16x16x32_bf16 v[72:75], v[218:221], v[194:197], v[72:75]
	v_mfma_f32_16x16x32_bf16 v[68:71], v[210:213], v[202:205], v[68:71]
	v_mfma_f32_16x16x32_bf16 v[64:67], v[218:221], v[202:205], v[64:67]
	v_mfma_f32_16x16x32_bf16 v[92:95], v[214:217], v[182:185], v[92:95]
	v_mfma_f32_16x16x32_bf16 v[88:91], v[222:225], v[182:185], v[88:91]
	v_mfma_f32_16x16x32_bf16 v[84:87], v[214:217], v[190:193], v[84:87]
	v_mfma_f32_16x16x32_bf16 v[80:83], v[222:225], v[190:193], v[80:83]
	v_mfma_f32_16x16x32_bf16 v[76:79], v[214:217], v[198:201], v[76:79]
	v_mfma_f32_16x16x32_bf16 v[72:75], v[222:225], v[198:201], v[72:75]
	v_mfma_f32_16x16x32_bf16 v[68:71], v[214:217], v[206:209], v[68:71]
	v_mfma_f32_16x16x32_bf16 v[64:67], v[222:225], v[206:209], v[64:67]
	s_barrier
	ds_read_b128 v[178:181], v152 offset:16384
	ds_read_b128 v[182:185], v152 offset:17408
	ds_read_b128 v[186:189], v151 offset:16384
	ds_read_b128 v[190:193], v151 offset:17408
	ds_read_b128 v[194:197], v150 offset:16384
	ds_read_b128 v[198:201], v150 offset:17408
	ds_read_b128 v[202:205], v149 offset:16384
	ds_read_b128 v[206:209], v149 offset:17408
	s_add_i32 s67, s98, 0x14000
	v_lshl_add_u64 v[226:227], v[130:131], 0, s[28:29]
	s_mov_b32 m0, s67
	s_add_i32 s67, s98, 0x16000
	global_load_lds_dwordx4 v[226:227], off
	v_lshl_add_u64 v[226:227], v[130:131], 0, s[30:31]
	s_mov_b32 m0, s67
	s_nop 0
	global_load_lds_dwordx4 v[226:227], off
	s_waitcnt vmcnt(12)
	s_barrier
	s_waitcnt lgkmcnt(0)
	s_waitcnt lgkmcnt(0)
	v_mfma_f32_16x16x32_bf16 v[60:63], v[162:165], v[178:181], v[60:63]
	v_mfma_f32_16x16x32_bf16 v[56:59], v[170:173], v[178:181], v[56:59]
	v_mfma_f32_16x16x32_bf16 v[52:55], v[162:165], v[186:189], v[52:55]
	v_mfma_f32_16x16x32_bf16 v[48:51], v[170:173], v[186:189], v[48:51]
	v_mfma_f32_16x16x32_bf16 v[44:47], v[162:165], v[194:197], v[44:47]
	v_mfma_f32_16x16x32_bf16 v[40:43], v[170:173], v[194:197], v[40:43]
	v_mfma_f32_16x16x32_bf16 v[36:39], v[162:165], v[202:205], v[36:39]
	v_mfma_f32_16x16x32_bf16 v[32:35], v[170:173], v[202:205], v[32:35]
	v_mfma_f32_16x16x32_bf16 v[60:63], v[166:169], v[182:185], v[60:63]
	v_mfma_f32_16x16x32_bf16 v[56:59], v[174:177], v[182:185], v[56:59]
	v_mfma_f32_16x16x32_bf16 v[52:55], v[166:169], v[190:193], v[52:55]
	v_mfma_f32_16x16x32_bf16 v[48:51], v[174:177], v[190:193], v[48:51]
	v_mfma_f32_16x16x32_bf16 v[44:47], v[166:169], v[198:201], v[44:47]
	v_mfma_f32_16x16x32_bf16 v[40:43], v[174:177], v[198:201], v[40:43]
	v_mfma_f32_16x16x32_bf16 v[36:39], v[166:169], v[206:209], v[36:39]
	v_mfma_f32_16x16x32_bf16 v[32:35], v[174:177], v[206:209], v[32:35]
	s_barrier
	s_add_i32 s67, s98, 0x4000
	v_lshl_add_u64 v[164:165], v[132:133], 0, s[34:35]
	s_mov_b32 m0, s67
	s_add_i32 s67, s98, 0x6000
	global_load_lds_dwordx4 v[164:165], off
	v_lshl_add_u64 v[164:165], v[132:133], 0, s[44:45]
	s_mov_b32 m0, s67
	s_nop 0
	global_load_lds_dwordx4 v[164:165], off
	ds_read_b128 v[162:165], v154
	ds_read_b128 v[166:169], v154 offset:1024
	ds_read_b128 v[170:173], v154 offset:2048
	ds_read_b128 v[174:177], v154 offset:3072
	s_waitcnt vmcnt(12)
	s_barrier
	v_mfma_f32_16x16x32_bf16 v[28:31], v[210:213], v[178:181], v[28:31]
	v_mfma_f32_16x16x32_bf16 v[24:27], v[218:221], v[178:181], v[24:27]
	v_mfma_f32_16x16x32_bf16 v[20:23], v[210:213], v[186:189], v[20:23]
	v_mfma_f32_16x16x32_bf16 v[16:19], v[218:221], v[186:189], v[16:19]
	v_mfma_f32_16x16x32_bf16 v[12:15], v[210:213], v[194:197], v[12:15]
	v_mfma_f32_16x16x32_bf16 v[8:11], v[218:221], v[194:197], v[8:11]
	v_mfma_f32_16x16x32_bf16 v[4:7], v[210:213], v[202:205], v[4:7]
	v_mfma_f32_16x16x32_bf16 v[0:3], v[218:221], v[202:205], v[0:3]
	v_mfma_f32_16x16x32_bf16 v[28:31], v[214:217], v[182:185], v[28:31]
	v_mfma_f32_16x16x32_bf16 v[24:27], v[222:225], v[182:185], v[24:27]
	v_mfma_f32_16x16x32_bf16 v[20:23], v[214:217], v[190:193], v[20:23]
	v_mfma_f32_16x16x32_bf16 v[16:19], v[222:225], v[190:193], v[16:19]
	v_mfma_f32_16x16x32_bf16 v[12:15], v[214:217], v[198:201], v[12:15]
	v_mfma_f32_16x16x32_bf16 v[8:11], v[222:225], v[198:201], v[8:11]
	v_mfma_f32_16x16x32_bf16 v[4:7], v[214:217], v[206:209], v[4:7]
	v_mfma_f32_16x16x32_bf16 v[0:3], v[222:225], v[206:209], v[0:3]
	s_barrier
	ds_read_b128 v[178:181], v152 offset:32768
	ds_read_b128 v[182:185], v152 offset:33792
	ds_read_b128 v[186:189], v151 offset:32768
	ds_read_b128 v[190:193], v151 offset:33792
	ds_read_b128 v[194:197], v150 offset:32768
	ds_read_b128 v[198:201], v150 offset:33792
	ds_read_b128 v[202:205], v149 offset:32768
	ds_read_b128 v[206:209], v149 offset:33792
	s_waitcnt lgkmcnt(8)
	s_waitcnt vmcnt(10)
	s_barrier
	s_waitcnt lgkmcnt(0)
	s_waitcnt lgkmcnt(0)
	v_mfma_f32_16x16x32_bf16 v[124:127], v[162:165], v[178:181], v[124:127]
	v_mfma_f32_16x16x32_bf16 v[120:123], v[170:173], v[178:181], v[120:123]
	v_mfma_f32_16x16x32_bf16 v[116:119], v[162:165], v[186:189], v[116:119]
	v_mfma_f32_16x16x32_bf16 v[112:115], v[170:173], v[186:189], v[112:115]
	v_mfma_f32_16x16x32_bf16 v[108:111], v[162:165], v[194:197], v[108:111]
	v_mfma_f32_16x16x32_bf16 v[104:107], v[170:173], v[194:197], v[104:107]
	v_mfma_f32_16x16x32_bf16 v[100:103], v[162:165], v[202:205], v[100:103]
	v_mfma_f32_16x16x32_bf16 v[96:99], v[170:173], v[202:205], v[96:99]
	v_mfma_f32_16x16x32_bf16 v[124:127], v[166:169], v[182:185], v[124:127]
	v_mfma_f32_16x16x32_bf16 v[120:123], v[174:177], v[182:185], v[120:123]
	v_mfma_f32_16x16x32_bf16 v[116:119], v[166:169], v[190:193], v[116:119]
	v_mfma_f32_16x16x32_bf16 v[112:115], v[174:177], v[190:193], v[112:115]
	v_mfma_f32_16x16x32_bf16 v[108:111], v[166:169], v[198:201], v[108:111]
	v_mfma_f32_16x16x32_bf16 v[104:107], v[174:177], v[198:201], v[104:107]
	v_mfma_f32_16x16x32_bf16 v[100:103], v[166:169], v[206:209], v[100:103]
	v_mfma_f32_16x16x32_bf16 v[96:99], v[174:177], v[206:209], v[96:99]
	s_barrier
	s_add_i32 s67, s98, 0x18000
	v_lshl_add_u64 v[226:227], v[130:131], 0, s[46:47]
	s_mov_b32 m0, s67
	s_add_i32 s67, s98, 0x1a000
	ds_read_b128 v[210:213], v153
	ds_read_b128 v[214:217], v153 offset:1024
	ds_read_b128 v[218:221], v153 offset:2048
	ds_read_b128 v[222:225], v153 offset:3072
	global_load_lds_dwordx4 v[226:227], off
	v_lshl_add_u64 v[226:227], v[130:131], 0, s[56:57]
	s_mov_b32 m0, s67
	s_nop 0
	global_load_lds_dwordx4 v[226:227], off
	s_add_i32 s67, s98, 0x8000
	v_lshl_add_u64 v[226:227], v[132:133], 0, s[58:59]
	s_mov_b32 m0, s67
	s_add_i32 s67, s98, 0xa000
	global_load_lds_dwordx4 v[226:227], off
	s_mov_b32 m0, s67
	s_nop 0
	global_load_lds_dwordx4 v[132:133], off
	s_waitcnt vmcnt(12)
	s_barrier
	s_waitcnt lgkmcnt(0)
	s_waitcnt lgkmcnt(0)
	v_mfma_f32_16x16x32_bf16 v[92:95], v[210:213], v[178:181], v[92:95]
	v_mfma_f32_16x16x32_bf16 v[88:91], v[218:221], v[178:181], v[88:91]
	v_mfma_f32_16x16x32_bf16 v[84:87], v[210:213], v[186:189], v[84:87]
	v_mfma_f32_16x16x32_bf16 v[80:83], v[218:221], v[186:189], v[80:83]
	v_mfma_f32_16x16x32_bf16 v[76:79], v[210:213], v[194:197], v[76:79]
	v_mfma_f32_16x16x32_bf16 v[72:75], v[218:221], v[194:197], v[72:75]
	v_mfma_f32_16x16x32_bf16 v[68:71], v[210:213], v[202:205], v[68:71]
	v_mfma_f32_16x16x32_bf16 v[64:67], v[218:221], v[202:205], v[64:67]
	v_mfma_f32_16x16x32_bf16 v[92:95], v[214:217], v[182:185], v[92:95]
	v_mfma_f32_16x16x32_bf16 v[88:91], v[222:225], v[182:185], v[88:91]
	v_mfma_f32_16x16x32_bf16 v[84:87], v[214:217], v[190:193], v[84:87]
	v_mfma_f32_16x16x32_bf16 v[80:83], v[222:225], v[190:193], v[80:83]
	v_mfma_f32_16x16x32_bf16 v[76:79], v[214:217], v[198:201], v[76:79]
	v_mfma_f32_16x16x32_bf16 v[72:75], v[222:225], v[198:201], v[72:75]
	v_mfma_f32_16x16x32_bf16 v[68:71], v[214:217], v[206:209], v[68:71]
	v_mfma_f32_16x16x32_bf16 v[64:67], v[222:225], v[206:209], v[64:67]
	s_barrier
	ds_read_b128 v[178:181], v152 offset:49152
	ds_read_b128 v[182:185], v152 offset:50176
	ds_read_b128 v[186:189], v151 offset:49152
	ds_read_b128 v[190:193], v151 offset:50176
	ds_read_b128 v[194:197], v150 offset:49152
	ds_read_b128 v[198:201], v150 offset:50176
	ds_read_b128 v[202:205], v149 offset:49152
	ds_read_b128 v[206:209], v149 offset:50176
	s_add_i32 s67, s98, 0x1c000
	v_lshl_add_u64 v[226:227], v[130:131], 0, s[58:59]
	s_mov_b32 m0, s67
	s_add_i32 s67, s98, 0x1e000
	global_load_lds_dwordx4 v[226:227], off
	s_mov_b32 m0, s67
	s_nop 0
	global_load_lds_dwordx4 v[130:131], off
	s_waitcnt vmcnt(12)
	s_barrier
	s_waitcnt lgkmcnt(0)
	s_waitcnt lgkmcnt(0)
	v_mfma_f32_16x16x32_bf16 v[60:63], v[162:165], v[178:181], v[60:63]
	v_mfma_f32_16x16x32_bf16 v[56:59], v[170:173], v[178:181], v[56:59]
	v_mfma_f32_16x16x32_bf16 v[52:55], v[162:165], v[186:189], v[52:55]
	v_mfma_f32_16x16x32_bf16 v[48:51], v[170:173], v[186:189], v[48:51]
	v_mfma_f32_16x16x32_bf16 v[44:47], v[162:165], v[194:197], v[44:47]
	v_mfma_f32_16x16x32_bf16 v[40:43], v[170:173], v[194:197], v[40:43]
	v_mfma_f32_16x16x32_bf16 v[36:39], v[162:165], v[202:205], v[36:39]
	v_mfma_f32_16x16x32_bf16 v[32:35], v[170:173], v[202:205], v[32:35]
	v_mfma_f32_16x16x32_bf16 v[60:63], v[166:169], v[182:185], v[60:63]
	v_mfma_f32_16x16x32_bf16 v[56:59], v[174:177], v[182:185], v[56:59]
	v_mfma_f32_16x16x32_bf16 v[52:55], v[166:169], v[190:193], v[52:55]
	v_mfma_f32_16x16x32_bf16 v[48:51], v[174:177], v[190:193], v[48:51]
	v_mfma_f32_16x16x32_bf16 v[44:47], v[166:169], v[198:201], v[44:47]
	v_mfma_f32_16x16x32_bf16 v[40:43], v[174:177], v[198:201], v[40:43]
	v_mfma_f32_16x16x32_bf16 v[36:39], v[166:169], v[206:209], v[36:39]
	v_mfma_f32_16x16x32_bf16 v[32:35], v[174:177], v[206:209], v[32:35]
	s_barrier
	v_lshl_add_u64 v[132:133], v[132:133], 0, s[62:63]
	s_mov_b32 vcc_lo, 0xffe01000
	s_mov_b32 vcc_hi, -1
	v_lshl_add_u64 v[164:165], v[132:133], 0, vcc
	s_add_i32 s67, s98, 0xc000
	s_mov_b32 vcc_lo, 0xffe02000
	s_mov_b32 m0, s67
	s_mov_b32 vcc_hi, -1
	s_add_i32 s67, s98, 0xe000
	global_load_lds_dwordx4 v[164:165], off
	v_lshl_add_u64 v[164:165], v[132:133], 0, vcc
	s_mov_b32 m0, s67
	s_nop 0
	global_load_lds_dwordx4 v[164:165], off
	ds_read_b128 v[162:165], v161
	ds_read_b128 v[166:169], v161 offset:1024
	ds_read_b128 v[170:173], v161 offset:2048
	ds_read_b128 v[174:177], v161 offset:3072
	s_waitcnt vmcnt(12)
	s_barrier
	v_mfma_f32_16x16x32_bf16 v[28:31], v[210:213], v[178:181], v[28:31]
	v_mfma_f32_16x16x32_bf16 v[24:27], v[218:221], v[178:181], v[24:27]
	v_mfma_f32_16x16x32_bf16 v[20:23], v[210:213], v[186:189], v[20:23]
	v_mfma_f32_16x16x32_bf16 v[16:19], v[218:221], v[186:189], v[16:19]
	v_mfma_f32_16x16x32_bf16 v[12:15], v[210:213], v[194:197], v[12:15]
	v_mfma_f32_16x16x32_bf16 v[8:11], v[218:221], v[194:197], v[8:11]
	v_mfma_f32_16x16x32_bf16 v[4:7], v[210:213], v[202:205], v[4:7]
	v_mfma_f32_16x16x32_bf16 v[0:3], v[218:221], v[202:205], v[0:3]
	v_mfma_f32_16x16x32_bf16 v[28:31], v[214:217], v[182:185], v[28:31]
	v_mfma_f32_16x16x32_bf16 v[24:27], v[222:225], v[182:185], v[24:27]
	v_mfma_f32_16x16x32_bf16 v[20:23], v[214:217], v[190:193], v[20:23]
	v_mfma_f32_16x16x32_bf16 v[16:19], v[222:225], v[190:193], v[16:19]
	v_mfma_f32_16x16x32_bf16 v[12:15], v[214:217], v[198:201], v[12:15]
	v_mfma_f32_16x16x32_bf16 v[8:11], v[222:225], v[198:201], v[8:11]
	v_mfma_f32_16x16x32_bf16 v[4:7], v[214:217], v[206:209], v[4:7]
	v_mfma_f32_16x16x32_bf16 v[0:3], v[222:225], v[206:209], v[0:3]
	v_lshl_add_u64 v[130:131], v[130:131], 0, s[60:61]
	s_cmp_lt_u32 s66, s65
	s_barrier
	s_cbranch_scc1 .LBB0_274
	s_lshl_b32 s65, s86, 5
	s_lshl_b32 s66, s86, 8
	s_and_b32 s65, s65, 0x1800
	s_and_b32 s66, s66, 0x700
	s_or_b32 s97, s66, s65
	s_lshl_b32 s65, s97, 6
	s_add_u32 s65, s68, s65
	s_addc_u32 s86, s69, 0
	s_add_i32 s20, s20, -1
	s_lshl_b64 s[66:67], s[20:21], 20
	v_add_u32_e32 v128, v156, v157
	s_add_u32 s66, s65, s66
	v_or_b32_e32 v128, v128, v155
	s_addc_u32 s67, s86, s67
	v_lshl_add_u64 v[156:157], s[66:67], 0, v[128:129]
	v_readfirstlane_b32 s20, v160
	v_lshl_add_u64 v[206:207], v[156:157], 0, s[4:5]
	s_mov_b32 m0, s20
	v_readfirstlane_b32 s20, v159
	ds_read_b128 v[130:133], v161
	ds_read_b128 v[162:165], v161 offset:1024
	ds_read_b128 v[166:169], v161 offset:2048
	ds_read_b128 v[170:173], v161 offset:3072
	ds_read_b128 v[174:177], v152
	ds_read_b128 v[178:181], v152 offset:1024
	ds_read_b128 v[182:185], v151
	ds_read_b128 v[186:189], v151 offset:1024
	ds_read_b128 v[190:193], v150
	ds_read_b128 v[194:197], v150 offset:1024
	ds_read_b128 v[198:201], v149
	ds_read_b128 v[202:205], v149 offset:1024
	v_lshl_add_u64 v[156:157], v[156:157], 0, s[6:7]
	s_mov_b32 m0, s20
	s_nop 0
	s_waitcnt vmcnt(8)
	s_barrier
	s_waitcnt lgkmcnt(0)
	s_setprio 1
	s_waitcnt lgkmcnt(0)
	v_mfma_f32_16x16x32_bf16 v[124:127], v[130:133], v[174:177], v[124:127]
	v_mfma_f32_16x16x32_bf16 v[120:123], v[166:169], v[174:177], v[120:123]
	v_mfma_f32_16x16x32_bf16 v[116:119], v[130:133], v[182:185], v[116:119]
	v_mfma_f32_16x16x32_bf16 v[112:115], v[166:169], v[182:185], v[112:115]
	v_mfma_f32_16x16x32_bf16 v[108:111], v[130:133], v[190:193], v[108:111]
	v_mfma_f32_16x16x32_bf16 v[104:107], v[166:169], v[190:193], v[104:107]
	v_mfma_f32_16x16x32_bf16 v[100:103], v[130:133], v[198:201], v[100:103]
	v_mfma_f32_16x16x32_bf16 v[96:99], v[166:169], v[198:201], v[96:99]
	v_mfma_f32_16x16x32_bf16 v[124:127], v[162:165], v[178:181], v[124:127]
	v_mfma_f32_16x16x32_bf16 v[120:123], v[170:173], v[178:181], v[120:123]
	v_mfma_f32_16x16x32_bf16 v[116:119], v[162:165], v[186:189], v[116:119]
	v_mfma_f32_16x16x32_bf16 v[112:115], v[170:173], v[186:189], v[112:115]
	v_mfma_f32_16x16x32_bf16 v[108:111], v[162:165], v[194:197], v[108:111]
	v_mfma_f32_16x16x32_bf16 v[104:107], v[170:173], v[194:197], v[104:107]
	v_mfma_f32_16x16x32_bf16 v[100:103], v[162:165], v[202:205], v[100:103]
	v_mfma_f32_16x16x32_bf16 v[96:99], v[170:173], v[202:205], v[96:99]
	s_setprio 0
	s_barrier
	ds_read_b128 v[206:209], v158
	ds_read_b128 v[210:213], v158 offset:1024
	ds_read_b128 v[214:217], v158 offset:2048
	ds_read_b128 v[156:159], v158 offset:3072
	s_barrier
	s_waitcnt lgkmcnt(0)
	s_setprio 1
	s_waitcnt lgkmcnt(0)
	v_mfma_f32_16x16x32_bf16 v[92:95], v[206:209], v[174:177], v[92:95]
	v_mfma_f32_16x16x32_bf16 v[88:91], v[214:217], v[174:177], v[88:91]
	v_mfma_f32_16x16x32_bf16 v[84:87], v[206:209], v[182:185], v[84:87]
	v_mfma_f32_16x16x32_bf16 v[80:83], v[214:217], v[182:185], v[80:83]
	v_mfma_f32_16x16x32_bf16 v[76:79], v[206:209], v[190:193], v[76:79]
	v_mfma_f32_16x16x32_bf16 v[72:75], v[214:217], v[190:193], v[72:75]
	v_mfma_f32_16x16x32_bf16 v[68:71], v[206:209], v[198:201], v[68:71]
	v_mfma_f32_16x16x32_bf16 v[64:67], v[214:217], v[198:201], v[64:67]
	v_mfma_f32_16x16x32_bf16 v[174:177], v[210:213], v[178:181], v[92:95]
	v_mfma_f32_16x16x32_bf16 v[178:181], v[156:159], v[178:181], v[88:91]
	v_mfma_f32_16x16x32_bf16 v[182:185], v[210:213], v[186:189], v[84:87]
	v_mfma_f32_16x16x32_bf16 v[186:189], v[156:159], v[186:189], v[80:83]
	v_mfma_f32_16x16x32_bf16 v[190:193], v[210:213], v[194:197], v[76:79]
	v_mfma_f32_16x16x32_bf16 v[194:197], v[156:159], v[194:197], v[72:75]
	v_mfma_f32_16x16x32_bf16 v[198:201], v[210:213], v[202:205], v[68:71]
	v_mfma_f32_16x16x32_bf16 v[202:205], v[156:159], v[202:205], v[64:67]
	s_setprio 0
	s_barrier
	s_nop 0
	ds_read_b128 v[64:67], v152 offset:16384
	ds_read_b128 v[68:71], v152 offset:17408
	ds_read_b128 v[72:75], v151 offset:16384
	ds_read_b128 v[76:79], v151 offset:17408
	ds_read_b128 v[80:83], v150 offset:16384
	ds_read_b128 v[84:87], v150 offset:17408
	ds_read_b128 v[88:91], v149 offset:16384
	ds_read_b128 v[92:95], v149 offset:17408
	s_waitcnt vmcnt(4)
	s_barrier
	s_waitcnt lgkmcnt(0)
	s_setprio 1
	s_waitcnt lgkmcnt(0)
	v_mfma_f32_16x16x32_bf16 v[60:63], v[130:133], v[64:67], v[60:63]
	v_mfma_f32_16x16x32_bf16 v[56:59], v[166:169], v[64:67], v[56:59]
	v_mfma_f32_16x16x32_bf16 v[52:55], v[130:133], v[72:75], v[52:55]
	v_mfma_f32_16x16x32_bf16 v[48:51], v[166:169], v[72:75], v[48:51]
	v_mfma_f32_16x16x32_bf16 v[218:221], v[130:133], v[80:83], v[44:47]
	v_mfma_f32_16x16x32_bf16 v[222:225], v[166:169], v[80:83], v[40:43]
	v_mfma_f32_16x16x32_bf16 v[130:133], v[130:133], v[88:91], v[36:39]
	v_mfma_f32_16x16x32_bf16 v[166:169], v[166:169], v[88:91], v[32:35]
	v_mfma_f32_16x16x32_bf16 v[32:35], v[162:165], v[68:71], v[60:63]
	v_mfma_f32_16x16x32_bf16 v[36:39], v[170:173], v[68:71], v[56:59]
	v_mfma_f32_16x16x32_bf16 v[40:43], v[162:165], v[76:79], v[52:55]
	v_mfma_f32_16x16x32_bf16 v[44:47], v[170:173], v[76:79], v[48:51]
	v_mfma_f32_16x16x32_bf16 v[48:51], v[162:165], v[84:87], v[218:221]
	v_mfma_f32_16x16x32_bf16 v[52:55], v[170:173], v[84:87], v[222:225]
	v_mfma_f32_16x16x32_bf16 v[56:59], v[162:165], v[92:95], v[130:133]
	v_mfma_f32_16x16x32_bf16 v[60:63], v[170:173], v[92:95], v[166:169]
	s_setprio 0
	s_setprio 1
	v_mfma_f32_16x16x32_bf16 v[28:31], v[206:209], v[64:67], v[28:31]
	v_mfma_f32_16x16x32_bf16 v[24:27], v[214:217], v[64:67], v[24:27]
	v_mfma_f32_16x16x32_bf16 v[20:23], v[206:209], v[72:75], v[20:23]
	v_mfma_f32_16x16x32_bf16 v[64:67], v[214:217], v[72:75], v[16:19]
	v_mfma_f32_16x16x32_bf16 v[72:75], v[206:209], v[80:83], v[12:15]
	v_mfma_f32_16x16x32_bf16 v[8:11], v[214:217], v[80:83], v[8:11]
	v_mfma_f32_16x16x32_bf16 v[80:83], v[206:209], v[88:91], v[4:7]
	v_mfma_f32_16x16x32_bf16 v[0:3], v[214:217], v[88:91], v[0:3]
	v_mfma_f32_16x16x32_bf16 v[4:7], v[210:213], v[68:71], v[28:31]
	v_mfma_f32_16x16x32_bf16 v[12:15], v[156:159], v[68:71], v[24:27]
	v_mfma_f32_16x16x32_bf16 v[16:19], v[210:213], v[76:79], v[20:23]
	v_mfma_f32_16x16x32_bf16 v[20:23], v[156:159], v[76:79], v[64:67]
	v_mfma_f32_16x16x32_bf16 v[24:27], v[210:213], v[84:87], v[72:75]
	v_mfma_f32_16x16x32_bf16 v[28:31], v[156:159], v[84:87], v[8:11]
	v_mfma_f32_16x16x32_bf16 v[64:67], v[210:213], v[92:95], v[80:83]
	v_mfma_f32_16x16x32_bf16 v[68:71], v[156:159], v[92:95], v[0:3]
	s_setprio 0
	s_barrier
	ds_read_b128 v[8:11], v154
	ds_read_b128 v[0:3], v154 offset:1024
	ds_read_b128 v[76:79], v154 offset:2048
	ds_read_b128 v[72:75], v154 offset:3072
	ds_read_b128 v[130:133], v152 offset:32768
	ds_read_b128 v[154:157], v152 offset:33792
	ds_read_b128 v[158:161], v151 offset:32768
	ds_read_b128 v[162:165], v151 offset:33792
	ds_read_b128 v[166:169], v150 offset:32768
	ds_read_b128 v[170:173], v150 offset:33792
	ds_read_b128 v[206:209], v149 offset:32768
	ds_read_b128 v[210:213], v149 offset:33792
	s_waitcnt vmcnt(2)
	s_barrier
	s_waitcnt lgkmcnt(0)
	s_setprio 1
	s_waitcnt lgkmcnt(0)
	v_mfma_f32_16x16x32_bf16 v[80:83], v[8:11], v[130:133], v[124:127]
	v_mfma_f32_16x16x32_bf16 v[84:87], v[76:79], v[130:133], v[120:123]
	v_mfma_f32_16x16x32_bf16 v[88:91], v[8:11], v[158:161], v[116:119]
	v_mfma_f32_16x16x32_bf16 v[92:95], v[76:79], v[158:161], v[112:115]
	v_mfma_f32_16x16x32_bf16 v[108:111], v[8:11], v[166:169], v[108:111]
	v_mfma_f32_16x16x32_bf16 v[104:107], v[76:79], v[166:169], v[104:107]
	v_mfma_f32_16x16x32_bf16 v[100:103], v[8:11], v[206:209], v[100:103]
	v_mfma_f32_16x16x32_bf16 v[96:99], v[76:79], v[206:209], v[96:99]
	v_mfma_f32_16x16x32_bf16 v[112:115], v[0:3], v[154:157], v[80:83]
	v_mfma_f32_16x16x32_bf16 v[116:119], v[72:75], v[154:157], v[84:87]
	v_mfma_f32_16x16x32_bf16 v[120:123], v[0:3], v[162:165], v[88:91]
	v_mfma_f32_16x16x32_bf16 v[124:127], v[72:75], v[162:165], v[92:95]
	v_mfma_f32_16x16x32_bf16 v[108:111], v[0:3], v[170:173], v[108:111]
	v_mfma_f32_16x16x32_bf16 v[104:107], v[72:75], v[170:173], v[104:107]
	v_mfma_f32_16x16x32_bf16 v[100:103], v[0:3], v[210:213], v[100:103]
	v_mfma_f32_16x16x32_bf16 v[96:99], v[72:75], v[210:213], v[96:99]
	s_setprio 0
	s_barrier
	ds_read_b128 v[88:91], v153
	ds_read_b128 v[80:83], v153 offset:1024
	ds_read_b128 v[92:95], v153 offset:2048
	ds_read_b128 v[84:87], v153 offset:3072
	s_waitcnt vmcnt(0)
	s_barrier
	s_waitcnt lgkmcnt(0)
	s_setprio 1
	s_waitcnt lgkmcnt(0)
	v_mfma_f32_16x16x32_bf16 v[174:177], v[88:91], v[130:133], v[174:177]
	v_mfma_f32_16x16x32_bf16 v[130:133], v[92:95], v[130:133], v[178:181]
	v_mfma_f32_16x16x32_bf16 v[178:181], v[88:91], v[158:161], v[182:185]
	v_mfma_f32_16x16x32_bf16 v[158:161], v[92:95], v[158:161], v[186:189]
	v_mfma_f32_16x16x32_bf16 v[182:185], v[88:91], v[166:169], v[190:193]
	v_mfma_f32_16x16x32_bf16 v[166:169], v[92:95], v[166:169], v[194:197]
	v_mfma_f32_16x16x32_bf16 v[186:189], v[88:91], v[206:209], v[198:201]
	v_mfma_f32_16x16x32_bf16 v[190:193], v[92:95], v[206:209], v[202:205]
	v_mfma_f32_16x16x32_bf16 v[174:177], v[80:83], v[154:157], v[174:177]
	v_mfma_f32_16x16x32_bf16 v[130:133], v[84:87], v[154:157], v[130:133]
	v_mfma_f32_16x16x32_bf16 v[154:157], v[80:83], v[162:165], v[178:181]
	v_mfma_f32_16x16x32_bf16 v[158:161], v[84:87], v[162:165], v[158:161]
	v_mfma_f32_16x16x32_bf16 v[162:165], v[80:83], v[170:173], v[182:185]
	v_mfma_f32_16x16x32_bf16 v[166:169], v[84:87], v[170:173], v[166:169]
	v_mfma_f32_16x16x32_bf16 v[170:173], v[80:83], v[210:213], v[186:189]
	v_mfma_f32_16x16x32_bf16 v[178:181], v[84:87], v[210:213], v[190:193]
	s_setprio 0
	s_barrier
	v_mbcnt_lo_u32_b32 v128, -1, 0
	v_mbcnt_hi_u32_b32 v128, -1, v128
	v_cvt_pk_bf16_f32 v112, v112, v113
	v_cvt_pk_bf16_f32 v113, v114, v115
	v_cvt_pk_bf16_f32 v114, v116, v117
	v_cvt_pk_bf16_f32 v115, v118, v119
	s_lshl_b32 s89, s64, 9
	v_add_u32_e32 v153, s72, v128
	v_ashrrev_i32_e32 v182, 6, v153
	v_and_b32_e32 v183, 15, v128
	v_and_b32_e32 v184, 48, v128
	v_mul_lo_u32 v185, v182, s77
	v_bfe_u32 v186, v128, 3, 3
	v_lshlrev_b32_e32 v128, 4, v128
	v_add_u32_e32 v185, 0x20000, v185
	v_lshrrev_b32_e32 v153, 2, v153
	v_and_b32_e32 v128, 0x70, v128
	v_mul_u32_u24_e32 v183, 0x90, v183
	v_and_b32_e32 v153, 64, v153
	v_add3_u32 v183, v185, v183, v184
	v_or_b32_e32 v184, v185, v128
	v_or3_b32 v153, s97, v153, v186
	v_mad_u32_u24 v184, v186, s79, v184
	ds_write_b128 v183, v[112:115]
	v_cvt_pk_bf16_f32 v112, v174, v175
	v_cvt_pk_bf16_f32 v113, v176, v177
	v_cvt_pk_bf16_f32 v114, v130, v131
	v_cvt_pk_bf16_f32 v115, v132, v133
	ds_write_b128 v183, v[112:115] offset:64
	v_lshlrev_b32_e32 v182, 7, v182
	ds_read_b128 v[112:115], v184
	v_lshlrev_b32_e32 v116, 12, v153
	v_and_or_b32 v116, v182, s80, v116
	v_or3_b32 v128, v116, s89, v128
	ds_read_b128 v[116:119], v184 offset:1152
	v_lshl_add_u64 v[130:131], s[0:1], 0, v[128:129]
	s_mov_b32 s20, 0x8000
	s_waitcnt lgkmcnt(0)
	global_store_dwordx4 v128, v[112:115], s[0:1]
	v_cvt_pk_bf16_f32 v108, v108, v109
	v_cvt_pk_bf16_f32 v109, v110, v111
	v_cvt_pk_bf16_f32 v110, v104, v105
	v_cvt_pk_bf16_f32 v111, v106, v107
	v_cvt_pk_bf16_f32 v104, v162, v163
	s_nop 1
	v_add_co_u32_e32 v112, vcc, s20, v130
	v_cvt_pk_bf16_f32 v114, v124, v125
	v_cvt_pk_bf16_f32 v115, v126, v127
	v_cvt_pk_bf16_f32 v105, v164, v165
	v_cvt_pk_bf16_f32 v106, v166, v167
	s_nop 1
	v_addc_co_u32_e32 v113, vcc, 0, v131, vcc
	global_store_dwordx4 v[112:113], v[116:119], off
	v_cvt_pk_bf16_f32 v112, v120, v121
	v_cvt_pk_bf16_f32 v113, v122, v123
	ds_write_b128 v183, v[112:115]
	v_cvt_pk_bf16_f32 v112, v154, v155
	v_cvt_pk_bf16_f32 v113, v156, v157
	v_cvt_pk_bf16_f32 v114, v158, v159
	v_cvt_pk_bf16_f32 v115, v160, v161
	ds_write_b128 v183, v[112:115] offset:64
	ds_read_b128 v[112:115], v184
	ds_read_b128 v[116:119], v184 offset:1152
	v_add_co_u32_e32 v120, vcc, s74, v130
	ds_write_b128 v183, v[108:111]
	v_cvt_pk_bf16_f32 v107, v168, v169
	ds_write_b128 v183, v[104:107] offset:64
	v_addc_co_u32_e32 v121, vcc, 0, v131, vcc
	ds_read_b128 v[104:107], v184
	ds_read_b128 v[108:111], v184 offset:1152
	s_waitcnt lgkmcnt(0)
	global_store_dwordx4 v[120:121], v[112:115], off
	v_cvt_pk_bf16_f32 v100, v100, v101
	v_cvt_pk_bf16_f32 v101, v102, v103
	v_cvt_pk_bf16_f32 v102, v96, v97
	v_cvt_pk_bf16_f32 v103, v98, v99
	ds_write_b128 v183, v[100:103]
	s_nop 0
	v_add_co_u32_e32 v112, vcc, s75, v130
	v_cvt_pk_bf16_f32 v96, v170, v171
	v_cvt_pk_bf16_f32 v97, v172, v173
	v_cvt_pk_bf16_f32 v98, v178, v179
	v_cvt_pk_bf16_f32 v99, v180, v181
	s_nop 1
	v_addc_co_u32_e32 v113, vcc, 0, v131, vcc
	global_store_dwordx4 v[112:113], v[116:119], off
	v_add_co_u32_e32 v112, vcc, s78, v130
	ds_write_b128 v183, v[96:99] offset:64
	s_nop 0
	v_addc_co_u32_e32 v113, vcc, 0, v131, vcc
	ds_read_b128 v[96:99], v184
	ds_read_b128 v[100:103], v184 offset:1152
	global_store_dwordx4 v[112:113], v[104:107], off
	s_nop 1
	v_add_co_u32_e32 v104, vcc, s81, v130
	s_nop 1
	v_addc_co_u32_e32 v105, vcc, 0, v131, vcc
	global_store_dwordx4 v[104:105], v[108:111], off
	v_add_co_u32_e32 v104, vcc, s82, v130
	s_nop 1
	v_addc_co_u32_e32 v105, vcc, 0, v131, vcc
	s_waitcnt lgkmcnt(0)
	global_store_dwordx4 v[104:105], v[96:99], off
	s_nop 1
	v_add_co_u32_e32 v96, vcc, s83, v130
	s_nop 1
	v_addc_co_u32_e32 v97, vcc, 0, v131, vcc
	global_store_dwordx4 v[96:97], v[100:103], off
	ds_read_b128 v[96:99], v152 offset:49152
	ds_read_b128 v[100:103], v152 offset:50176
	ds_read_b128 v[104:107], v151 offset:49152
	ds_read_b128 v[108:111], v151 offset:50176
	ds_read_b128 v[112:115], v150 offset:49152
	ds_read_b128 v[116:119], v150 offset:50176
	ds_read_b128 v[120:123], v149 offset:49152
	ds_read_b128 v[124:127], v149 offset:50176
	s_barrier
	s_waitcnt lgkmcnt(0)
	s_setprio 1
	s_waitcnt lgkmcnt(0)
	v_mfma_f32_16x16x32_bf16 v[32:35], v[8:11], v[96:99], v[32:35]
	v_mfma_f32_16x16x32_bf16 v[36:39], v[76:79], v[96:99], v[36:39]
	v_mfma_f32_16x16x32_bf16 v[40:43], v[8:11], v[104:107], v[40:43]
	v_mfma_f32_16x16x32_bf16 v[130:133], v[76:79], v[104:107], v[44:47]
	v_mfma_f32_16x16x32_bf16 v[150:153], v[8:11], v[112:115], v[48:51]
	v_mfma_f32_16x16x32_bf16 v[52:55], v[76:79], v[112:115], v[52:55]
	v_mfma_f32_16x16x32_bf16 v[8:11], v[8:11], v[120:123], v[56:59]
	v_mfma_f32_16x16x32_bf16 v[60:63], v[76:79], v[120:123], v[60:63]
	v_mfma_f32_16x16x32_bf16 v[56:59], v[0:3], v[100:103], v[32:35]
	v_mfma_f32_16x16x32_bf16 v[48:51], v[72:75], v[100:103], v[36:39]
	v_mfma_f32_16x16x32_bf16 v[44:47], v[0:3], v[108:111], v[40:43]
	v_mfma_f32_16x16x32_bf16 v[40:43], v[72:75], v[108:111], v[130:133]
	v_mfma_f32_16x16x32_bf16 v[36:39], v[0:3], v[116:119], v[150:153]
	v_mfma_f32_16x16x32_bf16 v[32:35], v[72:75], v[116:119], v[52:55]
	v_mfma_f32_16x16x32_bf16 v[8:11], v[0:3], v[124:127], v[8:11]
	v_mfma_f32_16x16x32_bf16 v[0:3], v[72:75], v[124:127], v[60:63]
	s_setprio 0
	s_setprio 1
	v_mfma_f32_16x16x32_bf16 v[4:7], v[88:91], v[96:99], v[4:7]
	v_mfma_f32_16x16x32_bf16 v[12:15], v[92:95], v[96:99], v[12:15]
	v_mfma_f32_16x16x32_bf16 v[16:19], v[88:91], v[104:107], v[16:19]
	v_mfma_f32_16x16x32_bf16 v[20:23], v[92:95], v[104:107], v[20:23]
	v_mfma_f32_16x16x32_bf16 v[72:75], v[88:91], v[112:115], v[24:27]
	v_mfma_f32_16x16x32_bf16 v[76:79], v[92:95], v[112:115], v[28:31]
	v_mfma_f32_16x16x32_bf16 v[64:67], v[88:91], v[120:123], v[64:67]
	v_mfma_f32_16x16x32_bf16 v[68:71], v[92:95], v[120:123], v[68:71]
	v_mfma_f32_16x16x32_bf16 v[60:63], v[80:83], v[100:103], v[4:7]
	v_mfma_f32_16x16x32_bf16 v[52:55], v[84:87], v[100:103], v[12:15]
	v_mfma_f32_16x16x32_bf16 v[28:31], v[80:83], v[108:111], v[16:19]
	v_mfma_f32_16x16x32_bf16 v[24:27], v[84:87], v[108:111], v[20:23]
	v_mfma_f32_16x16x32_bf16 v[20:23], v[80:83], v[116:119], v[72:75]
	v_mfma_f32_16x16x32_bf16 v[16:19], v[84:87], v[116:119], v[76:79]
	v_mfma_f32_16x16x32_bf16 v[12:15], v[80:83], v[124:127], v[64:67]
	v_mfma_f32_16x16x32_bf16 v[4:7], v[84:87], v[124:127], v[68:71]
	s_setprio 0
	v_cmp_gt_u32_e32 vcc, s85, v135
	s_barrier
	s_and_saveexec_b64 s[64:65], vcc
	s_cbranch_execz .LBB0_277
	s_barrier

.LBB0_356:
	ds_read_b128 v[154:157], v187
	ds_read_b128 v[158:161], v187 offset:1024
	ds_read_b128 v[188:191], v186
	ds_read_b128 v[192:195], v186 offset:1024
	ds_read_b128 v[196:199], v185
	ds_read_b128 v[200:203], v185 offset:1024
	ds_read_b128 v[204:207], v184
	ds_read_b128 v[208:211], v184 offset:1024
	s_waitcnt lgkmcnt(8)
	s_waitcnt vmcnt(10)
	s_barrier
	s_waitcnt lgkmcnt(0)
	s_waitcnt lgkmcnt(0)
	v_mfma_f32_16x16x32_bf16 v[124:127], v[138:141], v[154:157], v[124:127]
	v_mfma_f32_16x16x32_bf16 v[120:123], v[146:149], v[154:157], v[120:123]
	v_mfma_f32_16x16x32_bf16 v[116:119], v[138:141], v[188:191], v[116:119]
	v_mfma_f32_16x16x32_bf16 v[112:115], v[146:149], v[188:191], v[112:115]
	v_mfma_f32_16x16x32_bf16 v[108:111], v[138:141], v[196:199], v[108:111]
	v_mfma_f32_16x16x32_bf16 v[104:107], v[146:149], v[196:199], v[104:107]
	v_mfma_f32_16x16x32_bf16 v[100:103], v[138:141], v[204:207], v[100:103]
	v_mfma_f32_16x16x32_bf16 v[96:99], v[146:149], v[204:207], v[96:99]
	v_mfma_f32_16x16x32_bf16 v[124:127], v[142:145], v[158:161], v[124:127]
	v_mfma_f32_16x16x32_bf16 v[120:123], v[150:153], v[158:161], v[120:123]
	v_mfma_f32_16x16x32_bf16 v[116:119], v[142:145], v[192:195], v[116:119]
	v_mfma_f32_16x16x32_bf16 v[112:115], v[150:153], v[192:195], v[112:115]
	v_mfma_f32_16x16x32_bf16 v[108:111], v[142:145], v[200:203], v[108:111]
	v_mfma_f32_16x16x32_bf16 v[104:107], v[150:153], v[200:203], v[104:107]
	v_mfma_f32_16x16x32_bf16 v[100:103], v[142:145], v[208:211], v[100:103]
	v_mfma_f32_16x16x32_bf16 v[96:99], v[150:153], v[208:211], v[96:99]
	s_barrier
	s_add_u32 s70, s18, 1
	s_addc_u32 s71, s19, 0
	s_lshl_b64 s[72:73], s[70:71], s22
	s_add_u32 s74, s17, s72
	s_addc_u32 s75, s29, s73
	v_lshl_add_u64 v[162:163], s[74:75], 0, v[128:129]
	s_add_i32 s23, s98, 0x10000
	s_add_u32 s74, s74, s25
	s_mov_b32 m0, s23
	s_addc_u32 s75, s75, 0
	s_add_i32 s23, s98, 0x12000
	ds_read_b128 v[212:215], v131
	ds_read_b128 v[216:219], v131 offset:1024
	ds_read_b128 v[220:223], v131 offset:2048
	ds_read_b128 v[224:227], v131 offset:3072
	global_load_lds_dwordx4 v[162:163], off
	v_lshl_add_u64 v[162:163], s[74:75], 0, v[128:129]
	s_mov_b32 m0, s23
	s_nop 0
	global_load_lds_dwordx4 v[162:163], off
	s_lshl_b64 s[70:71], s[70:71], s28
	s_add_u32 s74, s15, s70
	s_addc_u32 s75, s30, s71
	v_lshl_add_u64 v[162:163], s[74:75], 0, v[164:165]
	s_mov_b32 s23, s98
	s_add_u32 s74, s74, s24
	s_mov_b32 m0, s23
	s_addc_u32 s75, s75, 0
	s_add_i32 s23, s98, 0x2000
	global_load_lds_dwordx4 v[162:163], off
	v_lshl_add_u64 v[162:163], s[74:75], 0, v[164:165]
	s_mov_b32 m0, s23
	s_nop 0
	global_load_lds_dwordx4 v[162:163], off
	s_waitcnt vmcnt(12)
	s_barrier
	s_waitcnt lgkmcnt(0)
	s_waitcnt lgkmcnt(0)
	v_mfma_f32_16x16x32_bf16 v[92:95], v[212:215], v[154:157], v[92:95]
	v_mfma_f32_16x16x32_bf16 v[88:91], v[220:223], v[154:157], v[88:91]
	v_mfma_f32_16x16x32_bf16 v[84:87], v[212:215], v[188:191], v[84:87]
	v_mfma_f32_16x16x32_bf16 v[80:83], v[220:223], v[188:191], v[80:83]
	v_mfma_f32_16x16x32_bf16 v[76:79], v[212:215], v[196:199], v[76:79]
	v_mfma_f32_16x16x32_bf16 v[72:75], v[220:223], v[196:199], v[72:75]
	v_mfma_f32_16x16x32_bf16 v[68:71], v[212:215], v[204:207], v[68:71]
	v_mfma_f32_16x16x32_bf16 v[64:67], v[220:223], v[204:207], v[64:67]
	v_mfma_f32_16x16x32_bf16 v[92:95], v[216:219], v[158:161], v[92:95]
	v_mfma_f32_16x16x32_bf16 v[88:91], v[224:227], v[158:161], v[88:91]
	v_mfma_f32_16x16x32_bf16 v[84:87], v[216:219], v[192:195], v[84:87]
	v_mfma_f32_16x16x32_bf16 v[80:83], v[224:227], v[192:195], v[80:83]
	v_mfma_f32_16x16x32_bf16 v[76:79], v[216:219], v[200:203], v[76:79]
	v_mfma_f32_16x16x32_bf16 v[72:75], v[224:227], v[200:203], v[72:75]
	v_mfma_f32_16x16x32_bf16 v[68:71], v[216:219], v[208:211], v[68:71]
	v_mfma_f32_16x16x32_bf16 v[64:67], v[224:227], v[208:211], v[64:67]
	s_barrier
	ds_read_b128 v[154:157], v187 offset:16384
	ds_read_b128 v[158:161], v187 offset:17408
	ds_read_b128 v[188:191], v186 offset:16384
	ds_read_b128 v[192:195], v186 offset:17408
	ds_read_b128 v[196:199], v185 offset:16384
	ds_read_b128 v[200:203], v185 offset:17408
	ds_read_b128 v[204:207], v184 offset:16384
	ds_read_b128 v[208:211], v184 offset:17408
	s_add_u32 s72, s20, s72
	s_addc_u32 s73, s21, s73
	v_lshl_add_u64 v[162:163], s[72:73], 0, v[128:129]
	s_add_i32 s23, s98, 0x14000
	s_add_u32 s72, s72, s25
	s_mov_b32 m0, s23
	s_addc_u32 s73, s73, 0
	s_add_i32 s23, s98, 0x16000
	global_load_lds_dwordx4 v[162:163], off
	v_lshl_add_u64 v[162:163], s[72:73], 0, v[128:129]
	s_mov_b32 m0, s23
	s_nop 0
	global_load_lds_dwordx4 v[162:163], off
	s_waitcnt vmcnt(12)
	s_barrier
	s_waitcnt lgkmcnt(0)
	s_waitcnt lgkmcnt(0)
	v_mfma_f32_16x16x32_bf16 v[60:63], v[138:141], v[154:157], v[60:63]
	v_mfma_f32_16x16x32_bf16 v[56:59], v[146:149], v[154:157], v[56:59]
	v_mfma_f32_16x16x32_bf16 v[52:55], v[138:141], v[188:191], v[52:55]
	v_mfma_f32_16x16x32_bf16 v[48:51], v[146:149], v[188:191], v[48:51]
	v_mfma_f32_16x16x32_bf16 v[44:47], v[138:141], v[196:199], v[44:47]
	v_mfma_f32_16x16x32_bf16 v[40:43], v[146:149], v[196:199], v[40:43]
	v_mfma_f32_16x16x32_bf16 v[36:39], v[138:141], v[204:207], v[36:39]
	v_mfma_f32_16x16x32_bf16 v[32:35], v[146:149], v[204:207], v[32:35]
	v_mfma_f32_16x16x32_bf16 v[60:63], v[142:145], v[158:161], v[60:63]
	v_mfma_f32_16x16x32_bf16 v[56:59], v[150:153], v[158:161], v[56:59]
	v_mfma_f32_16x16x32_bf16 v[52:55], v[142:145], v[192:195], v[52:55]
	v_mfma_f32_16x16x32_bf16 v[48:51], v[150:153], v[192:195], v[48:51]
	v_mfma_f32_16x16x32_bf16 v[44:47], v[142:145], v[200:203], v[44:47]
	v_mfma_f32_16x16x32_bf16 v[40:43], v[150:153], v[200:203], v[40:43]
	v_mfma_f32_16x16x32_bf16 v[36:39], v[142:145], v[208:211], v[36:39]
	v_mfma_f32_16x16x32_bf16 v[32:35], v[150:153], v[208:211], v[32:35]
	s_barrier
	s_add_u32 s70, s26, s70
	s_addc_u32 s71, s27, s71
	v_lshl_add_u64 v[162:163], s[70:71], 0, v[164:165]
	s_add_i32 s23, s98, 0x4000
	s_add_u32 s70, s70, s24
	s_mov_b32 m0, s23
	s_addc_u32 s71, s71, 0
	s_add_i32 s23, s98, 0x6000
	global_load_lds_dwordx4 v[162:163], off
	v_lshl_add_u64 v[162:163], s[70:71], 0, v[164:165]
	s_mov_b32 m0, s23
	s_nop 0
	global_load_lds_dwordx4 v[162:163], off
	ds_read_b128 v[138:141], v130
	ds_read_b128 v[142:145], v130 offset:1024
	ds_read_b128 v[146:149], v130 offset:2048
	ds_read_b128 v[150:153], v130 offset:3072
	s_waitcnt vmcnt(12)
	s_barrier
	v_mfma_f32_16x16x32_bf16 v[28:31], v[212:215], v[154:157], v[28:31]
	v_mfma_f32_16x16x32_bf16 v[24:27], v[220:223], v[154:157], v[24:27]
	v_mfma_f32_16x16x32_bf16 v[20:23], v[212:215], v[188:191], v[20:23]
	v_mfma_f32_16x16x32_bf16 v[16:19], v[220:223], v[188:191], v[16:19]
	v_mfma_f32_16x16x32_bf16 v[12:15], v[212:215], v[196:199], v[12:15]
	v_mfma_f32_16x16x32_bf16 v[8:11], v[220:223], v[196:199], v[8:11]
	v_mfma_f32_16x16x32_bf16 v[4:7], v[212:215], v[204:207], v[4:7]
	v_mfma_f32_16x16x32_bf16 v[0:3], v[220:223], v[204:207], v[0:3]
	v_mfma_f32_16x16x32_bf16 v[28:31], v[216:219], v[158:161], v[28:31]
	v_mfma_f32_16x16x32_bf16 v[24:27], v[224:227], v[158:161], v[24:27]
	v_mfma_f32_16x16x32_bf16 v[20:23], v[216:219], v[192:195], v[20:23]
	v_mfma_f32_16x16x32_bf16 v[16:19], v[224:227], v[192:195], v[16:19]
	v_mfma_f32_16x16x32_bf16 v[12:15], v[216:219], v[200:203], v[12:15]
	v_mfma_f32_16x16x32_bf16 v[8:11], v[224:227], v[200:203], v[8:11]
	v_mfma_f32_16x16x32_bf16 v[4:7], v[216:219], v[208:211], v[4:7]
	v_mfma_f32_16x16x32_bf16 v[0:3], v[224:227], v[208:211], v[0:3]
	s_barrier
	ds_read_b128 v[154:157], v187 offset:32768
	ds_read_b128 v[158:161], v187 offset:33792
	ds_read_b128 v[188:191], v186 offset:32768
	ds_read_b128 v[192:195], v186 offset:33792
	ds_read_b128 v[196:199], v185 offset:32768
	ds_read_b128 v[200:203], v185 offset:33792
	ds_read_b128 v[204:207], v184 offset:32768
	ds_read_b128 v[208:211], v184 offset:33792
	s_waitcnt lgkmcnt(8)
	s_waitcnt vmcnt(10)
	s_barrier
	s_waitcnt lgkmcnt(0)
	s_waitcnt lgkmcnt(0)
	v_mfma_f32_16x16x32_bf16 v[124:127], v[138:141], v[154:157], v[124:127]
	v_mfma_f32_16x16x32_bf16 v[120:123], v[146:149], v[154:157], v[120:123]
	v_mfma_f32_16x16x32_bf16 v[116:119], v[138:141], v[188:191], v[116:119]
	v_mfma_f32_16x16x32_bf16 v[112:115], v[146:149], v[188:191], v[112:115]
	v_mfma_f32_16x16x32_bf16 v[108:111], v[138:141], v[196:199], v[108:111]
	v_mfma_f32_16x16x32_bf16 v[104:107], v[146:149], v[196:199], v[104:107]
	v_mfma_f32_16x16x32_bf16 v[100:103], v[138:141], v[204:207], v[100:103]
	v_mfma_f32_16x16x32_bf16 v[96:99], v[146:149], v[204:207], v[96:99]
	v_mfma_f32_16x16x32_bf16 v[124:127], v[142:145], v[158:161], v[124:127]
	v_mfma_f32_16x16x32_bf16 v[120:123], v[150:153], v[158:161], v[120:123]
	v_mfma_f32_16x16x32_bf16 v[116:119], v[142:145], v[192:195], v[116:119]
	v_mfma_f32_16x16x32_bf16 v[112:115], v[150:153], v[192:195], v[112:115]
	v_mfma_f32_16x16x32_bf16 v[108:111], v[142:145], v[200:203], v[108:111]
	v_mfma_f32_16x16x32_bf16 v[104:107], v[150:153], v[200:203], v[104:107]
	v_mfma_f32_16x16x32_bf16 v[100:103], v[142:145], v[208:211], v[100:103]
	v_mfma_f32_16x16x32_bf16 v[96:99], v[150:153], v[208:211], v[96:99]
	s_barrier
	s_add_u32 s18, s18, 2
	s_addc_u32 s19, s19, 0
	s_lshl_b64 s[70:71], s[18:19], s22
	s_add_u32 s72, s17, s70
	s_addc_u32 s73, s29, s71
	v_lshl_add_u64 v[162:163], s[72:73], 0, v[128:129]
	s_add_i32 s23, s98, 0x18000
	s_add_u32 s72, s72, s25
	s_mov_b32 m0, s23
	s_addc_u32 s73, s73, 0
	s_add_i32 s23, s98, 0x1a000
	ds_read_b128 v[212:215], v136
	ds_read_b128 v[216:219], v136 offset:1024
	ds_read_b128 v[220:223], v136 offset:2048
	ds_read_b128 v[224:227], v136 offset:3072
	global_load_lds_dwordx4 v[162:163], off
	v_lshl_add_u64 v[162:163], s[72:73], 0, v[128:129]
	s_mov_b32 m0, s23
	s_nop 0
	global_load_lds_dwordx4 v[162:163], off
	s_lshl_b64 s[72:73], s[18:19], s28
	s_add_u32 s72, s15, s72
	s_addc_u32 s73, s30, s73
	v_lshl_add_u64 v[162:163], s[72:73], 0, v[164:165]
	s_add_i32 s23, s98, 0x8000
	s_add_u32 s72, s72, s24
	s_mov_b32 m0, s23
	s_addc_u32 s73, s73, 0
	s_add_i32 s23, s98, 0xa000
	global_load_lds_dwordx4 v[162:163], off
	v_lshl_add_u64 v[162:163], s[72:73], 0, v[164:165]
	s_mov_b32 m0, s23
	s_nop 0
	global_load_lds_dwordx4 v[162:163], off
	s_waitcnt vmcnt(12)
	s_barrier
	s_waitcnt lgkmcnt(0)
	s_waitcnt lgkmcnt(0)
	v_mfma_f32_16x16x32_bf16 v[92:95], v[212:215], v[154:157], v[92:95]
	v_mfma_f32_16x16x32_bf16 v[88:91], v[220:223], v[154:157], v[88:91]
	v_mfma_f32_16x16x32_bf16 v[84:87], v[212:215], v[188:191], v[84:87]
	v_mfma_f32_16x16x32_bf16 v[80:83], v[220:223], v[188:191], v[80:83]
	v_mfma_f32_16x16x32_bf16 v[76:79], v[212:215], v[196:199], v[76:79]
	v_mfma_f32_16x16x32_bf16 v[72:75], v[220:223], v[196:199], v[72:75]
	v_mfma_f32_16x16x32_bf16 v[68:71], v[212:215], v[204:207], v[68:71]
	v_mfma_f32_16x16x32_bf16 v[64:67], v[220:223], v[204:207], v[64:67]
	v_mfma_f32_16x16x32_bf16 v[92:95], v[216:219], v[158:161], v[92:95]
	v_mfma_f32_16x16x32_bf16 v[88:91], v[224:227], v[158:161], v[88:91]
	v_mfma_f32_16x16x32_bf16 v[84:87], v[216:219], v[192:195], v[84:87]
	v_mfma_f32_16x16x32_bf16 v[80:83], v[224:227], v[192:195], v[80:83]
	v_mfma_f32_16x16x32_bf16 v[76:79], v[216:219], v[200:203], v[76:79]
	v_mfma_f32_16x16x32_bf16 v[72:75], v[224:227], v[200:203], v[72:75]
	v_mfma_f32_16x16x32_bf16 v[68:71], v[216:219], v[208:211], v[68:71]
	v_mfma_f32_16x16x32_bf16 v[64:67], v[224:227], v[208:211], v[64:67]
	s_barrier
	ds_read_b128 v[154:157], v187 offset:49152
	ds_read_b128 v[158:161], v187 offset:50176
	ds_read_b128 v[188:191], v186 offset:49152
	ds_read_b128 v[192:195], v186 offset:50176
	ds_read_b128 v[196:199], v185 offset:49152
	ds_read_b128 v[200:203], v185 offset:50176
	ds_read_b128 v[204:207], v184 offset:49152
	ds_read_b128 v[208:211], v184 offset:50176
	s_add_u32 s70, s20, s70
	s_addc_u32 s71, s21, s71
	v_lshl_add_u64 v[162:163], s[70:71], 0, v[128:129]
	s_add_i32 s23, s98, 0x1c000
	s_add_u32 s70, s70, s25
	s_mov_b32 m0, s23
	s_addc_u32 s71, s71, 0
	s_add_i32 s23, s98, 0x1e000
	global_load_lds_dwordx4 v[162:163], off
	v_lshl_add_u64 v[162:163], s[70:71], 0, v[128:129]
	s_mov_b32 m0, s23
	s_nop 0
	global_load_lds_dwordx4 v[162:163], off
	s_waitcnt vmcnt(12)
	s_barrier
	s_waitcnt lgkmcnt(0)
	s_waitcnt lgkmcnt(0)
	v_mfma_f32_16x16x32_bf16 v[60:63], v[138:141], v[154:157], v[60:63]
	v_mfma_f32_16x16x32_bf16 v[56:59], v[146:149], v[154:157], v[56:59]
	v_mfma_f32_16x16x32_bf16 v[52:55], v[138:141], v[188:191], v[52:55]
	v_mfma_f32_16x16x32_bf16 v[48:51], v[146:149], v[188:191], v[48:51]
	v_mfma_f32_16x16x32_bf16 v[44:47], v[138:141], v[196:199], v[44:47]
	v_mfma_f32_16x16x32_bf16 v[40:43], v[146:149], v[196:199], v[40:43]
	v_mfma_f32_16x16x32_bf16 v[36:39], v[138:141], v[204:207], v[36:39]
	v_mfma_f32_16x16x32_bf16 v[32:35], v[146:149], v[204:207], v[32:35]
	v_mfma_f32_16x16x32_bf16 v[60:63], v[142:145], v[158:161], v[60:63]
	v_mfma_f32_16x16x32_bf16 v[56:59], v[150:153], v[158:161], v[56:59]
	v_mfma_f32_16x16x32_bf16 v[52:55], v[142:145], v[192:195], v[52:55]
	v_mfma_f32_16x16x32_bf16 v[48:51], v[150:153], v[192:195], v[48:51]
	v_mfma_f32_16x16x32_bf16 v[44:47], v[142:145], v[200:203], v[44:47]
	v_mfma_f32_16x16x32_bf16 v[40:43], v[150:153], v[200:203], v[40:43]
	v_mfma_f32_16x16x32_bf16 v[36:39], v[142:145], v[208:211], v[36:39]
	v_mfma_f32_16x16x32_bf16 v[32:35], v[150:153], v[208:211], v[32:35]
	s_barrier
	s_lshl_b64 s[70:71], s[18:19], s28
	s_add_u32 s70, s26, s70
	s_addc_u32 s71, s27, s71
	v_lshl_add_u64 v[162:163], s[70:71], 0, v[164:165]
	s_add_i32 s23, s98, 0xc000
	s_add_u32 s70, s70, s24
	s_mov_b32 m0, s23
	s_addc_u32 s71, s71, 0
	s_add_i32 s23, s98, 0xe000
	global_load_lds_dwordx4 v[162:163], off
	v_lshl_add_u64 v[162:163], s[70:71], 0, v[164:165]
	s_mov_b32 m0, s23
	s_nop 0
	global_load_lds_dwordx4 v[162:163], off
	ds_read_b128 v[138:141], v134
	ds_read_b128 v[142:145], v134 offset:1024
	ds_read_b128 v[146:149], v134 offset:2048
	ds_read_b128 v[150:153], v134 offset:3072
	s_waitcnt vmcnt(12)
	s_barrier
	v_mfma_f32_16x16x32_bf16 v[28:31], v[212:215], v[154:157], v[28:31]
	v_mfma_f32_16x16x32_bf16 v[24:27], v[220:223], v[154:157], v[24:27]
	v_mfma_f32_16x16x32_bf16 v[20:23], v[212:215], v[188:191], v[20:23]
	v_mfma_f32_16x16x32_bf16 v[16:19], v[220:223], v[188:191], v[16:19]
	v_mfma_f32_16x16x32_bf16 v[12:15], v[212:215], v[196:199], v[12:15]
	v_mfma_f32_16x16x32_bf16 v[8:11], v[220:223], v[196:199], v[8:11]
	v_mfma_f32_16x16x32_bf16 v[4:7], v[212:215], v[204:207], v[4:7]
	v_mfma_f32_16x16x32_bf16 v[0:3], v[220:223], v[204:207], v[0:3]
	v_mfma_f32_16x16x32_bf16 v[28:31], v[216:219], v[158:161], v[28:31]
	v_mfma_f32_16x16x32_bf16 v[24:27], v[224:227], v[158:161], v[24:27]
	v_mfma_f32_16x16x32_bf16 v[20:23], v[216:219], v[192:195], v[20:23]
	v_mfma_f32_16x16x32_bf16 v[16:19], v[224:227], v[192:195], v[16:19]
	v_mfma_f32_16x16x32_bf16 v[12:15], v[216:219], v[200:203], v[12:15]
	v_mfma_f32_16x16x32_bf16 v[8:11], v[224:227], v[200:203], v[8:11]
	v_mfma_f32_16x16x32_bf16 v[4:7], v[216:219], v[208:211], v[4:7]
	v_mfma_f32_16x16x32_bf16 v[0:3], v[224:227], v[208:211], v[0:3]
	s_add_i32 s23, s18, -3
	s_cmp_lt_u32 s23, 28
	s_barrier
	s_cbranch_scc1 .LBB0_356
	s_lshl_b64 s[18:19], 31, s28
	s_add_u32 s18, s26, s18
	s_addc_u32 s19, s27, s19
	v_lshl_add_u64 v[128:129], s[18:19], 0, v[164:165]
	v_readfirstlane_b32 s15, v133
	s_add_u32 s18, s18, s24
	s_mov_b32 m0, s15
	s_addc_u32 s19, s19, 0
	v_readfirstlane_b32 s15, v132
	ds_read_b128 v[138:141], v134
	ds_read_b128 v[142:145], v134 offset:1024
	ds_read_b128 v[146:149], v134 offset:2048
	ds_read_b128 v[150:153], v134 offset:3072
	ds_read_b128 v[154:157], v187
	ds_read_b128 v[158:161], v187 offset:1024
	ds_read_b128 v[188:191], v186
	ds_read_b128 v[192:195], v186 offset:1024
	ds_read_b128 v[196:199], v185
	ds_read_b128 v[200:203], v185 offset:1024
	ds_read_b128 v[204:207], v184
	ds_read_b128 v[208:211], v184 offset:1024
	v_lshl_add_u64 v[128:129], s[18:19], 0, v[164:165]
	s_mov_b32 m0, s15
	s_nop 0
	s_waitcnt vmcnt(8)
	s_barrier
	s_waitcnt lgkmcnt(0)
	s_setprio 1
	s_waitcnt lgkmcnt(0)
	v_mfma_f32_16x16x32_bf16 v[124:127], v[138:141], v[154:157], v[124:127]
	v_mfma_f32_16x16x32_bf16 v[120:123], v[146:149], v[154:157], v[120:123]
	v_mfma_f32_16x16x32_bf16 v[116:119], v[138:141], v[188:191], v[116:119]
	v_mfma_f32_16x16x32_bf16 v[112:115], v[146:149], v[188:191], v[112:115]
	v_mfma_f32_16x16x32_bf16 v[108:111], v[138:141], v[196:199], v[108:111]
	v_mfma_f32_16x16x32_bf16 v[104:107], v[146:149], v[196:199], v[104:107]
	v_mfma_f32_16x16x32_bf16 v[100:103], v[138:141], v[204:207], v[100:103]
	v_mfma_f32_16x16x32_bf16 v[96:99], v[146:149], v[204:207], v[96:99]
	v_mfma_f32_16x16x32_bf16 v[124:127], v[142:145], v[158:161], v[124:127]
	v_mfma_f32_16x16x32_bf16 v[120:123], v[150:153], v[158:161], v[120:123]
	v_mfma_f32_16x16x32_bf16 v[116:119], v[142:145], v[192:195], v[116:119]
	v_mfma_f32_16x16x32_bf16 v[112:115], v[150:153], v[192:195], v[112:115]
	v_mfma_f32_16x16x32_bf16 v[108:111], v[142:145], v[200:203], v[108:111]
	v_mfma_f32_16x16x32_bf16 v[104:107], v[150:153], v[200:203], v[104:107]
	v_mfma_f32_16x16x32_bf16 v[100:103], v[142:145], v[208:211], v[100:103]
	v_mfma_f32_16x16x32_bf16 v[96:99], v[150:153], v[208:211], v[96:99]
	s_setprio 0
	s_barrier
	ds_read_b128 v[132:135], v131
	ds_read_b128 v[212:215], v131 offset:1024
	ds_read_b128 v[216:219], v131 offset:2048
	ds_read_b128 v[220:223], v131 offset:3072
	s_barrier
	s_waitcnt lgkmcnt(0)
	s_setprio 1
	s_waitcnt lgkmcnt(0)
	v_mfma_f32_16x16x32_bf16 v[92:95], v[132:135], v[154:157], v[92:95]
	v_mfma_f32_16x16x32_bf16 v[88:91], v[216:219], v[154:157], v[88:91]
	v_mfma_f32_16x16x32_bf16 v[84:87], v[132:135], v[188:191], v[84:87]
	v_mfma_f32_16x16x32_bf16 v[80:83], v[216:219], v[188:191], v[80:83]
	v_mfma_f32_16x16x32_bf16 v[76:79], v[132:135], v[196:199], v[76:79]
	v_mfma_f32_16x16x32_bf16 v[72:75], v[216:219], v[196:199], v[72:75]
	v_mfma_f32_16x16x32_bf16 v[68:71], v[132:135], v[204:207], v[68:71]
	v_mfma_f32_16x16x32_bf16 v[64:67], v[216:219], v[204:207], v[64:67]
	v_mfma_f32_16x16x32_bf16 v[154:157], v[212:215], v[158:161], v[92:95]
	v_mfma_f32_16x16x32_bf16 v[158:161], v[220:223], v[158:161], v[88:91]
	v_mfma_f32_16x16x32_bf16 v[188:191], v[212:215], v[192:195], v[84:87]
	v_mfma_f32_16x16x32_bf16 v[192:195], v[220:223], v[192:195], v[80:83]
	v_mfma_f32_16x16x32_bf16 v[196:199], v[212:215], v[200:203], v[76:79]
	v_mfma_f32_16x16x32_bf16 v[200:203], v[220:223], v[200:203], v[72:75]
	v_mfma_f32_16x16x32_bf16 v[204:207], v[212:215], v[208:211], v[68:71]
	v_mfma_f32_16x16x32_bf16 v[208:211], v[220:223], v[208:211], v[64:67]
	s_setprio 0
	s_barrier
	s_nop 0
	ds_read_b128 v[64:67], v187 offset:16384
	ds_read_b128 v[68:71], v187 offset:17408
	ds_read_b128 v[72:75], v186 offset:16384
	ds_read_b128 v[76:79], v186 offset:17408
	ds_read_b128 v[80:83], v185 offset:16384
	ds_read_b128 v[84:87], v185 offset:17408
	ds_read_b128 v[88:91], v184 offset:16384
	ds_read_b128 v[92:95], v184 offset:17408
	s_waitcnt vmcnt(4)
	s_barrier
	s_waitcnt lgkmcnt(0)
	s_setprio 1
	s_waitcnt lgkmcnt(0)
	v_mfma_f32_16x16x32_bf16 v[60:63], v[138:141], v[64:67], v[60:63]
	v_mfma_f32_16x16x32_bf16 v[56:59], v[146:149], v[64:67], v[56:59]
	v_mfma_f32_16x16x32_bf16 v[52:55], v[138:141], v[72:75], v[52:55]
	v_mfma_f32_16x16x32_bf16 v[48:51], v[146:149], v[72:75], v[48:51]
	v_mfma_f32_16x16x32_bf16 v[224:227], v[138:141], v[80:83], v[44:47]
	v_mfma_f32_16x16x32_bf16 v[228:231], v[146:149], v[80:83], v[40:43]
	v_mfma_f32_16x16x32_bf16 v[138:141], v[138:141], v[88:91], v[36:39]
	v_mfma_f32_16x16x32_bf16 v[146:149], v[146:149], v[88:91], v[32:35]
	v_mfma_f32_16x16x32_bf16 v[32:35], v[142:145], v[68:71], v[60:63]
	v_mfma_f32_16x16x32_bf16 v[36:39], v[150:153], v[68:71], v[56:59]
	v_mfma_f32_16x16x32_bf16 v[40:43], v[142:145], v[76:79], v[52:55]
	v_mfma_f32_16x16x32_bf16 v[44:47], v[150:153], v[76:79], v[48:51]
	v_mfma_f32_16x16x32_bf16 v[48:51], v[142:145], v[84:87], v[224:227]
	v_mfma_f32_16x16x32_bf16 v[52:55], v[150:153], v[84:87], v[228:231]
	v_mfma_f32_16x16x32_bf16 v[56:59], v[142:145], v[92:95], v[138:141]
	v_mfma_f32_16x16x32_bf16 v[60:63], v[150:153], v[92:95], v[146:149]
	s_setprio 0
	s_setprio 1
	v_mfma_f32_16x16x32_bf16 v[28:31], v[132:135], v[64:67], v[28:31]
	v_mfma_f32_16x16x32_bf16 v[24:27], v[216:219], v[64:67], v[24:27]
	v_mfma_f32_16x16x32_bf16 v[20:23], v[132:135], v[72:75], v[20:23]
	v_mfma_f32_16x16x32_bf16 v[16:19], v[216:219], v[72:75], v[16:19]
	v_mfma_f32_16x16x32_bf16 v[64:67], v[132:135], v[80:83], v[12:15]
	v_mfma_f32_16x16x32_bf16 v[8:11], v[216:219], v[80:83], v[8:11]
	v_mfma_f32_16x16x32_bf16 v[72:75], v[132:135], v[88:91], v[4:7]
	v_mfma_f32_16x16x32_bf16 v[0:3], v[216:219], v[88:91], v[0:3]
	v_mfma_f32_16x16x32_bf16 v[4:7], v[212:215], v[68:71], v[28:31]
	v_mfma_f32_16x16x32_bf16 v[12:15], v[220:223], v[68:71], v[24:27]
	v_mfma_f32_16x16x32_bf16 v[20:23], v[212:215], v[76:79], v[20:23]
	v_mfma_f32_16x16x32_bf16 v[28:31], v[220:223], v[76:79], v[16:19]
	v_mfma_f32_16x16x32_bf16 v[64:67], v[212:215], v[84:87], v[64:67]
	v_mfma_f32_16x16x32_bf16 v[68:71], v[220:223], v[84:87], v[8:11]
	v_mfma_f32_16x16x32_bf16 v[72:75], v[212:215], v[92:95], v[72:75]
	v_mfma_f32_16x16x32_bf16 v[76:79], v[220:223], v[92:95], v[0:3]
	s_setprio 0
	s_barrier
	ds_read_b128 v[8:11], v130
	ds_read_b128 v[0:3], v130 offset:1024
	ds_read_b128 v[16:19], v130 offset:2048
	ds_read_b128 v[80:83], v130 offset:3072
	ds_read_b128 v[138:141], v187 offset:32768
	ds_read_b128 v[212:215], v187 offset:33792
	ds_read_b128 v[216:219], v186 offset:32768
	ds_read_b128 v[220:223], v186 offset:33792
	ds_read_b128 v[224:227], v185 offset:32768
	ds_read_b128 v[228:231], v185 offset:33792
	ds_read_b128 v[232:235], v184 offset:32768
	ds_read_b128 v[236:239], v184 offset:33792
	s_waitcnt vmcnt(2)
	s_barrier
	s_waitcnt lgkmcnt(0)
	s_setprio 1
	s_waitcnt lgkmcnt(0)
	v_mfma_f32_16x16x32_bf16 v[24:27], v[8:11], v[138:141], v[124:127]
	v_mfma_f32_16x16x32_bf16 v[84:87], v[16:19], v[138:141], v[120:123]
	v_mfma_f32_16x16x32_bf16 v[88:91], v[8:11], v[216:219], v[116:119]
	v_mfma_f32_16x16x32_bf16 v[92:95], v[16:19], v[216:219], v[112:115]
	v_mfma_f32_16x16x32_bf16 v[108:111], v[8:11], v[224:227], v[108:111]
	v_mfma_f32_16x16x32_bf16 v[104:107], v[16:19], v[224:227], v[104:107]
	v_mfma_f32_16x16x32_bf16 v[100:103], v[8:11], v[232:235], v[100:103]
	v_mfma_f32_16x16x32_bf16 v[96:99], v[16:19], v[232:235], v[96:99]
	v_mfma_f32_16x16x32_bf16 v[148:151], v[0:3], v[212:215], v[24:27]
	v_mfma_f32_16x16x32_bf16 v[144:147], v[80:83], v[212:215], v[84:87]
	v_mfma_f32_16x16x32_bf16 v[132:135], v[0:3], v[220:223], v[88:91]
	v_mfma_f32_16x16x32_bf16 v[128:131], v[80:83], v[220:223], v[92:95]
	v_mfma_f32_16x16x32_bf16 v[116:119], v[0:3], v[228:231], v[108:111]
	v_mfma_f32_16x16x32_bf16 v[112:115], v[80:83], v[228:231], v[104:107]
	v_mfma_f32_16x16x32_bf16 v[100:103], v[0:3], v[236:239], v[100:103]
	v_mfma_f32_16x16x32_bf16 v[24:27], v[80:83], v[236:239], v[96:99]
	s_setprio 0
	s_barrier
	ds_read_b128 v[92:95], v136
	ds_read_b128 v[84:87], v136 offset:1024
	ds_read_b128 v[96:99], v136 offset:2048
	ds_read_b128 v[88:91], v136 offset:3072
	s_waitcnt vmcnt(0)
	s_barrier
	s_waitcnt lgkmcnt(0)
	s_setprio 1
	s_waitcnt lgkmcnt(0)
	v_mfma_f32_16x16x32_bf16 v[104:107], v[92:95], v[138:141], v[154:157]
	v_mfma_f32_16x16x32_bf16 v[108:111], v[96:99], v[138:141], v[158:161]
	v_mfma_f32_16x16x32_bf16 v[120:123], v[92:95], v[216:219], v[188:191]
	v_mfma_f32_16x16x32_bf16 v[124:127], v[96:99], v[216:219], v[192:195]
	v_mfma_f32_16x16x32_bf16 v[160:163], v[92:95], v[224:227], v[196:199]
	v_mfma_f32_16x16x32_bf16 v[188:191], v[96:99], v[224:227], v[200:203]
	v_mfma_f32_16x16x32_bf16 v[192:195], v[92:95], v[232:235], v[204:207]
	v_mfma_f32_16x16x32_bf16 v[196:199], v[96:99], v[232:235], v[208:211]
	v_mfma_f32_16x16x32_bf16 v[156:159], v[84:87], v[212:215], v[104:107]
	v_mfma_f32_16x16x32_bf16 v[152:155], v[88:91], v[212:215], v[108:111]
	v_mfma_f32_16x16x32_bf16 v[140:143], v[84:87], v[220:223], v[120:123]
	v_mfma_f32_16x16x32_bf16 v[136:139], v[88:91], v[220:223], v[124:127]
	v_mfma_f32_16x16x32_bf16 v[124:127], v[84:87], v[228:231], v[160:163]
	v_mfma_f32_16x16x32_bf16 v[120:123], v[88:91], v[228:231], v[188:191]
	v_mfma_f32_16x16x32_bf16 v[108:111], v[84:87], v[236:239], v[192:195]
	v_mfma_f32_16x16x32_bf16 v[104:107], v[88:91], v[236:239], v[196:199]
	s_setprio 0
	s_barrier
	v_mbcnt_lo_u32_b32 v164, -1, 0
	v_mbcnt_hi_u32_b32 v164, -1, v164
	s_cmp_lt_i32 s64, 3
	v_add_u32_e32 v160, s34, v164
	v_ashrrev_i32_e32 v192, 6, v160
	v_bfe_u32 v190, v160, 8, 1
	v_and_b32_e32 v191, 3, v192
	v_and_b32_e32 v188, 15, v164
	v_bfe_u32 v189, v160, 4, 2
	s_mov_b64 s[18:19], 0
	s_cbranch_scc1 .LBB0_362
	v_lshrrev_b32_e32 v160, 4, v160
	v_lshlrev_b32_e32 v162, 9, v189
	v_lshlrev_b32_e32 v163, 9, v160
	s_mov_b64 s[20:21], -1
	s_cmp_gt_i32 s64, 3
	v_lshlrev_b32_e32 v161, 4, v188
	v_and_b32_e32 v160, 0x400, v162
	v_and_b32_e32 v162, 0x200, v163
	s_cbranch_scc0 .LBB0_360
	s_lshl_b32 s15, s66, 20
	s_lshl_b32 s20, s66, 16
	s_and_b32 s15, s15, 0xff000000
	s_and_b32 s20, s20, 0xf0000
	s_lshl_b32 s17, s68, 21
	s_or_b32 s15, s20, s15
	v_lshlrev_b32_e32 v163, 14, v191
	s_add_i32 s15, s15, s17
	v_lshlrev_b32_e32 v166, 12, v190
	v_or3_b32 v163, s15, v161, v163
	v_or3_b32 v163, v163, v166, v162
	v_add_u32_e32 v166, v163, v160
	s_mov_b64 s[20:21], 0

.LBB0_465:
	ds_read_b128 v[180:183], v153
	ds_read_b128 v[184:187], v153 offset:1024
	ds_read_b128 v[188:191], v152
	ds_read_b128 v[192:195], v152 offset:1024
	ds_read_b128 v[196:199], v151
	ds_read_b128 v[200:203], v151 offset:1024
	ds_read_b128 v[204:207], v150
	ds_read_b128 v[208:211], v150 offset:1024
	s_waitcnt lgkmcnt(8)
	s_waitcnt vmcnt(10)
	s_barrier
	s_waitcnt lgkmcnt(0)
	s_waitcnt lgkmcnt(0)
	v_mfma_f32_16x16x32_bf16 v[124:127], v[164:167], v[180:183], v[124:127]
	v_mfma_f32_16x16x32_bf16 v[120:123], v[172:175], v[180:183], v[120:123]
	v_mfma_f32_16x16x32_bf16 v[116:119], v[164:167], v[188:191], v[116:119]
	v_mfma_f32_16x16x32_bf16 v[112:115], v[172:175], v[188:191], v[112:115]
	v_mfma_f32_16x16x32_bf16 v[108:111], v[164:167], v[196:199], v[108:111]
	v_mfma_f32_16x16x32_bf16 v[104:107], v[172:175], v[196:199], v[104:107]
	v_mfma_f32_16x16x32_bf16 v[100:103], v[164:167], v[204:207], v[100:103]
	v_mfma_f32_16x16x32_bf16 v[96:99], v[172:175], v[204:207], v[96:99]
	v_mfma_f32_16x16x32_bf16 v[124:127], v[168:171], v[184:187], v[124:127]
	v_mfma_f32_16x16x32_bf16 v[120:123], v[176:179], v[184:187], v[120:123]
	v_mfma_f32_16x16x32_bf16 v[116:119], v[168:171], v[192:195], v[116:119]
	v_mfma_f32_16x16x32_bf16 v[112:115], v[176:179], v[192:195], v[112:115]
	v_mfma_f32_16x16x32_bf16 v[108:111], v[168:171], v[200:203], v[108:111]
	v_mfma_f32_16x16x32_bf16 v[104:107], v[176:179], v[200:203], v[104:107]
	v_mfma_f32_16x16x32_bf16 v[100:103], v[168:171], v[208:211], v[100:103]
	v_mfma_f32_16x16x32_bf16 v[96:99], v[176:179], v[208:211], v[96:99]
	s_barrier
	v_lshl_add_u64 v[230:231], s[50:51], 0, v[130:131]
	s_mov_b64 s[68:69], 0x3880000
	s_add_i32 s36, s98, 0x10000
	v_lshl_add_u64 v[232:233], v[230:231], 0, s[68:69]
	s_mov_b32 m0, s36
	s_mov_b64 s[68:69], 0x3881000
	s_add_i32 s36, s98, 0x12000
	ds_read_b128 v[212:215], v159
	ds_read_b128 v[216:219], v159 offset:1024
	ds_read_b128 v[220:223], v159 offset:2048
	ds_read_b128 v[224:227], v159 offset:3072
	global_load_lds_dwordx4 v[232:233], off
	v_lshl_add_u64 v[232:233], v[230:231], 0, s[68:69]
	s_mov_b32 m0, s36
	s_nop 0
	global_load_lds_dwordx4 v[232:233], off
	s_mov_b64 s[68:69], 0xe000100
	s_mov_b32 s36, s98
	v_lshl_add_u64 v[232:233], v[228:229], 0, s[68:69]
	s_mov_b32 m0, s36
	s_mov_b64 s[68:69], 0xe040100
	s_add_i32 s36, s98, 0x2000
	global_load_lds_dwordx4 v[232:233], off
	v_lshl_add_u64 v[232:233], v[228:229], 0, s[68:69]
	s_mov_b32 m0, s36
	s_nop 0
	global_load_lds_dwordx4 v[232:233], off
	s_waitcnt vmcnt(12)
	s_barrier
	s_waitcnt lgkmcnt(0)
	s_waitcnt lgkmcnt(0)
	v_mfma_f32_16x16x32_bf16 v[92:95], v[212:215], v[180:183], v[92:95]
	v_mfma_f32_16x16x32_bf16 v[88:91], v[220:223], v[180:183], v[88:91]
	v_mfma_f32_16x16x32_bf16 v[84:87], v[212:215], v[188:191], v[84:87]
	v_mfma_f32_16x16x32_bf16 v[80:83], v[220:223], v[188:191], v[80:83]
	v_mfma_f32_16x16x32_bf16 v[76:79], v[212:215], v[196:199], v[76:79]
	v_mfma_f32_16x16x32_bf16 v[72:75], v[220:223], v[196:199], v[72:75]
	v_mfma_f32_16x16x32_bf16 v[68:71], v[212:215], v[204:207], v[68:71]
	v_mfma_f32_16x16x32_bf16 v[64:67], v[220:223], v[204:207], v[64:67]
	v_mfma_f32_16x16x32_bf16 v[92:95], v[216:219], v[184:187], v[92:95]
	v_mfma_f32_16x16x32_bf16 v[88:91], v[224:227], v[184:187], v[88:91]
	v_mfma_f32_16x16x32_bf16 v[84:87], v[216:219], v[192:195], v[84:87]
	v_mfma_f32_16x16x32_bf16 v[80:83], v[224:227], v[192:195], v[80:83]
	v_mfma_f32_16x16x32_bf16 v[76:79], v[216:219], v[200:203], v[76:79]
	v_mfma_f32_16x16x32_bf16 v[72:75], v[224:227], v[200:203], v[72:75]
	v_mfma_f32_16x16x32_bf16 v[68:71], v[216:219], v[208:211], v[68:71]
	v_mfma_f32_16x16x32_bf16 v[64:67], v[224:227], v[208:211], v[64:67]
	s_barrier
	ds_read_b128 v[180:183], v153 offset:16384
	ds_read_b128 v[184:187], v153 offset:17408
	ds_read_b128 v[188:191], v152 offset:16384
	ds_read_b128 v[192:195], v152 offset:17408
	ds_read_b128 v[196:199], v151 offset:16384
	ds_read_b128 v[200:203], v151 offset:17408
	ds_read_b128 v[204:207], v150 offset:16384
	ds_read_b128 v[208:211], v150 offset:17408
	s_mov_b64 s[68:69], 0x3882000
	s_add_i32 s36, s98, 0x14000
	v_lshl_add_u64 v[232:233], v[230:231], 0, s[68:69]
	s_mov_b32 m0, s36
	s_mov_b64 s[68:69], 0x3883000
	s_add_i32 s36, s98, 0x16000
	global_load_lds_dwordx4 v[232:233], off
	v_lshl_add_u64 v[232:233], v[230:231], 0, s[68:69]
	s_mov_b32 m0, s36
	s_nop 0
	global_load_lds_dwordx4 v[232:233], off
	s_waitcnt vmcnt(12)
	s_barrier
	s_waitcnt lgkmcnt(0)
	s_waitcnt lgkmcnt(0)
	v_mfma_f32_16x16x32_bf16 v[60:63], v[164:167], v[180:183], v[60:63]
	v_mfma_f32_16x16x32_bf16 v[56:59], v[172:175], v[180:183], v[56:59]
	v_mfma_f32_16x16x32_bf16 v[52:55], v[164:167], v[188:191], v[52:55]
	v_mfma_f32_16x16x32_bf16 v[48:51], v[172:175], v[188:191], v[48:51]
	v_mfma_f32_16x16x32_bf16 v[44:47], v[164:167], v[196:199], v[44:47]
	v_mfma_f32_16x16x32_bf16 v[40:43], v[172:175], v[196:199], v[40:43]
	v_mfma_f32_16x16x32_bf16 v[36:39], v[164:167], v[204:207], v[36:39]
	v_mfma_f32_16x16x32_bf16 v[32:35], v[172:175], v[204:207], v[32:35]
	v_mfma_f32_16x16x32_bf16 v[60:63], v[168:171], v[184:187], v[60:63]
	v_mfma_f32_16x16x32_bf16 v[56:59], v[176:179], v[184:187], v[56:59]
	v_mfma_f32_16x16x32_bf16 v[52:55], v[168:171], v[192:195], v[52:55]
	v_mfma_f32_16x16x32_bf16 v[48:51], v[176:179], v[192:195], v[48:51]
	v_mfma_f32_16x16x32_bf16 v[44:47], v[168:171], v[200:203], v[44:47]
	v_mfma_f32_16x16x32_bf16 v[40:43], v[176:179], v[200:203], v[40:43]
	v_mfma_f32_16x16x32_bf16 v[36:39], v[168:171], v[208:211], v[36:39]
	v_mfma_f32_16x16x32_bf16 v[32:35], v[176:179], v[208:211], v[32:35]
	s_barrier
	s_add_i32 s36, s98, 0x4000
	v_lshl_add_u64 v[166:167], v[228:229], 0, s[26:27]
	s_mov_b32 m0, s36
	s_add_i32 s36, s98, 0x6000
	global_load_lds_dwordx4 v[166:167], off
	v_lshl_add_u64 v[166:167], v[228:229], 0, s[28:29]
	s_mov_b32 m0, s36
	s_nop 0
	global_load_lds_dwordx4 v[166:167], off
	ds_read_b128 v[164:167], v155
	ds_read_b128 v[168:171], v155 offset:1024
	ds_read_b128 v[172:175], v155 offset:2048
	ds_read_b128 v[176:179], v155 offset:3072
	s_waitcnt vmcnt(12)
	s_barrier
	v_mfma_f32_16x16x32_bf16 v[28:31], v[212:215], v[180:183], v[28:31]
	v_mfma_f32_16x16x32_bf16 v[24:27], v[220:223], v[180:183], v[24:27]
	v_mfma_f32_16x16x32_bf16 v[20:23], v[212:215], v[188:191], v[20:23]
	v_mfma_f32_16x16x32_bf16 v[16:19], v[220:223], v[188:191], v[16:19]
	v_mfma_f32_16x16x32_bf16 v[12:15], v[212:215], v[196:199], v[12:15]
	v_mfma_f32_16x16x32_bf16 v[8:11], v[220:223], v[196:199], v[8:11]
	v_mfma_f32_16x16x32_bf16 v[4:7], v[212:215], v[204:207], v[4:7]
	v_mfma_f32_16x16x32_bf16 v[0:3], v[220:223], v[204:207], v[0:3]
	v_mfma_f32_16x16x32_bf16 v[28:31], v[216:219], v[184:187], v[28:31]
	v_mfma_f32_16x16x32_bf16 v[24:27], v[224:227], v[184:187], v[24:27]
	v_mfma_f32_16x16x32_bf16 v[20:23], v[216:219], v[192:195], v[20:23]
	v_mfma_f32_16x16x32_bf16 v[16:19], v[224:227], v[192:195], v[16:19]
	v_mfma_f32_16x16x32_bf16 v[12:15], v[216:219], v[200:203], v[12:15]
	v_mfma_f32_16x16x32_bf16 v[8:11], v[224:227], v[200:203], v[8:11]
	v_mfma_f32_16x16x32_bf16 v[4:7], v[216:219], v[208:211], v[4:7]
	v_mfma_f32_16x16x32_bf16 v[0:3], v[224:227], v[208:211], v[0:3]
	s_barrier
	ds_read_b128 v[180:183], v153 offset:32768
	ds_read_b128 v[184:187], v153 offset:33792
	ds_read_b128 v[188:191], v152 offset:32768
	ds_read_b128 v[192:195], v152 offset:33792
	ds_read_b128 v[196:199], v151 offset:32768
	ds_read_b128 v[200:203], v151 offset:33792
	ds_read_b128 v[204:207], v150 offset:32768
	ds_read_b128 v[208:211], v150 offset:33792
	s_waitcnt lgkmcnt(8)
	s_waitcnt vmcnt(10)
	s_barrier
	s_waitcnt lgkmcnt(0)
	s_waitcnt lgkmcnt(0)
	v_mfma_f32_16x16x32_bf16 v[124:127], v[164:167], v[180:183], v[124:127]
	v_mfma_f32_16x16x32_bf16 v[120:123], v[172:175], v[180:183], v[120:123]
	v_mfma_f32_16x16x32_bf16 v[116:119], v[164:167], v[188:191], v[116:119]
	v_mfma_f32_16x16x32_bf16 v[112:115], v[172:175], v[188:191], v[112:115]
	v_mfma_f32_16x16x32_bf16 v[108:111], v[164:167], v[196:199], v[108:111]
	v_mfma_f32_16x16x32_bf16 v[104:107], v[172:175], v[196:199], v[104:107]
	v_mfma_f32_16x16x32_bf16 v[100:103], v[164:167], v[204:207], v[100:103]
	v_mfma_f32_16x16x32_bf16 v[96:99], v[172:175], v[204:207], v[96:99]
	v_mfma_f32_16x16x32_bf16 v[124:127], v[168:171], v[184:187], v[124:127]
	v_mfma_f32_16x16x32_bf16 v[120:123], v[176:179], v[184:187], v[120:123]
	v_mfma_f32_16x16x32_bf16 v[116:119], v[168:171], v[192:195], v[116:119]
	v_mfma_f32_16x16x32_bf16 v[112:115], v[176:179], v[192:195], v[112:115]
	v_mfma_f32_16x16x32_bf16 v[108:111], v[168:171], v[200:203], v[108:111]
	v_mfma_f32_16x16x32_bf16 v[104:107], v[176:179], v[200:203], v[104:107]
	v_mfma_f32_16x16x32_bf16 v[100:103], v[168:171], v[208:211], v[100:103]
	v_mfma_f32_16x16x32_bf16 v[96:99], v[176:179], v[208:211], v[96:99]
	s_barrier
	s_add_i32 s36, s98, 0x18000
	v_lshl_add_u64 v[232:233], v[230:231], 0, s[30:31]
	s_mov_b32 m0, s36
	s_add_i32 s36, s98, 0x1a000
	ds_read_b128 v[212:215], v154
	ds_read_b128 v[216:219], v154 offset:1024
	ds_read_b128 v[220:223], v154 offset:2048
	ds_read_b128 v[224:227], v154 offset:3072
	global_load_lds_dwordx4 v[232:233], off
	v_lshl_add_u64 v[232:233], v[230:231], 0, s[34:35]
	s_mov_b32 m0, s36
	s_nop 0
	global_load_lds_dwordx4 v[232:233], off
	s_add_i32 s36, s98, 0x8000
	v_lshl_add_u64 v[232:233], v[228:229], 0, s[44:45]
	s_mov_b32 m0, s36
	s_add_i32 s36, s98, 0xa000
	global_load_lds_dwordx4 v[232:233], off
	v_lshl_add_u64 v[228:229], v[228:229], 0, s[46:47]
	s_mov_b32 m0, s36
	s_nop 0
	global_load_lds_dwordx4 v[228:229], off
	s_waitcnt vmcnt(12)
	s_barrier
	s_waitcnt lgkmcnt(0)
	s_waitcnt lgkmcnt(0)
	v_mfma_f32_16x16x32_bf16 v[92:95], v[212:215], v[180:183], v[92:95]
	v_mfma_f32_16x16x32_bf16 v[88:91], v[220:223], v[180:183], v[88:91]
	v_mfma_f32_16x16x32_bf16 v[84:87], v[212:215], v[188:191], v[84:87]
	v_mfma_f32_16x16x32_bf16 v[80:83], v[220:223], v[188:191], v[80:83]
	v_mfma_f32_16x16x32_bf16 v[76:79], v[212:215], v[196:199], v[76:79]
	v_mfma_f32_16x16x32_bf16 v[72:75], v[220:223], v[196:199], v[72:75]
	v_mfma_f32_16x16x32_bf16 v[68:71], v[212:215], v[204:207], v[68:71]
	v_mfma_f32_16x16x32_bf16 v[64:67], v[220:223], v[204:207], v[64:67]
	v_mfma_f32_16x16x32_bf16 v[92:95], v[216:219], v[184:187], v[92:95]
	v_mfma_f32_16x16x32_bf16 v[88:91], v[224:227], v[184:187], v[88:91]
	v_mfma_f32_16x16x32_bf16 v[84:87], v[216:219], v[192:195], v[84:87]
	v_mfma_f32_16x16x32_bf16 v[80:83], v[224:227], v[192:195], v[80:83]
	v_mfma_f32_16x16x32_bf16 v[76:79], v[216:219], v[200:203], v[76:79]
	v_mfma_f32_16x16x32_bf16 v[72:75], v[224:227], v[200:203], v[72:75]
	v_mfma_f32_16x16x32_bf16 v[68:71], v[216:219], v[208:211], v[68:71]
	v_mfma_f32_16x16x32_bf16 v[64:67], v[224:227], v[208:211], v[64:67]
	s_barrier
	ds_read_b128 v[180:183], v153 offset:49152
	ds_read_b128 v[184:187], v153 offset:50176
	ds_read_b128 v[188:191], v152 offset:49152
	ds_read_b128 v[192:195], v152 offset:50176
	ds_read_b128 v[196:199], v151 offset:49152
	ds_read_b128 v[200:203], v151 offset:50176
	ds_read_b128 v[204:207], v150 offset:49152
	ds_read_b128 v[208:211], v150 offset:50176
	s_add_i32 s36, s98, 0x1c000
	v_lshl_add_u64 v[232:233], v[230:231], 0, s[56:57]
	s_mov_b32 m0, s36
	s_add_i32 s36, s98, 0x1e000
	global_load_lds_dwordx4 v[232:233], off
	v_lshl_add_u64 v[232:233], v[230:231], 0, s[58:59]
	s_mov_b32 m0, s36
	s_nop 0
	global_load_lds_dwordx4 v[232:233], off
	s_waitcnt vmcnt(12)
	s_barrier
	s_waitcnt lgkmcnt(0)
	s_waitcnt lgkmcnt(0)
	v_mfma_f32_16x16x32_bf16 v[60:63], v[164:167], v[180:183], v[60:63]
	v_mfma_f32_16x16x32_bf16 v[56:59], v[172:175], v[180:183], v[56:59]
	v_mfma_f32_16x16x32_bf16 v[52:55], v[164:167], v[188:191], v[52:55]
	v_mfma_f32_16x16x32_bf16 v[48:51], v[172:175], v[188:191], v[48:51]
	v_mfma_f32_16x16x32_bf16 v[44:47], v[164:167], v[196:199], v[44:47]
	v_mfma_f32_16x16x32_bf16 v[40:43], v[172:175], v[196:199], v[40:43]
	v_mfma_f32_16x16x32_bf16 v[36:39], v[164:167], v[204:207], v[36:39]
	v_mfma_f32_16x16x32_bf16 v[32:35], v[172:175], v[204:207], v[32:35]
	v_mfma_f32_16x16x32_bf16 v[60:63], v[168:171], v[184:187], v[60:63]
	v_mfma_f32_16x16x32_bf16 v[56:59], v[176:179], v[184:187], v[56:59]
	v_mfma_f32_16x16x32_bf16 v[52:55], v[168:171], v[192:195], v[52:55]
	v_mfma_f32_16x16x32_bf16 v[48:51], v[176:179], v[192:195], v[48:51]
	v_mfma_f32_16x16x32_bf16 v[44:47], v[168:171], v[200:203], v[44:47]
	v_mfma_f32_16x16x32_bf16 v[40:43], v[176:179], v[200:203], v[40:43]
	v_mfma_f32_16x16x32_bf16 v[36:39], v[168:171], v[208:211], v[36:39]
	v_mfma_f32_16x16x32_bf16 v[32:35], v[176:179], v[208:211], v[32:35]
	s_barrier
	v_lshl_add_u64 v[132:133], v[132:133], 0, s[60:61]
	v_lshl_add_u64 v[228:229], s[50:51], 0, v[132:133]
	s_mov_b64 s[68:69], 0xe080080
	s_add_i32 s36, s98, 0xc000
	v_lshl_add_u64 v[166:167], v[228:229], 0, s[68:69]
	s_mov_b32 m0, s36
	s_mov_b64 s[68:69], 0xe0c0080
	s_add_i32 s36, s98, 0xe000
	global_load_lds_dwordx4 v[166:167], off
	v_lshl_add_u64 v[166:167], v[228:229], 0, s[68:69]
	s_mov_b32 m0, s36
	s_nop 0
	global_load_lds_dwordx4 v[166:167], off
	ds_read_b128 v[164:167], v162
	ds_read_b128 v[168:171], v162 offset:1024
	ds_read_b128 v[172:175], v162 offset:2048
	ds_read_b128 v[176:179], v162 offset:3072
	s_waitcnt vmcnt(12)
	s_barrier
	v_mfma_f32_16x16x32_bf16 v[28:31], v[212:215], v[180:183], v[28:31]
	v_mfma_f32_16x16x32_bf16 v[24:27], v[220:223], v[180:183], v[24:27]
	v_mfma_f32_16x16x32_bf16 v[20:23], v[212:215], v[188:191], v[20:23]
	v_mfma_f32_16x16x32_bf16 v[16:19], v[220:223], v[188:191], v[16:19]
	v_mfma_f32_16x16x32_bf16 v[12:15], v[212:215], v[196:199], v[12:15]
	v_mfma_f32_16x16x32_bf16 v[8:11], v[220:223], v[196:199], v[8:11]
	v_mfma_f32_16x16x32_bf16 v[4:7], v[212:215], v[204:207], v[4:7]
	v_mfma_f32_16x16x32_bf16 v[0:3], v[220:223], v[204:207], v[0:3]
	v_mfma_f32_16x16x32_bf16 v[28:31], v[216:219], v[184:187], v[28:31]
	v_mfma_f32_16x16x32_bf16 v[24:27], v[224:227], v[184:187], v[24:27]
	v_mfma_f32_16x16x32_bf16 v[20:23], v[216:219], v[192:195], v[20:23]
	v_mfma_f32_16x16x32_bf16 v[16:19], v[224:227], v[192:195], v[16:19]
	v_mfma_f32_16x16x32_bf16 v[12:15], v[216:219], v[200:203], v[12:15]
	v_mfma_f32_16x16x32_bf16 v[8:11], v[224:227], v[200:203], v[8:11]
	v_mfma_f32_16x16x32_bf16 v[4:7], v[216:219], v[208:211], v[4:7]
	v_mfma_f32_16x16x32_bf16 v[0:3], v[224:227], v[208:211], v[0:3]
	s_add_i32 s24, s24, 2
	v_lshl_add_u64 v[130:131], v[130:131], 0, s[10:11]
	s_cmp_lt_u32 s24, 28
	s_barrier
	s_cbranch_scc1 .LBB0_465
	s_lshl_b32 s24, s86, 5
	s_lshl_b32 s36, s86, 8
	s_and_b32 s24, s24, 0x1800
	s_and_b32 s36, s36, 0x700
	s_or_b32 s24, s36, s24
	v_lshlrev_b32_e32 v128, 3, v156
	v_lshlrev_b32_e32 v130, 5, v156
	v_and_b32_e32 v128, 0xffff0, v128
	v_and_b32_e32 v130, 32, v130
	s_lshl_b32 s36, s24, 12
	v_add_u32_e32 v130, v130, v158
	v_add_lshl_u32 v128, v157, v128, 12
	s_add_u32 s68, s70, s36
	v_lshl_add_u32 v128, v130, 1, v128
	s_addc_u32 s69, s71, 0
	v_lshl_add_u64 v[156:157], s[68:69], 0, v[128:129]
	v_readfirstlane_b32 s36, v161
	ds_read_b128 v[130:133], v162
	ds_read_b128 v[164:167], v162 offset:1024
	ds_read_b128 v[168:171], v162 offset:2048
	ds_read_b128 v[172:175], v162 offset:3072
	ds_read_b128 v[176:179], v153
	ds_read_b128 v[180:183], v153 offset:1024
	ds_read_b128 v[184:187], v152
	ds_read_b128 v[188:191], v152 offset:1024
	ds_read_b128 v[192:195], v151
	ds_read_b128 v[196:199], v151 offset:1024
	ds_read_b128 v[200:203], v150
	ds_read_b128 v[204:207], v150 offset:1024
	v_lshl_add_u64 v[162:163], v[156:157], 0, s[62:63]
	s_mov_b32 m0, s36
	v_readfirstlane_b32 s36, v160
	v_lshl_add_u64 v[156:157], v[156:157], 0, s[64:65]
	s_mov_b32 m0, s36
	s_nop 0
	s_waitcnt vmcnt(8)
	s_barrier
	s_waitcnt lgkmcnt(0)
	s_setprio 1
	s_waitcnt lgkmcnt(0)
	v_mfma_f32_16x16x32_bf16 v[124:127], v[130:133], v[176:179], v[124:127]
	v_mfma_f32_16x16x32_bf16 v[120:123], v[168:171], v[176:179], v[120:123]
	v_mfma_f32_16x16x32_bf16 v[116:119], v[130:133], v[184:187], v[116:119]
	v_mfma_f32_16x16x32_bf16 v[112:115], v[168:171], v[184:187], v[112:115]
	v_mfma_f32_16x16x32_bf16 v[108:111], v[130:133], v[192:195], v[108:111]
	v_mfma_f32_16x16x32_bf16 v[104:107], v[168:171], v[192:195], v[104:107]
	v_mfma_f32_16x16x32_bf16 v[100:103], v[130:133], v[200:203], v[100:103]
	v_mfma_f32_16x16x32_bf16 v[96:99], v[168:171], v[200:203], v[96:99]
	v_mfma_f32_16x16x32_bf16 v[124:127], v[164:167], v[180:183], v[124:127]
	v_mfma_f32_16x16x32_bf16 v[120:123], v[172:175], v[180:183], v[120:123]
	v_mfma_f32_16x16x32_bf16 v[116:119], v[164:167], v[188:191], v[116:119]
	v_mfma_f32_16x16x32_bf16 v[112:115], v[172:175], v[188:191], v[112:115]
	v_mfma_f32_16x16x32_bf16 v[108:111], v[164:167], v[196:199], v[108:111]
	v_mfma_f32_16x16x32_bf16 v[104:107], v[172:175], v[196:199], v[104:107]
	v_mfma_f32_16x16x32_bf16 v[100:103], v[164:167], v[204:207], v[100:103]
	v_mfma_f32_16x16x32_bf16 v[96:99], v[172:175], v[204:207], v[96:99]
	s_setprio 0
	s_barrier
	ds_read_b128 v[160:163], v159
	ds_read_b128 v[208:211], v159 offset:1024
	ds_read_b128 v[212:215], v159 offset:2048
	ds_read_b128 v[156:159], v159 offset:3072
	s_barrier
	s_waitcnt lgkmcnt(0)
	s_setprio 1
	s_waitcnt lgkmcnt(0)
	v_mfma_f32_16x16x32_bf16 v[92:95], v[160:163], v[176:179], v[92:95]
	v_mfma_f32_16x16x32_bf16 v[88:91], v[212:215], v[176:179], v[88:91]
	v_mfma_f32_16x16x32_bf16 v[84:87], v[160:163], v[184:187], v[84:87]
	v_mfma_f32_16x16x32_bf16 v[80:83], v[212:215], v[184:187], v[80:83]
	v_mfma_f32_16x16x32_bf16 v[76:79], v[160:163], v[192:195], v[76:79]
	v_mfma_f32_16x16x32_bf16 v[72:75], v[212:215], v[192:195], v[72:75]
	v_mfma_f32_16x16x32_bf16 v[68:71], v[160:163], v[200:203], v[68:71]
	v_mfma_f32_16x16x32_bf16 v[64:67], v[212:215], v[200:203], v[64:67]
	v_mfma_f32_16x16x32_bf16 v[176:179], v[208:211], v[180:183], v[92:95]
	v_mfma_f32_16x16x32_bf16 v[180:183], v[156:159], v[180:183], v[88:91]
	v_mfma_f32_16x16x32_bf16 v[184:187], v[208:211], v[188:191], v[84:87]
	v_mfma_f32_16x16x32_bf16 v[188:191], v[156:159], v[188:191], v[80:83]
	v_mfma_f32_16x16x32_bf16 v[192:195], v[208:211], v[196:199], v[76:79]
	v_mfma_f32_16x16x32_bf16 v[196:199], v[156:159], v[196:199], v[72:75]
	v_mfma_f32_16x16x32_bf16 v[200:203], v[208:211], v[204:207], v[68:71]
	v_mfma_f32_16x16x32_bf16 v[204:207], v[156:159], v[204:207], v[64:67]
	s_setprio 0
	s_barrier
	s_nop 0
	ds_read_b128 v[64:67], v153 offset:16384
	ds_read_b128 v[68:71], v153 offset:17408
	ds_read_b128 v[72:75], v152 offset:16384
	ds_read_b128 v[76:79], v152 offset:17408
	ds_read_b128 v[80:83], v151 offset:16384
	ds_read_b128 v[84:87], v151 offset:17408
	ds_read_b128 v[88:91], v150 offset:16384
	ds_read_b128 v[92:95], v150 offset:17408
	s_waitcnt vmcnt(4)
	s_barrier
	s_waitcnt lgkmcnt(0)
	s_setprio 1
	s_waitcnt lgkmcnt(0)
	v_mfma_f32_16x16x32_bf16 v[60:63], v[130:133], v[64:67], v[60:63]
	v_mfma_f32_16x16x32_bf16 v[56:59], v[168:171], v[64:67], v[56:59]
	v_mfma_f32_16x16x32_bf16 v[52:55], v[130:133], v[72:75], v[52:55]
	v_mfma_f32_16x16x32_bf16 v[48:51], v[168:171], v[72:75], v[48:51]
	v_mfma_f32_16x16x32_bf16 v[216:219], v[130:133], v[80:83], v[44:47]
	v_mfma_f32_16x16x32_bf16 v[220:223], v[168:171], v[80:83], v[40:43]
	v_mfma_f32_16x16x32_bf16 v[130:133], v[130:133], v[88:91], v[36:39]
	v_mfma_f32_16x16x32_bf16 v[168:171], v[168:171], v[88:91], v[32:35]
	v_mfma_f32_16x16x32_bf16 v[32:35], v[164:167], v[68:71], v[60:63]
	v_mfma_f32_16x16x32_bf16 v[36:39], v[172:175], v[68:71], v[56:59]
	v_mfma_f32_16x16x32_bf16 v[40:43], v[164:167], v[76:79], v[52:55]
	v_mfma_f32_16x16x32_bf16 v[44:47], v[172:175], v[76:79], v[48:51]
	v_mfma_f32_16x16x32_bf16 v[48:51], v[164:167], v[84:87], v[216:219]
	v_mfma_f32_16x16x32_bf16 v[52:55], v[172:175], v[84:87], v[220:223]
	v_mfma_f32_16x16x32_bf16 v[56:59], v[164:167], v[92:95], v[130:133]
	v_mfma_f32_16x16x32_bf16 v[60:63], v[172:175], v[92:95], v[168:171]
	s_setprio 0
	s_setprio 1
	v_mfma_f32_16x16x32_bf16 v[28:31], v[160:163], v[64:67], v[28:31]
	v_mfma_f32_16x16x32_bf16 v[24:27], v[212:215], v[64:67], v[24:27]
	v_mfma_f32_16x16x32_bf16 v[20:23], v[160:163], v[72:75], v[20:23]
	v_mfma_f32_16x16x32_bf16 v[64:67], v[212:215], v[72:75], v[16:19]
	v_mfma_f32_16x16x32_bf16 v[72:75], v[160:163], v[80:83], v[12:15]
	v_mfma_f32_16x16x32_bf16 v[8:11], v[212:215], v[80:83], v[8:11]
	v_mfma_f32_16x16x32_bf16 v[80:83], v[160:163], v[88:91], v[4:7]
	v_mfma_f32_16x16x32_bf16 v[0:3], v[212:215], v[88:91], v[0:3]
	v_mfma_f32_16x16x32_bf16 v[4:7], v[208:211], v[68:71], v[28:31]
	v_mfma_f32_16x16x32_bf16 v[12:15], v[156:159], v[68:71], v[24:27]
	v_mfma_f32_16x16x32_bf16 v[16:19], v[208:211], v[76:79], v[20:23]
	v_mfma_f32_16x16x32_bf16 v[20:23], v[156:159], v[76:79], v[64:67]
	v_mfma_f32_16x16x32_bf16 v[24:27], v[208:211], v[84:87], v[72:75]
	v_mfma_f32_16x16x32_bf16 v[28:31], v[156:159], v[84:87], v[8:11]
	v_mfma_f32_16x16x32_bf16 v[64:67], v[208:211], v[92:95], v[80:83]
	v_mfma_f32_16x16x32_bf16 v[68:71], v[156:159], v[92:95], v[0:3]
	s_setprio 0
	s_barrier
	ds_read_b128 v[8:11], v155
	ds_read_b128 v[0:3], v155 offset:1024
	ds_read_b128 v[76:79], v155 offset:2048
	ds_read_b128 v[72:75], v155 offset:3072
	ds_read_b128 v[130:133], v153 offset:32768
	ds_read_b128 v[156:159], v153 offset:33792
	ds_read_b128 v[160:163], v152 offset:32768
	ds_read_b128 v[164:167], v152 offset:33792
	ds_read_b128 v[168:171], v151 offset:32768
	ds_read_b128 v[172:175], v151 offset:33792
	ds_read_b128 v[208:211], v150 offset:32768
	ds_read_b128 v[212:215], v150 offset:33792
	s_waitcnt vmcnt(2)
	s_barrier
	s_waitcnt lgkmcnt(0)
	s_setprio 1
	s_waitcnt lgkmcnt(0)
	v_mfma_f32_16x16x32_bf16 v[80:83], v[8:11], v[130:133], v[124:127]
	v_mfma_f32_16x16x32_bf16 v[84:87], v[76:79], v[130:133], v[120:123]
	v_mfma_f32_16x16x32_bf16 v[88:91], v[8:11], v[160:163], v[116:119]
	v_mfma_f32_16x16x32_bf16 v[92:95], v[76:79], v[160:163], v[112:115]
	v_mfma_f32_16x16x32_bf16 v[108:111], v[8:11], v[168:171], v[108:111]
	v_mfma_f32_16x16x32_bf16 v[104:107], v[76:79], v[168:171], v[104:107]
	v_mfma_f32_16x16x32_bf16 v[100:103], v[8:11], v[208:211], v[100:103]
	v_mfma_f32_16x16x32_bf16 v[96:99], v[76:79], v[208:211], v[96:99]
	v_mfma_f32_16x16x32_bf16 v[112:115], v[0:3], v[156:159], v[80:83]
	v_mfma_f32_16x16x32_bf16 v[116:119], v[72:75], v[156:159], v[84:87]
	v_mfma_f32_16x16x32_bf16 v[120:123], v[0:3], v[164:167], v[88:91]
	v_mfma_f32_16x16x32_bf16 v[124:127], v[72:75], v[164:167], v[92:95]
	v_mfma_f32_16x16x32_bf16 v[108:111], v[0:3], v[172:175], v[108:111]
	v_mfma_f32_16x16x32_bf16 v[104:107], v[72:75], v[172:175], v[104:107]
	v_mfma_f32_16x16x32_bf16 v[100:103], v[0:3], v[212:215], v[100:103]
	v_mfma_f32_16x16x32_bf16 v[96:99], v[72:75], v[212:215], v[96:99]
	s_setprio 0
	s_barrier
	ds_read_b128 v[88:91], v154
	ds_read_b128 v[80:83], v154 offset:1024
	ds_read_b128 v[92:95], v154 offset:2048
	ds_read_b128 v[84:87], v154 offset:3072
	s_waitcnt vmcnt(0)
	s_barrier
	s_waitcnt lgkmcnt(0)
	s_setprio 1
	s_waitcnt lgkmcnt(0)
	v_mfma_f32_16x16x32_bf16 v[176:179], v[88:91], v[130:133], v[176:179]
	v_mfma_f32_16x16x32_bf16 v[130:133], v[92:95], v[130:133], v[180:183]
	v_mfma_f32_16x16x32_bf16 v[180:183], v[88:91], v[160:163], v[184:187]
	v_mfma_f32_16x16x32_bf16 v[160:163], v[92:95], v[160:163], v[188:191]
	v_mfma_f32_16x16x32_bf16 v[184:187], v[88:91], v[168:171], v[192:195]
	v_mfma_f32_16x16x32_bf16 v[168:171], v[92:95], v[168:171], v[196:199]
	v_mfma_f32_16x16x32_bf16 v[188:191], v[88:91], v[208:211], v[200:203]
	v_mfma_f32_16x16x32_bf16 v[192:195], v[92:95], v[208:211], v[204:207]
	v_mfma_f32_16x16x32_bf16 v[176:179], v[80:83], v[156:159], v[176:179]
	v_mfma_f32_16x16x32_bf16 v[130:133], v[84:87], v[156:159], v[130:133]
	v_mfma_f32_16x16x32_bf16 v[154:157], v[80:83], v[164:167], v[180:183]
	v_mfma_f32_16x16x32_bf16 v[158:161], v[84:87], v[164:167], v[160:163]
	v_mfma_f32_16x16x32_bf16 v[162:165], v[80:83], v[172:175], v[184:187]
	v_mfma_f32_16x16x32_bf16 v[166:169], v[84:87], v[172:175], v[168:171]
	v_mfma_f32_16x16x32_bf16 v[170:173], v[80:83], v[212:215], v[188:191]
	v_mfma_f32_16x16x32_bf16 v[180:183], v[84:87], v[212:215], v[192:195]
	s_setprio 0
	s_barrier
	v_mbcnt_lo_u32_b32 v128, -1, 0
	v_mbcnt_hi_u32_b32 v128, -1, v128
	v_cvt_pk_bf16_f32 v112, v112, v113
	v_cvt_pk_bf16_f32 v113, v114, v115
	v_cvt_pk_bf16_f32 v114, v116, v117
	v_cvt_pk_bf16_f32 v115, v118, v119
	s_lshl_b32 s68, s66, 9
	v_add_u32_e32 v174, s74, v128
	v_ashrrev_i32_e32 v175, 6, v174
	v_and_b32_e32 v184, 15, v128
	v_and_b32_e32 v185, 48, v128
	v_mul_lo_u32 v186, v175, s79
	v_bfe_u32 v187, v128, 3, 3
	v_lshlrev_b32_e32 v128, 4, v128
	v_add_u32_e32 v186, 0x20000, v186
	v_lshrrev_b32_e32 v174, 2, v174
	v_and_b32_e32 v128, 0x70, v128
	v_mul_u32_u24_e32 v184, 0x90, v184
	v_and_b32_e32 v174, 64, v174
	v_add3_u32 v184, v186, v184, v185
	v_or_b32_e32 v185, v186, v128
	v_or3_b32 v174, s24, v174, v187
	v_mad_u32_u24 v185, v187, s80, v185
	ds_write_b128 v184, v[112:115]
	v_cvt_pk_bf16_f32 v112, v176, v177
	v_cvt_pk_bf16_f32 v113, v178, v179
	v_cvt_pk_bf16_f32 v114, v130, v131
	v_cvt_pk_bf16_f32 v115, v132, v133
	ds_write_b128 v184, v[112:115] offset:64
	v_lshlrev_b32_e32 v175, 7, v175
	ds_read_b128 v[112:115], v185
	v_lshlrev_b32_e32 v116, 12, v174
	v_and_or_b32 v116, v175, s81, v116
	v_or3_b32 v128, v116, s68, v128
	ds_read_b128 v[116:119], v185 offset:1152
	v_lshl_add_u64 v[130:131], s[0:1], 0, v[128:129]
	s_mov_b32 s36, 0x8000
	s_waitcnt lgkmcnt(0)
	global_store_dwordx4 v128, v[112:115], s[0:1]
	v_cvt_pk_bf16_f32 v108, v108, v109
	v_cvt_pk_bf16_f32 v109, v110, v111
	v_cvt_pk_bf16_f32 v110, v104, v105
	v_cvt_pk_bf16_f32 v111, v106, v107
	v_cvt_pk_bf16_f32 v104, v162, v163
	s_nop 1
	v_add_co_u32_e32 v112, vcc, s36, v130
	v_cvt_pk_bf16_f32 v114, v124, v125
	v_cvt_pk_bf16_f32 v115, v126, v127
	v_cvt_pk_bf16_f32 v105, v164, v165
	v_cvt_pk_bf16_f32 v106, v166, v167
	s_nop 1
	v_addc_co_u32_e32 v113, vcc, 0, v131, vcc
	global_store_dwordx4 v[112:113], v[116:119], off
	v_cvt_pk_bf16_f32 v112, v120, v121
	v_cvt_pk_bf16_f32 v113, v122, v123
	ds_write_b128 v184, v[112:115]
	v_cvt_pk_bf16_f32 v112, v154, v155
	v_cvt_pk_bf16_f32 v113, v156, v157
	v_cvt_pk_bf16_f32 v114, v158, v159
	v_cvt_pk_bf16_f32 v115, v160, v161
	ds_write_b128 v184, v[112:115] offset:64
	ds_read_b128 v[112:115], v185
	ds_read_b128 v[116:119], v185 offset:1152
	v_add_co_u32_e32 v120, vcc, s76, v130
	ds_write_b128 v184, v[108:111]
	v_cvt_pk_bf16_f32 v107, v168, v169
	ds_write_b128 v184, v[104:107] offset:64
	v_addc_co_u32_e32 v121, vcc, 0, v131, vcc
	ds_read_b128 v[104:107], v185
	ds_read_b128 v[108:111], v185 offset:1152
	s_waitcnt lgkmcnt(0)
	global_store_dwordx4 v[120:121], v[112:115], off
	v_cvt_pk_bf16_f32 v100, v100, v101
	v_cvt_pk_bf16_f32 v101, v102, v103
	v_cvt_pk_bf16_f32 v102, v96, v97
	v_cvt_pk_bf16_f32 v103, v98, v99
	ds_write_b128 v184, v[100:103]
	s_nop 0
	v_add_co_u32_e32 v112, vcc, s77, v130
	v_cvt_pk_bf16_f32 v96, v170, v171
	v_cvt_pk_bf16_f32 v97, v172, v173
	v_cvt_pk_bf16_f32 v98, v180, v181
	v_cvt_pk_bf16_f32 v99, v182, v183
	s_nop 1
	v_addc_co_u32_e32 v113, vcc, 0, v131, vcc
	global_store_dwordx4 v[112:113], v[116:119], off
	v_add_co_u32_e32 v112, vcc, s78, v130
	ds_write_b128 v184, v[96:99] offset:64
	s_nop 0
	v_addc_co_u32_e32 v113, vcc, 0, v131, vcc
	ds_read_b128 v[96:99], v185
	ds_read_b128 v[100:103], v185 offset:1152
	global_store_dwordx4 v[112:113], v[104:107], off
	s_nop 1
	v_add_co_u32_e32 v104, vcc, s82, v130
	s_nop 1
	v_addc_co_u32_e32 v105, vcc, 0, v131, vcc
	global_store_dwordx4 v[104:105], v[108:111], off
	v_add_co_u32_e32 v104, vcc, s83, v130
	s_nop 1
	v_addc_co_u32_e32 v105, vcc, 0, v131, vcc
	s_waitcnt lgkmcnt(0)
	global_store_dwordx4 v[104:105], v[96:99], off
	s_nop 1
	v_add_co_u32_e32 v96, vcc, s91, v130
	s_nop 1
	v_addc_co_u32_e32 v97, vcc, 0, v131, vcc
	global_store_dwordx4 v[96:97], v[100:103], off
	ds_read_b128 v[96:99], v153 offset:49152
	ds_read_b128 v[100:103], v153 offset:50176
	ds_read_b128 v[104:107], v152 offset:49152
	ds_read_b128 v[108:111], v152 offset:50176
	ds_read_b128 v[112:115], v151 offset:49152
	ds_read_b128 v[116:119], v151 offset:50176
	ds_read_b128 v[120:123], v150 offset:49152
	ds_read_b128 v[124:127], v150 offset:50176
	s_barrier
	s_waitcnt lgkmcnt(0)
	s_setprio 1
	s_waitcnt lgkmcnt(0)
	v_mfma_f32_16x16x32_bf16 v[32:35], v[8:11], v[96:99], v[32:35]
	v_mfma_f32_16x16x32_bf16 v[36:39], v[76:79], v[96:99], v[36:39]
	v_mfma_f32_16x16x32_bf16 v[40:43], v[8:11], v[104:107], v[40:43]
	v_mfma_f32_16x16x32_bf16 v[130:133], v[76:79], v[104:107], v[44:47]
	v_mfma_f32_16x16x32_bf16 v[150:153], v[8:11], v[112:115], v[48:51]
	v_mfma_f32_16x16x32_bf16 v[52:55], v[76:79], v[112:115], v[52:55]
	v_mfma_f32_16x16x32_bf16 v[8:11], v[8:11], v[120:123], v[56:59]
	v_mfma_f32_16x16x32_bf16 v[60:63], v[76:79], v[120:123], v[60:63]
	v_mfma_f32_16x16x32_bf16 v[56:59], v[0:3], v[100:103], v[32:35]
	v_mfma_f32_16x16x32_bf16 v[48:51], v[72:75], v[100:103], v[36:39]
	v_mfma_f32_16x16x32_bf16 v[44:47], v[0:3], v[108:111], v[40:43]
	v_mfma_f32_16x16x32_bf16 v[40:43], v[72:75], v[108:111], v[130:133]
	v_mfma_f32_16x16x32_bf16 v[36:39], v[0:3], v[116:119], v[150:153]
	v_mfma_f32_16x16x32_bf16 v[32:35], v[72:75], v[116:119], v[52:55]
	v_mfma_f32_16x16x32_bf16 v[8:11], v[0:3], v[124:127], v[8:11]
	v_mfma_f32_16x16x32_bf16 v[0:3], v[72:75], v[124:127], v[60:63]
	s_setprio 0
	s_setprio 1
	v_mfma_f32_16x16x32_bf16 v[4:7], v[88:91], v[96:99], v[4:7]
	v_mfma_f32_16x16x32_bf16 v[12:15], v[92:95], v[96:99], v[12:15]
	v_mfma_f32_16x16x32_bf16 v[16:19], v[88:91], v[104:107], v[16:19]
	v_mfma_f32_16x16x32_bf16 v[20:23], v[92:95], v[104:107], v[20:23]
	v_mfma_f32_16x16x32_bf16 v[72:75], v[88:91], v[112:115], v[24:27]
	v_mfma_f32_16x16x32_bf16 v[76:79], v[92:95], v[112:115], v[28:31]
	v_mfma_f32_16x16x32_bf16 v[64:67], v[88:91], v[120:123], v[64:67]
	v_mfma_f32_16x16x32_bf16 v[68:71], v[92:95], v[120:123], v[68:71]
	v_mfma_f32_16x16x32_bf16 v[60:63], v[80:83], v[100:103], v[4:7]
	v_mfma_f32_16x16x32_bf16 v[52:55], v[84:87], v[100:103], v[12:15]
	v_mfma_f32_16x16x32_bf16 v[28:31], v[80:83], v[108:111], v[16:19]
	v_mfma_f32_16x16x32_bf16 v[24:27], v[84:87], v[108:111], v[20:23]
	v_mfma_f32_16x16x32_bf16 v[20:23], v[80:83], v[116:119], v[72:75]
	v_mfma_f32_16x16x32_bf16 v[16:19], v[84:87], v[116:119], v[76:79]
	v_mfma_f32_16x16x32_bf16 v[12:15], v[80:83], v[124:127], v[64:67]
	v_mfma_f32_16x16x32_bf16 v[4:7], v[84:87], v[124:127], v[68:71]
	s_setprio 0
	v_cmp_gt_u32_e32 vcc, s92, v136
	s_barrier
	s_and_saveexec_b64 s[66:67], vcc
	s_cbranch_execz .LBB0_468
	s_barrier

.LBB0_521:
	ds_read_b128 v[156:159], v193
	ds_read_b128 v[160:163], v193 offset:1024
	ds_read_b128 v[194:197], v192
	ds_read_b128 v[198:201], v192 offset:1024
	ds_read_b128 v[202:205], v191
	ds_read_b128 v[206:209], v191 offset:1024
	ds_read_b128 v[210:213], v190
	ds_read_b128 v[214:217], v190 offset:1024
	s_waitcnt lgkmcnt(8)
	s_waitcnt vmcnt(10)
	s_barrier
	s_waitcnt lgkmcnt(0)
	s_waitcnt lgkmcnt(0)
	v_mfma_f32_16x16x32_bf16 v[124:127], v[140:143], v[156:159], v[124:127]
	v_mfma_f32_16x16x32_bf16 v[120:123], v[148:151], v[156:159], v[120:123]
	v_mfma_f32_16x16x32_bf16 v[116:119], v[140:143], v[194:197], v[116:119]
	v_mfma_f32_16x16x32_bf16 v[112:115], v[148:151], v[194:197], v[112:115]
	v_mfma_f32_16x16x32_bf16 v[108:111], v[140:143], v[202:205], v[108:111]
	v_mfma_f32_16x16x32_bf16 v[104:107], v[148:151], v[202:205], v[104:107]
	v_mfma_f32_16x16x32_bf16 v[100:103], v[140:143], v[210:213], v[100:103]
	v_mfma_f32_16x16x32_bf16 v[96:99], v[148:151], v[210:213], v[96:99]
	v_mfma_f32_16x16x32_bf16 v[124:127], v[144:147], v[160:163], v[124:127]
	v_mfma_f32_16x16x32_bf16 v[120:123], v[152:155], v[160:163], v[120:123]
	v_mfma_f32_16x16x32_bf16 v[116:119], v[144:147], v[198:201], v[116:119]
	v_mfma_f32_16x16x32_bf16 v[112:115], v[152:155], v[198:201], v[112:115]
	v_mfma_f32_16x16x32_bf16 v[108:111], v[144:147], v[206:209], v[108:111]
	v_mfma_f32_16x16x32_bf16 v[104:107], v[152:155], v[206:209], v[104:107]
	v_mfma_f32_16x16x32_bf16 v[100:103], v[144:147], v[214:217], v[100:103]
	v_mfma_f32_16x16x32_bf16 v[96:99], v[152:155], v[214:217], v[96:99]
	s_barrier
	s_add_i32 s36, s98, 0x10000
	v_lshl_add_u64 v[234:235], s[58:59], 0, v[164:165]
	s_mov_b32 m0, s36
	s_add_i32 s36, s98, 0x12000
	ds_read_b128 v[218:221], v135
	ds_read_b128 v[222:225], v135 offset:1024
	ds_read_b128 v[226:229], v135 offset:2048
	ds_read_b128 v[230:233], v135 offset:3072
	global_load_lds_dwordx4 v[234:235], off
	v_lshl_add_u64 v[236:237], v[234:235], 0, s[2:3]
	s_mov_b32 m0, s36
	s_nop 0
	global_load_lds_dwordx4 v[236:237], off
	s_mov_b32 s36, s98
	v_lshl_add_u64 v[236:237], v[128:129], 0, s[22:23]
	s_mov_b32 m0, s36
	s_add_i32 s36, s98, 0x2000
	global_load_lds_dwordx4 v[236:237], off
	v_lshl_add_u64 v[236:237], v[128:129], 0, s[24:25]
	s_mov_b32 m0, s36
	s_nop 0
	global_load_lds_dwordx4 v[236:237], off
	s_waitcnt vmcnt(12)
	s_barrier
	s_waitcnt lgkmcnt(0)
	s_waitcnt lgkmcnt(0)
	v_mfma_f32_16x16x32_bf16 v[92:95], v[218:221], v[156:159], v[92:95]
	v_mfma_f32_16x16x32_bf16 v[88:91], v[226:229], v[156:159], v[88:91]
	v_mfma_f32_16x16x32_bf16 v[84:87], v[218:221], v[194:197], v[84:87]
	v_mfma_f32_16x16x32_bf16 v[80:83], v[226:229], v[194:197], v[80:83]
	v_mfma_f32_16x16x32_bf16 v[76:79], v[218:221], v[202:205], v[76:79]
	v_mfma_f32_16x16x32_bf16 v[72:75], v[226:229], v[202:205], v[72:75]
	v_mfma_f32_16x16x32_bf16 v[68:71], v[218:221], v[210:213], v[68:71]
	v_mfma_f32_16x16x32_bf16 v[64:67], v[226:229], v[210:213], v[64:67]
	v_mfma_f32_16x16x32_bf16 v[92:95], v[222:225], v[160:163], v[92:95]
	v_mfma_f32_16x16x32_bf16 v[88:91], v[230:233], v[160:163], v[88:91]
	v_mfma_f32_16x16x32_bf16 v[84:87], v[222:225], v[198:201], v[84:87]
	v_mfma_f32_16x16x32_bf16 v[80:83], v[230:233], v[198:201], v[80:83]
	v_mfma_f32_16x16x32_bf16 v[76:79], v[222:225], v[206:209], v[76:79]
	v_mfma_f32_16x16x32_bf16 v[72:75], v[230:233], v[206:209], v[72:75]
	v_mfma_f32_16x16x32_bf16 v[68:71], v[222:225], v[214:217], v[68:71]
	v_mfma_f32_16x16x32_bf16 v[64:67], v[230:233], v[214:217], v[64:67]
	s_barrier
	ds_read_b128 v[156:159], v193 offset:16384
	ds_read_b128 v[160:163], v193 offset:17408
	ds_read_b128 v[194:197], v192 offset:16384
	ds_read_b128 v[198:201], v192 offset:17408
	ds_read_b128 v[202:205], v191 offset:16384
	ds_read_b128 v[206:209], v191 offset:17408
	ds_read_b128 v[210:213], v190 offset:16384
	ds_read_b128 v[214:217], v190 offset:17408
	s_add_i32 s36, s98, 0x14000
	v_lshl_add_u64 v[236:237], v[234:235], 0, s[6:7]
	s_mov_b32 m0, s36
	s_add_i32 s36, s98, 0x16000
	global_load_lds_dwordx4 v[236:237], off
	v_lshl_add_u64 v[236:237], v[234:235], 0, s[8:9]
	s_mov_b32 m0, s36
	s_nop 0
	global_load_lds_dwordx4 v[236:237], off
	s_waitcnt vmcnt(12)
	s_barrier
	s_waitcnt lgkmcnt(0)
	s_waitcnt lgkmcnt(0)
	v_mfma_f32_16x16x32_bf16 v[60:63], v[140:143], v[156:159], v[60:63]
	v_mfma_f32_16x16x32_bf16 v[56:59], v[148:151], v[156:159], v[56:59]
	v_mfma_f32_16x16x32_bf16 v[52:55], v[140:143], v[194:197], v[52:55]
	v_mfma_f32_16x16x32_bf16 v[48:51], v[148:151], v[194:197], v[48:51]
	v_mfma_f32_16x16x32_bf16 v[44:47], v[140:143], v[202:205], v[44:47]
	v_mfma_f32_16x16x32_bf16 v[40:43], v[148:151], v[202:205], v[40:43]
	v_mfma_f32_16x16x32_bf16 v[36:39], v[140:143], v[210:213], v[36:39]
	v_mfma_f32_16x16x32_bf16 v[32:35], v[148:151], v[210:213], v[32:35]
	v_mfma_f32_16x16x32_bf16 v[60:63], v[144:147], v[160:163], v[60:63]
	v_mfma_f32_16x16x32_bf16 v[56:59], v[152:155], v[160:163], v[56:59]
	v_mfma_f32_16x16x32_bf16 v[52:55], v[144:147], v[198:201], v[52:55]
	v_mfma_f32_16x16x32_bf16 v[48:51], v[152:155], v[198:201], v[48:51]
	v_mfma_f32_16x16x32_bf16 v[44:47], v[144:147], v[206:209], v[44:47]
	v_mfma_f32_16x16x32_bf16 v[40:43], v[152:155], v[206:209], v[40:43]
	v_mfma_f32_16x16x32_bf16 v[36:39], v[144:147], v[214:217], v[36:39]
	v_mfma_f32_16x16x32_bf16 v[32:35], v[152:155], v[214:217], v[32:35]
	s_barrier
	s_add_i32 s36, s98, 0x4000
	v_lshl_add_u64 v[142:143], v[128:129], 0, s[26:27]
	s_mov_b32 m0, s36
	s_add_i32 s36, s98, 0x6000
	global_load_lds_dwordx4 v[142:143], off
	s_mov_b32 m0, s36
	s_nop 0
	global_load_lds_dwordx4 v[128:129], off
	ds_read_b128 v[140:143], v130
	ds_read_b128 v[144:147], v130 offset:1024
	ds_read_b128 v[148:151], v130 offset:2048
	ds_read_b128 v[152:155], v130 offset:3072
	s_waitcnt vmcnt(12)
	s_barrier
	v_mfma_f32_16x16x32_bf16 v[28:31], v[218:221], v[156:159], v[28:31]
	v_mfma_f32_16x16x32_bf16 v[24:27], v[226:229], v[156:159], v[24:27]
	v_mfma_f32_16x16x32_bf16 v[20:23], v[218:221], v[194:197], v[20:23]
	v_mfma_f32_16x16x32_bf16 v[16:19], v[226:229], v[194:197], v[16:19]
	v_mfma_f32_16x16x32_bf16 v[12:15], v[218:221], v[202:205], v[12:15]
	v_mfma_f32_16x16x32_bf16 v[8:11], v[226:229], v[202:205], v[8:11]
	v_mfma_f32_16x16x32_bf16 v[4:7], v[218:221], v[210:213], v[4:7]
	v_mfma_f32_16x16x32_bf16 v[0:3], v[226:229], v[210:213], v[0:3]
	v_mfma_f32_16x16x32_bf16 v[28:31], v[222:225], v[160:163], v[28:31]
	v_mfma_f32_16x16x32_bf16 v[24:27], v[230:233], v[160:163], v[24:27]
	v_mfma_f32_16x16x32_bf16 v[20:23], v[222:225], v[198:201], v[20:23]
	v_mfma_f32_16x16x32_bf16 v[16:19], v[230:233], v[198:201], v[16:19]
	v_mfma_f32_16x16x32_bf16 v[12:15], v[222:225], v[206:209], v[12:15]
	v_mfma_f32_16x16x32_bf16 v[8:11], v[230:233], v[206:209], v[8:11]
	v_mfma_f32_16x16x32_bf16 v[4:7], v[222:225], v[214:217], v[4:7]
	v_mfma_f32_16x16x32_bf16 v[0:3], v[230:233], v[214:217], v[0:3]
	s_barrier
	ds_read_b128 v[156:159], v193 offset:32768
	ds_read_b128 v[160:163], v193 offset:33792
	ds_read_b128 v[194:197], v192 offset:32768
	ds_read_b128 v[198:201], v192 offset:33792
	ds_read_b128 v[202:205], v191 offset:32768
	ds_read_b128 v[206:209], v191 offset:33792
	ds_read_b128 v[210:213], v190 offset:32768
	ds_read_b128 v[214:217], v190 offset:33792
	s_waitcnt lgkmcnt(8)
	s_waitcnt vmcnt(10)
	s_barrier
	s_waitcnt lgkmcnt(0)
	s_waitcnt lgkmcnt(0)
	v_mfma_f32_16x16x32_bf16 v[124:127], v[140:143], v[156:159], v[124:127]
	v_mfma_f32_16x16x32_bf16 v[120:123], v[148:151], v[156:159], v[120:123]
	v_mfma_f32_16x16x32_bf16 v[116:119], v[140:143], v[194:197], v[116:119]
	v_mfma_f32_16x16x32_bf16 v[112:115], v[148:151], v[194:197], v[112:115]
	v_mfma_f32_16x16x32_bf16 v[108:111], v[140:143], v[202:205], v[108:111]
	v_mfma_f32_16x16x32_bf16 v[104:107], v[148:151], v[202:205], v[104:107]
	v_mfma_f32_16x16x32_bf16 v[100:103], v[140:143], v[210:213], v[100:103]
	v_mfma_f32_16x16x32_bf16 v[96:99], v[148:151], v[210:213], v[96:99]
	v_mfma_f32_16x16x32_bf16 v[124:127], v[144:147], v[160:163], v[124:127]
	v_mfma_f32_16x16x32_bf16 v[120:123], v[152:155], v[160:163], v[120:123]
	v_mfma_f32_16x16x32_bf16 v[116:119], v[144:147], v[198:201], v[116:119]
	v_mfma_f32_16x16x32_bf16 v[112:115], v[152:155], v[198:201], v[112:115]
	v_mfma_f32_16x16x32_bf16 v[108:111], v[144:147], v[206:209], v[108:111]
	v_mfma_f32_16x16x32_bf16 v[104:107], v[152:155], v[206:209], v[104:107]
	v_mfma_f32_16x16x32_bf16 v[100:103], v[144:147], v[214:217], v[100:103]
	v_mfma_f32_16x16x32_bf16 v[96:99], v[152:155], v[214:217], v[96:99]
	s_barrier
	s_add_i32 s36, s98, 0x18000
	v_lshl_add_u64 v[234:235], s[46:47], 0, v[164:165]
	s_mov_b32 m0, s36
	s_add_i32 s36, s98, 0x1a000
	ds_read_b128 v[218:221], v132
	ds_read_b128 v[222:225], v132 offset:1024
	ds_read_b128 v[226:229], v132 offset:2048
	ds_read_b128 v[230:233], v132 offset:3072
	global_load_lds_dwordx4 v[234:235], off
	v_lshl_add_u64 v[236:237], v[234:235], 0, s[2:3]
	s_mov_b32 m0, s36
	s_nop 0
	global_load_lds_dwordx4 v[236:237], off
	s_add_i32 s36, s98, 0x8000
	v_lshl_add_u64 v[236:237], v[128:129], 0, s[28:29]
	s_mov_b32 m0, s36
	s_add_i32 s36, s98, 0xa000
	global_load_lds_dwordx4 v[236:237], off
	v_lshl_add_u64 v[236:237], v[128:129], 0, s[30:31]
	s_mov_b32 m0, s36
	s_nop 0
	global_load_lds_dwordx4 v[236:237], off
	s_waitcnt vmcnt(12)
	s_barrier
	s_waitcnt lgkmcnt(0)
	s_waitcnt lgkmcnt(0)
	v_mfma_f32_16x16x32_bf16 v[92:95], v[218:221], v[156:159], v[92:95]
	v_mfma_f32_16x16x32_bf16 v[88:91], v[226:229], v[156:159], v[88:91]
	v_mfma_f32_16x16x32_bf16 v[84:87], v[218:221], v[194:197], v[84:87]
	v_mfma_f32_16x16x32_bf16 v[80:83], v[226:229], v[194:197], v[80:83]
	v_mfma_f32_16x16x32_bf16 v[76:79], v[218:221], v[202:205], v[76:79]
	v_mfma_f32_16x16x32_bf16 v[72:75], v[226:229], v[202:205], v[72:75]
	v_mfma_f32_16x16x32_bf16 v[68:71], v[218:221], v[210:213], v[68:71]
	v_mfma_f32_16x16x32_bf16 v[64:67], v[226:229], v[210:213], v[64:67]
	v_mfma_f32_16x16x32_bf16 v[92:95], v[222:225], v[160:163], v[92:95]
	v_mfma_f32_16x16x32_bf16 v[88:91], v[230:233], v[160:163], v[88:91]
	v_mfma_f32_16x16x32_bf16 v[84:87], v[222:225], v[198:201], v[84:87]
	v_mfma_f32_16x16x32_bf16 v[80:83], v[230:233], v[198:201], v[80:83]
	v_mfma_f32_16x16x32_bf16 v[76:79], v[222:225], v[206:209], v[76:79]
	v_mfma_f32_16x16x32_bf16 v[72:75], v[230:233], v[206:209], v[72:75]
	v_mfma_f32_16x16x32_bf16 v[68:71], v[222:225], v[214:217], v[68:71]
	v_mfma_f32_16x16x32_bf16 v[64:67], v[230:233], v[214:217], v[64:67]
	s_barrier
	ds_read_b128 v[156:159], v193 offset:49152
	ds_read_b128 v[160:163], v193 offset:50176
	ds_read_b128 v[194:197], v192 offset:49152
	ds_read_b128 v[198:201], v192 offset:50176
	ds_read_b128 v[202:205], v191 offset:49152
	ds_read_b128 v[206:209], v191 offset:50176
	ds_read_b128 v[210:213], v190 offset:49152
	ds_read_b128 v[214:217], v190 offset:50176
	s_add_i32 s36, s98, 0x1c000
	v_lshl_add_u64 v[236:237], v[234:235], 0, s[6:7]
	s_mov_b32 m0, s36
	s_add_i32 s36, s98, 0x1e000
	global_load_lds_dwordx4 v[236:237], off
	v_lshl_add_u64 v[236:237], v[234:235], 0, s[8:9]
	s_mov_b32 m0, s36
	s_nop 0
	global_load_lds_dwordx4 v[236:237], off
	s_waitcnt vmcnt(12)
	s_barrier
	s_waitcnt lgkmcnt(0)
	s_waitcnt lgkmcnt(0)
	v_mfma_f32_16x16x32_bf16 v[60:63], v[140:143], v[156:159], v[60:63]
	v_mfma_f32_16x16x32_bf16 v[56:59], v[148:151], v[156:159], v[56:59]
	v_mfma_f32_16x16x32_bf16 v[52:55], v[140:143], v[194:197], v[52:55]
	v_mfma_f32_16x16x32_bf16 v[48:51], v[148:151], v[194:197], v[48:51]
	v_mfma_f32_16x16x32_bf16 v[44:47], v[140:143], v[202:205], v[44:47]
	v_mfma_f32_16x16x32_bf16 v[40:43], v[148:151], v[202:205], v[40:43]
	v_mfma_f32_16x16x32_bf16 v[36:39], v[140:143], v[210:213], v[36:39]
	v_mfma_f32_16x16x32_bf16 v[32:35], v[148:151], v[210:213], v[32:35]
	v_mfma_f32_16x16x32_bf16 v[60:63], v[144:147], v[160:163], v[60:63]
	v_mfma_f32_16x16x32_bf16 v[56:59], v[152:155], v[160:163], v[56:59]
	v_mfma_f32_16x16x32_bf16 v[52:55], v[144:147], v[198:201], v[52:55]
	v_mfma_f32_16x16x32_bf16 v[48:51], v[152:155], v[198:201], v[48:51]
	v_mfma_f32_16x16x32_bf16 v[44:47], v[144:147], v[206:209], v[44:47]
	v_mfma_f32_16x16x32_bf16 v[40:43], v[152:155], v[206:209], v[40:43]
	v_mfma_f32_16x16x32_bf16 v[36:39], v[144:147], v[214:217], v[36:39]
	v_mfma_f32_16x16x32_bf16 v[32:35], v[152:155], v[214:217], v[32:35]
	s_barrier
	v_lshl_add_u64 v[128:129], v[128:129], 0, s[34:35]
	s_add_i32 s36, s98, 0xc000
	v_lshl_add_u64 v[142:143], v[128:129], 0, s[18:19]
	s_mov_b32 m0, s36
	s_add_i32 s36, s98, 0xe000
	global_load_lds_dwordx4 v[142:143], off
	v_lshl_add_u64 v[142:143], v[128:129], 0, s[20:21]
	s_mov_b32 m0, s36
	s_nop 0
	global_load_lds_dwordx4 v[142:143], off
	ds_read_b128 v[140:143], v138
	ds_read_b128 v[144:147], v138 offset:1024
	ds_read_b128 v[148:151], v138 offset:2048
	ds_read_b128 v[152:155], v138 offset:3072
	s_waitcnt vmcnt(12)
	s_barrier
	v_mfma_f32_16x16x32_bf16 v[28:31], v[218:221], v[156:159], v[28:31]
	v_mfma_f32_16x16x32_bf16 v[24:27], v[226:229], v[156:159], v[24:27]
	v_mfma_f32_16x16x32_bf16 v[20:23], v[218:221], v[194:197], v[20:23]
	v_mfma_f32_16x16x32_bf16 v[16:19], v[226:229], v[194:197], v[16:19]
	v_mfma_f32_16x16x32_bf16 v[12:15], v[218:221], v[202:205], v[12:15]
	v_mfma_f32_16x16x32_bf16 v[8:11], v[226:229], v[202:205], v[8:11]
	v_mfma_f32_16x16x32_bf16 v[4:7], v[218:221], v[210:213], v[4:7]
	v_mfma_f32_16x16x32_bf16 v[0:3], v[226:229], v[210:213], v[0:3]
	v_mfma_f32_16x16x32_bf16 v[28:31], v[222:225], v[160:163], v[28:31]
	v_mfma_f32_16x16x32_bf16 v[24:27], v[230:233], v[160:163], v[24:27]
	v_mfma_f32_16x16x32_bf16 v[20:23], v[222:225], v[198:201], v[20:23]
	v_mfma_f32_16x16x32_bf16 v[16:19], v[230:233], v[198:201], v[16:19]
	v_mfma_f32_16x16x32_bf16 v[12:15], v[222:225], v[206:209], v[12:15]
	v_mfma_f32_16x16x32_bf16 v[8:11], v[230:233], v[206:209], v[8:11]
	v_mfma_f32_16x16x32_bf16 v[4:7], v[222:225], v[214:217], v[4:7]
	v_mfma_f32_16x16x32_bf16 v[0:3], v[230:233], v[214:217], v[0:3]
	s_add_i32 s14, s14, 2
	s_add_u32 s46, s46, s56
	s_addc_u32 s47, s47, s57
	s_add_u32 s58, s58, s56
	s_addc_u32 s59, s59, s57
	s_cmp_lt_u32 s14, 28
	s_barrier
	s_cbranch_scc1 .LBB0_521
	s_lshl_b32 s14, s60, 3
	s_or_b32 s80, s61, s14
	s_lshl_b32 s46, s80, 8
	v_lshlrev_b32_e32 v128, 3, v131
	v_lshlrev_b32_e32 v129, 5, v131
	s_or_b32 s14, s46, 0x80
	v_and_b32_e32 v128, 0x7fff0, v128
	v_and_b32_e32 v129, 32, v129
	s_lshl_b64 s[56:57], s[14:15], 13
	v_add_u32_e32 v129, v129, v134
	v_add_lshl_u32 v128, v133, v128, 13
	s_add_u32 s56, s40, s56
	v_lshl_add_u32 v164, v129, 1, v128
	s_addc_u32 s57, s41, s57
	v_lshl_add_u64 v[128:129], s[56:57], 0, v[164:165]
	v_readfirstlane_b32 s14, v137
	ds_read_b128 v[140:143], v138
	ds_read_b128 v[144:147], v138 offset:1024
	ds_read_b128 v[148:151], v138 offset:2048
	ds_read_b128 v[152:155], v138 offset:3072
	ds_read_b128 v[156:159], v193
	ds_read_b128 v[160:163], v193 offset:1024
	ds_read_b128 v[194:197], v192
	ds_read_b128 v[198:201], v192 offset:1024
	ds_read_b128 v[202:205], v191
	ds_read_b128 v[206:209], v191 offset:1024
	ds_read_b128 v[210:213], v190
	ds_read_b128 v[214:217], v190 offset:1024
	v_lshl_add_u64 v[138:139], v[128:129], 0, s[38:39]
	s_mov_b32 m0, s14
	v_readfirstlane_b32 s14, v136
	v_lshl_add_u64 v[128:129], v[128:129], 0, s[44:45]
	s_mov_b32 m0, s14
	s_mov_b32 s47, s15
	s_mul_i32 s99, s76, s84
	s_add_i32 s99, s99, s33
	s_cmpk_lt_u32 s99, 0x400
	s_cbranch_scc1 .Lxt12_has
	s_mov_b32 s99, 0
	s_branch .Lxt12_set

.LBB0_561:
	ds_read_b128 v[178:181], v152
	ds_read_b128 v[182:185], v152 offset:1024
	ds_read_b128 v[186:189], v151
	ds_read_b128 v[190:193], v151 offset:1024
	ds_read_b128 v[194:197], v150
	ds_read_b128 v[198:201], v150 offset:1024
	ds_read_b128 v[202:205], v149
	ds_read_b128 v[206:209], v149 offset:1024
	s_waitcnt lgkmcnt(8)
	s_waitcnt vmcnt(10)
	s_barrier
	s_waitcnt lgkmcnt(0)
	s_waitcnt lgkmcnt(0)
	v_mfma_f32_16x16x32_bf16 v[124:127], v[162:165], v[178:181], v[124:127]
	v_mfma_f32_16x16x32_bf16 v[120:123], v[170:173], v[178:181], v[120:123]
	v_mfma_f32_16x16x32_bf16 v[116:119], v[162:165], v[186:189], v[116:119]
	v_mfma_f32_16x16x32_bf16 v[112:115], v[170:173], v[186:189], v[112:115]
	v_mfma_f32_16x16x32_bf16 v[108:111], v[162:165], v[194:197], v[108:111]
	v_mfma_f32_16x16x32_bf16 v[104:107], v[170:173], v[194:197], v[104:107]
	v_mfma_f32_16x16x32_bf16 v[100:103], v[162:165], v[202:205], v[100:103]
	v_mfma_f32_16x16x32_bf16 v[96:99], v[170:173], v[202:205], v[96:99]
	v_mfma_f32_16x16x32_bf16 v[124:127], v[166:169], v[182:185], v[124:127]
	v_mfma_f32_16x16x32_bf16 v[120:123], v[174:177], v[182:185], v[120:123]
	v_mfma_f32_16x16x32_bf16 v[116:119], v[166:169], v[190:193], v[116:119]
	v_mfma_f32_16x16x32_bf16 v[112:115], v[174:177], v[190:193], v[112:115]
	v_mfma_f32_16x16x32_bf16 v[108:111], v[166:169], v[198:201], v[108:111]
	v_mfma_f32_16x16x32_bf16 v[104:107], v[174:177], v[198:201], v[104:107]
	v_mfma_f32_16x16x32_bf16 v[100:103], v[166:169], v[206:209], v[100:103]
	v_mfma_f32_16x16x32_bf16 v[96:99], v[174:177], v[206:209], v[96:99]
	s_barrier
	s_add_i32 s36, s98, 0x10000
	v_lshl_add_u64 v[226:227], v[130:131], 0, s[26:27]
	s_mov_b32 m0, s36
	s_add_i32 s36, s98, 0x12000
	ds_read_b128 v[210:213], v158
	ds_read_b128 v[214:217], v158 offset:1024
	ds_read_b128 v[218:221], v158 offset:2048
	ds_read_b128 v[222:225], v158 offset:3072
	global_load_lds_dwordx4 v[226:227], off
	v_lshl_add_u64 v[226:227], v[130:131], 0, s[28:29]
	s_mov_b32 m0, s36
	s_add_i32 s68, s68, 2
	global_load_lds_dwordx4 v[226:227], off
	s_mov_b32 s36, s98
	v_lshl_add_u64 v[226:227], v[132:133], 0, s[30:31]
	s_mov_b32 m0, s36
	s_add_i32 s36, s98, 0x2000
	global_load_lds_dwordx4 v[226:227], off
	v_lshl_add_u64 v[226:227], v[132:133], 0, s[34:35]
	s_mov_b32 m0, s36
	s_nop 0
	global_load_lds_dwordx4 v[226:227], off
	s_waitcnt vmcnt(12)
	s_barrier
	s_waitcnt lgkmcnt(0)
	s_waitcnt lgkmcnt(0)
	v_mfma_f32_16x16x32_bf16 v[92:95], v[210:213], v[178:181], v[92:95]
	v_mfma_f32_16x16x32_bf16 v[88:91], v[218:221], v[178:181], v[88:91]
	v_mfma_f32_16x16x32_bf16 v[84:87], v[210:213], v[186:189], v[84:87]
	v_mfma_f32_16x16x32_bf16 v[80:83], v[218:221], v[186:189], v[80:83]
	v_mfma_f32_16x16x32_bf16 v[76:79], v[210:213], v[194:197], v[76:79]
	v_mfma_f32_16x16x32_bf16 v[72:75], v[218:221], v[194:197], v[72:75]
	v_mfma_f32_16x16x32_bf16 v[68:71], v[210:213], v[202:205], v[68:71]
	v_mfma_f32_16x16x32_bf16 v[64:67], v[218:221], v[202:205], v[64:67]
	v_mfma_f32_16x16x32_bf16 v[92:95], v[214:217], v[182:185], v[92:95]
	v_mfma_f32_16x16x32_bf16 v[88:91], v[222:225], v[182:185], v[88:91]
	v_mfma_f32_16x16x32_bf16 v[84:87], v[214:217], v[190:193], v[84:87]
	v_mfma_f32_16x16x32_bf16 v[80:83], v[222:225], v[190:193], v[80:83]
	v_mfma_f32_16x16x32_bf16 v[76:79], v[214:217], v[198:201], v[76:79]
	v_mfma_f32_16x16x32_bf16 v[72:75], v[222:225], v[198:201], v[72:75]
	v_mfma_f32_16x16x32_bf16 v[68:71], v[214:217], v[206:209], v[68:71]
	v_mfma_f32_16x16x32_bf16 v[64:67], v[222:225], v[206:209], v[64:67]
	s_barrier
	ds_read_b128 v[178:181], v152 offset:16384
	ds_read_b128 v[182:185], v152 offset:17408
	ds_read_b128 v[186:189], v151 offset:16384
	ds_read_b128 v[190:193], v151 offset:17408
	ds_read_b128 v[194:197], v150 offset:16384
	ds_read_b128 v[198:201], v150 offset:17408
	ds_read_b128 v[202:205], v149 offset:16384
	ds_read_b128 v[206:209], v149 offset:17408
	s_add_i32 s36, s98, 0x14000
	v_lshl_add_u64 v[226:227], v[130:131], 0, s[38:39]
	s_mov_b32 m0, s36
	s_add_i32 s36, s98, 0x16000
	global_load_lds_dwordx4 v[226:227], off
	v_lshl_add_u64 v[226:227], v[130:131], 0, s[44:45]
	s_mov_b32 m0, s36
	s_nop 0
	global_load_lds_dwordx4 v[226:227], off
	s_waitcnt vmcnt(12)
	s_barrier
	s_waitcnt lgkmcnt(0)
	s_waitcnt lgkmcnt(0)
	v_mfma_f32_16x16x32_bf16 v[60:63], v[162:165], v[178:181], v[60:63]
	v_mfma_f32_16x16x32_bf16 v[56:59], v[170:173], v[178:181], v[56:59]
	v_mfma_f32_16x16x32_bf16 v[52:55], v[162:165], v[186:189], v[52:55]
	v_mfma_f32_16x16x32_bf16 v[48:51], v[170:173], v[186:189], v[48:51]
	v_mfma_f32_16x16x32_bf16 v[44:47], v[162:165], v[194:197], v[44:47]
	v_mfma_f32_16x16x32_bf16 v[40:43], v[170:173], v[194:197], v[40:43]
	v_mfma_f32_16x16x32_bf16 v[36:39], v[162:165], v[202:205], v[36:39]
	v_mfma_f32_16x16x32_bf16 v[32:35], v[170:173], v[202:205], v[32:35]
	v_mfma_f32_16x16x32_bf16 v[60:63], v[166:169], v[182:185], v[60:63]
	v_mfma_f32_16x16x32_bf16 v[56:59], v[174:177], v[182:185], v[56:59]
	v_mfma_f32_16x16x32_bf16 v[52:55], v[166:169], v[190:193], v[52:55]
	v_mfma_f32_16x16x32_bf16 v[48:51], v[174:177], v[190:193], v[48:51]
	v_mfma_f32_16x16x32_bf16 v[44:47], v[166:169], v[198:201], v[44:47]
	v_mfma_f32_16x16x32_bf16 v[40:43], v[174:177], v[198:201], v[40:43]
	v_mfma_f32_16x16x32_bf16 v[36:39], v[166:169], v[206:209], v[36:39]
	v_mfma_f32_16x16x32_bf16 v[32:35], v[174:177], v[206:209], v[32:35]
	s_barrier
	s_add_i32 s36, s98, 0x4000
	v_lshl_add_u64 v[164:165], v[132:133], 0, s[46:47]
	s_mov_b32 m0, s36
	s_add_i32 s36, s98, 0x6000
	global_load_lds_dwordx4 v[164:165], off
	v_lshl_add_u64 v[164:165], v[132:133], 0, s[50:51]
	s_mov_b32 m0, s36
	s_nop 0
	global_load_lds_dwordx4 v[164:165], off
	ds_read_b128 v[162:165], v154
	ds_read_b128 v[166:169], v154 offset:1024
	ds_read_b128 v[170:173], v154 offset:2048
	ds_read_b128 v[174:177], v154 offset:3072
	s_waitcnt vmcnt(12)
	s_barrier
	v_mfma_f32_16x16x32_bf16 v[28:31], v[210:213], v[178:181], v[28:31]
	v_mfma_f32_16x16x32_bf16 v[24:27], v[218:221], v[178:181], v[24:27]
	v_mfma_f32_16x16x32_bf16 v[20:23], v[210:213], v[186:189], v[20:23]
	v_mfma_f32_16x16x32_bf16 v[16:19], v[218:221], v[186:189], v[16:19]
	v_mfma_f32_16x16x32_bf16 v[12:15], v[210:213], v[194:197], v[12:15]
	v_mfma_f32_16x16x32_bf16 v[8:11], v[218:221], v[194:197], v[8:11]
	v_mfma_f32_16x16x32_bf16 v[4:7], v[210:213], v[202:205], v[4:7]
	v_mfma_f32_16x16x32_bf16 v[0:3], v[218:221], v[202:205], v[0:3]
	v_mfma_f32_16x16x32_bf16 v[28:31], v[214:217], v[182:185], v[28:31]
	v_mfma_f32_16x16x32_bf16 v[24:27], v[222:225], v[182:185], v[24:27]
	v_mfma_f32_16x16x32_bf16 v[20:23], v[214:217], v[190:193], v[20:23]
	v_mfma_f32_16x16x32_bf16 v[16:19], v[222:225], v[190:193], v[16:19]
	v_mfma_f32_16x16x32_bf16 v[12:15], v[214:217], v[198:201], v[12:15]
	v_mfma_f32_16x16x32_bf16 v[8:11], v[222:225], v[198:201], v[8:11]
	v_mfma_f32_16x16x32_bf16 v[4:7], v[214:217], v[206:209], v[4:7]
	v_mfma_f32_16x16x32_bf16 v[0:3], v[222:225], v[206:209], v[0:3]
	s_barrier
	ds_read_b128 v[178:181], v152 offset:32768
	ds_read_b128 v[182:185], v152 offset:33792
	ds_read_b128 v[186:189], v151 offset:32768
	ds_read_b128 v[190:193], v151 offset:33792
	ds_read_b128 v[194:197], v150 offset:32768
	ds_read_b128 v[198:201], v150 offset:33792
	ds_read_b128 v[202:205], v149 offset:32768
	ds_read_b128 v[206:209], v149 offset:33792
	s_waitcnt lgkmcnt(8)
	s_waitcnt vmcnt(10)
	s_barrier
	s_waitcnt lgkmcnt(0)
	s_waitcnt lgkmcnt(0)
	v_mfma_f32_16x16x32_bf16 v[124:127], v[162:165], v[178:181], v[124:127]
	v_mfma_f32_16x16x32_bf16 v[120:123], v[170:173], v[178:181], v[120:123]
	v_mfma_f32_16x16x32_bf16 v[116:119], v[162:165], v[186:189], v[116:119]
	v_mfma_f32_16x16x32_bf16 v[112:115], v[170:173], v[186:189], v[112:115]
	v_mfma_f32_16x16x32_bf16 v[108:111], v[162:165], v[194:197], v[108:111]
	v_mfma_f32_16x16x32_bf16 v[104:107], v[170:173], v[194:197], v[104:107]
	v_mfma_f32_16x16x32_bf16 v[100:103], v[162:165], v[202:205], v[100:103]
	v_mfma_f32_16x16x32_bf16 v[96:99], v[170:173], v[202:205], v[96:99]
	v_mfma_f32_16x16x32_bf16 v[124:127], v[166:169], v[182:185], v[124:127]
	v_mfma_f32_16x16x32_bf16 v[120:123], v[174:177], v[182:185], v[120:123]
	v_mfma_f32_16x16x32_bf16 v[116:119], v[166:169], v[190:193], v[116:119]
	v_mfma_f32_16x16x32_bf16 v[112:115], v[174:177], v[190:193], v[112:115]
	v_mfma_f32_16x16x32_bf16 v[108:111], v[166:169], v[198:201], v[108:111]
	v_mfma_f32_16x16x32_bf16 v[104:107], v[174:177], v[198:201], v[104:107]
	v_mfma_f32_16x16x32_bf16 v[100:103], v[166:169], v[206:209], v[100:103]
	v_mfma_f32_16x16x32_bf16 v[96:99], v[174:177], v[206:209], v[96:99]
	s_barrier
	s_add_i32 s36, s98, 0x18000
	v_lshl_add_u64 v[226:227], v[130:131], 0, s[56:57]
	s_mov_b32 m0, s36
	s_add_i32 s36, s98, 0x1a000
	ds_read_b128 v[210:213], v153
	ds_read_b128 v[214:217], v153 offset:1024
	ds_read_b128 v[218:221], v153 offset:2048
	ds_read_b128 v[222:225], v153 offset:3072
	global_load_lds_dwordx4 v[226:227], off
	v_lshl_add_u64 v[226:227], v[130:131], 0, s[58:59]
	s_mov_b32 m0, s36
	s_nop 0
	global_load_lds_dwordx4 v[226:227], off
	s_add_i32 s36, s98, 0x8000
	v_lshl_add_u64 v[226:227], v[132:133], 0, s[60:61]
	s_mov_b32 m0, s36
	s_add_i32 s36, s98, 0xa000
	global_load_lds_dwordx4 v[226:227], off
	s_mov_b32 m0, s36
	s_nop 0
	global_load_lds_dwordx4 v[132:133], off
	s_waitcnt vmcnt(12)
	s_barrier
	s_waitcnt lgkmcnt(0)
	s_waitcnt lgkmcnt(0)
	v_mfma_f32_16x16x32_bf16 v[92:95], v[210:213], v[178:181], v[92:95]
	v_mfma_f32_16x16x32_bf16 v[88:91], v[218:221], v[178:181], v[88:91]
	v_mfma_f32_16x16x32_bf16 v[84:87], v[210:213], v[186:189], v[84:87]
	v_mfma_f32_16x16x32_bf16 v[80:83], v[218:221], v[186:189], v[80:83]
	v_mfma_f32_16x16x32_bf16 v[76:79], v[210:213], v[194:197], v[76:79]
	v_mfma_f32_16x16x32_bf16 v[72:75], v[218:221], v[194:197], v[72:75]
	v_mfma_f32_16x16x32_bf16 v[68:71], v[210:213], v[202:205], v[68:71]
	v_mfma_f32_16x16x32_bf16 v[64:67], v[218:221], v[202:205], v[64:67]
	v_mfma_f32_16x16x32_bf16 v[92:95], v[214:217], v[182:185], v[92:95]
	v_mfma_f32_16x16x32_bf16 v[88:91], v[222:225], v[182:185], v[88:91]
	v_mfma_f32_16x16x32_bf16 v[84:87], v[214:217], v[190:193], v[84:87]
	v_mfma_f32_16x16x32_bf16 v[80:83], v[222:225], v[190:193], v[80:83]
	v_mfma_f32_16x16x32_bf16 v[76:79], v[214:217], v[198:201], v[76:79]
	v_mfma_f32_16x16x32_bf16 v[72:75], v[222:225], v[198:201], v[72:75]
	v_mfma_f32_16x16x32_bf16 v[68:71], v[214:217], v[206:209], v[68:71]
	v_mfma_f32_16x16x32_bf16 v[64:67], v[222:225], v[206:209], v[64:67]
	s_barrier
	ds_read_b128 v[178:181], v152 offset:49152
	ds_read_b128 v[182:185], v152 offset:50176
	ds_read_b128 v[186:189], v151 offset:49152
	ds_read_b128 v[190:193], v151 offset:50176
	ds_read_b128 v[194:197], v150 offset:49152
	ds_read_b128 v[198:201], v150 offset:50176
	ds_read_b128 v[202:205], v149 offset:49152
	ds_read_b128 v[206:209], v149 offset:50176
	s_add_i32 s36, s98, 0x1c000
	v_lshl_add_u64 v[226:227], v[130:131], 0, s[60:61]
	s_mov_b32 m0, s36
	s_add_i32 s36, s98, 0x1e000
	global_load_lds_dwordx4 v[226:227], off
	s_mov_b32 m0, s36
	s_nop 0
	global_load_lds_dwordx4 v[130:131], off
	s_waitcnt vmcnt(12)
	s_barrier
	s_waitcnt lgkmcnt(0)
	s_waitcnt lgkmcnt(0)
	v_mfma_f32_16x16x32_bf16 v[60:63], v[162:165], v[178:181], v[60:63]
	v_mfma_f32_16x16x32_bf16 v[56:59], v[170:173], v[178:181], v[56:59]
	v_mfma_f32_16x16x32_bf16 v[52:55], v[162:165], v[186:189], v[52:55]
	v_mfma_f32_16x16x32_bf16 v[48:51], v[170:173], v[186:189], v[48:51]
	v_mfma_f32_16x16x32_bf16 v[44:47], v[162:165], v[194:197], v[44:47]
	v_mfma_f32_16x16x32_bf16 v[40:43], v[170:173], v[194:197], v[40:43]
	v_mfma_f32_16x16x32_bf16 v[36:39], v[162:165], v[202:205], v[36:39]
	v_mfma_f32_16x16x32_bf16 v[32:35], v[170:173], v[202:205], v[32:35]
	v_mfma_f32_16x16x32_bf16 v[60:63], v[166:169], v[182:185], v[60:63]
	v_mfma_f32_16x16x32_bf16 v[56:59], v[174:177], v[182:185], v[56:59]
	v_mfma_f32_16x16x32_bf16 v[52:55], v[166:169], v[190:193], v[52:55]
	v_mfma_f32_16x16x32_bf16 v[48:51], v[174:177], v[190:193], v[48:51]
	v_mfma_f32_16x16x32_bf16 v[44:47], v[166:169], v[198:201], v[44:47]
	v_mfma_f32_16x16x32_bf16 v[40:43], v[174:177], v[198:201], v[40:43]
	v_mfma_f32_16x16x32_bf16 v[36:39], v[166:169], v[206:209], v[36:39]
	v_mfma_f32_16x16x32_bf16 v[32:35], v[174:177], v[206:209], v[32:35]
	s_barrier
	v_lshl_add_u64 v[132:133], v[132:133], 0, s[64:65]
	s_add_i32 s36, s98, 0xc000
	v_lshl_add_u64 v[164:165], v[132:133], 0, s[22:23]
	s_mov_b32 m0, s36
	s_add_i32 s36, s98, 0xe000
	global_load_lds_dwordx4 v[164:165], off
	v_lshl_add_u64 v[164:165], v[132:133], 0, s[24:25]
	s_mov_b32 m0, s36
	s_nop 0
	global_load_lds_dwordx4 v[164:165], off
	ds_read_b128 v[162:165], v161
	ds_read_b128 v[166:169], v161 offset:1024
	ds_read_b128 v[170:173], v161 offset:2048
	ds_read_b128 v[174:177], v161 offset:3072
	s_waitcnt vmcnt(12)
	s_barrier
	v_mfma_f32_16x16x32_bf16 v[28:31], v[210:213], v[178:181], v[28:31]
	v_mfma_f32_16x16x32_bf16 v[24:27], v[218:221], v[178:181], v[24:27]
	v_mfma_f32_16x16x32_bf16 v[20:23], v[210:213], v[186:189], v[20:23]
	v_mfma_f32_16x16x32_bf16 v[16:19], v[218:221], v[186:189], v[16:19]
	v_mfma_f32_16x16x32_bf16 v[12:15], v[210:213], v[194:197], v[12:15]
	v_mfma_f32_16x16x32_bf16 v[8:11], v[218:221], v[194:197], v[8:11]
	v_mfma_f32_16x16x32_bf16 v[4:7], v[210:213], v[202:205], v[4:7]
	v_mfma_f32_16x16x32_bf16 v[0:3], v[218:221], v[202:205], v[0:3]
	v_mfma_f32_16x16x32_bf16 v[28:31], v[214:217], v[182:185], v[28:31]
	v_mfma_f32_16x16x32_bf16 v[24:27], v[222:225], v[182:185], v[24:27]
	v_mfma_f32_16x16x32_bf16 v[20:23], v[214:217], v[190:193], v[20:23]
	v_mfma_f32_16x16x32_bf16 v[16:19], v[222:225], v[190:193], v[16:19]
	v_mfma_f32_16x16x32_bf16 v[12:15], v[214:217], v[198:201], v[12:15]
	v_mfma_f32_16x16x32_bf16 v[8:11], v[222:225], v[198:201], v[8:11]
	v_mfma_f32_16x16x32_bf16 v[4:7], v[214:217], v[206:209], v[4:7]
	v_mfma_f32_16x16x32_bf16 v[0:3], v[222:225], v[206:209], v[0:3]
	v_lshl_add_u64 v[130:131], v[130:131], 0, s[62:63]
	s_cmp_lt_u32 s68, s67
	s_barrier
	s_cbranch_scc1 .LBB0_561
	s_lshl_b32 s36, s86, 5
	s_lshl_b32 s37, s86, 8
	s_and_b32 s36, s36, 0x1800
	s_and_b32 s37, s37, 0x700
	s_or_b32 s96, s37, s36
	s_lshl_b32 s36, s96, 6
	s_add_u32 s36, s70, s36
	s_addc_u32 s37, s71, 0
	s_add_i32 s20, s20, -1
	s_lshl_b64 s[68:69], s[20:21], 20
	v_add_u32_e32 v128, v156, v157
	s_add_u32 s68, s36, s68
	v_or_b32_e32 v128, v128, v155
	s_addc_u32 s69, s37, s69
	v_lshl_add_u64 v[156:157], s[68:69], 0, v[128:129]
	v_readfirstlane_b32 s20, v160
	v_lshl_add_u64 v[206:207], v[156:157], 0, s[4:5]
	s_mov_b32 m0, s20
	v_readfirstlane_b32 s20, v159
	ds_read_b128 v[130:133], v161
	ds_read_b128 v[162:165], v161 offset:1024
	ds_read_b128 v[166:169], v161 offset:2048
	ds_read_b128 v[170:173], v161 offset:3072
	ds_read_b128 v[174:177], v152
	ds_read_b128 v[178:181], v152 offset:1024
	ds_read_b128 v[182:185], v151
	ds_read_b128 v[186:189], v151 offset:1024
	ds_read_b128 v[190:193], v150
	ds_read_b128 v[194:197], v150 offset:1024
	ds_read_b128 v[198:201], v149
	ds_read_b128 v[202:205], v149 offset:1024
	v_lshl_add_u64 v[156:157], v[156:157], 0, s[6:7]
	s_mov_b32 m0, s20
	s_nop 0
	s_waitcnt vmcnt(8)
	s_barrier
	s_waitcnt lgkmcnt(0)
	s_setprio 1
	s_waitcnt lgkmcnt(0)
	v_mfma_f32_16x16x32_bf16 v[124:127], v[130:133], v[174:177], v[124:127]
	v_mfma_f32_16x16x32_bf16 v[120:123], v[166:169], v[174:177], v[120:123]
	v_mfma_f32_16x16x32_bf16 v[116:119], v[130:133], v[182:185], v[116:119]
	v_mfma_f32_16x16x32_bf16 v[112:115], v[166:169], v[182:185], v[112:115]
	v_mfma_f32_16x16x32_bf16 v[108:111], v[130:133], v[190:193], v[108:111]
	v_mfma_f32_16x16x32_bf16 v[104:107], v[166:169], v[190:193], v[104:107]
	v_mfma_f32_16x16x32_bf16 v[100:103], v[130:133], v[198:201], v[100:103]
	v_mfma_f32_16x16x32_bf16 v[96:99], v[166:169], v[198:201], v[96:99]
	v_mfma_f32_16x16x32_bf16 v[124:127], v[162:165], v[178:181], v[124:127]
	v_mfma_f32_16x16x32_bf16 v[120:123], v[170:173], v[178:181], v[120:123]
	v_mfma_f32_16x16x32_bf16 v[116:119], v[162:165], v[186:189], v[116:119]
	v_mfma_f32_16x16x32_bf16 v[112:115], v[170:173], v[186:189], v[112:115]
	v_mfma_f32_16x16x32_bf16 v[108:111], v[162:165], v[194:197], v[108:111]
	v_mfma_f32_16x16x32_bf16 v[104:107], v[170:173], v[194:197], v[104:107]
	v_mfma_f32_16x16x32_bf16 v[100:103], v[162:165], v[202:205], v[100:103]
	v_mfma_f32_16x16x32_bf16 v[96:99], v[170:173], v[202:205], v[96:99]
	s_setprio 0
	s_barrier
	ds_read_b128 v[206:209], v158
	ds_read_b128 v[210:213], v158 offset:1024
	ds_read_b128 v[214:217], v158 offset:2048
	ds_read_b128 v[156:159], v158 offset:3072
	s_barrier
	s_waitcnt lgkmcnt(0)
	s_setprio 1
	s_waitcnt lgkmcnt(0)
	v_mfma_f32_16x16x32_bf16 v[92:95], v[206:209], v[174:177], v[92:95]
	v_mfma_f32_16x16x32_bf16 v[88:91], v[214:217], v[174:177], v[88:91]
	v_mfma_f32_16x16x32_bf16 v[84:87], v[206:209], v[182:185], v[84:87]
	v_mfma_f32_16x16x32_bf16 v[80:83], v[214:217], v[182:185], v[80:83]
	v_mfma_f32_16x16x32_bf16 v[76:79], v[206:209], v[190:193], v[76:79]
	v_mfma_f32_16x16x32_bf16 v[72:75], v[214:217], v[190:193], v[72:75]
	v_mfma_f32_16x16x32_bf16 v[68:71], v[206:209], v[198:201], v[68:71]
	v_mfma_f32_16x16x32_bf16 v[64:67], v[214:217], v[198:201], v[64:67]
	v_mfma_f32_16x16x32_bf16 v[174:177], v[210:213], v[178:181], v[92:95]
	v_mfma_f32_16x16x32_bf16 v[178:181], v[156:159], v[178:181], v[88:91]
	v_mfma_f32_16x16x32_bf16 v[182:185], v[210:213], v[186:189], v[84:87]
	v_mfma_f32_16x16x32_bf16 v[186:189], v[156:159], v[186:189], v[80:83]
	v_mfma_f32_16x16x32_bf16 v[190:193], v[210:213], v[194:197], v[76:79]
	v_mfma_f32_16x16x32_bf16 v[194:197], v[156:159], v[194:197], v[72:75]
	v_mfma_f32_16x16x32_bf16 v[198:201], v[210:213], v[202:205], v[68:71]
	v_mfma_f32_16x16x32_bf16 v[202:205], v[156:159], v[202:205], v[64:67]
	s_setprio 0
	s_barrier
	s_nop 0
	ds_read_b128 v[64:67], v152 offset:16384
	ds_read_b128 v[68:71], v152 offset:17408
	ds_read_b128 v[72:75], v151 offset:16384
	ds_read_b128 v[76:79], v151 offset:17408
	ds_read_b128 v[80:83], v150 offset:16384
	ds_read_b128 v[84:87], v150 offset:17408
	ds_read_b128 v[88:91], v149 offset:16384
	ds_read_b128 v[92:95], v149 offset:17408
	s_waitcnt vmcnt(4)
	s_barrier
	s_waitcnt lgkmcnt(0)
	s_setprio 1
	s_waitcnt lgkmcnt(0)
	v_mfma_f32_16x16x32_bf16 v[60:63], v[130:133], v[64:67], v[60:63]
	v_mfma_f32_16x16x32_bf16 v[56:59], v[166:169], v[64:67], v[56:59]
	v_mfma_f32_16x16x32_bf16 v[52:55], v[130:133], v[72:75], v[52:55]
	v_mfma_f32_16x16x32_bf16 v[48:51], v[166:169], v[72:75], v[48:51]
	v_mfma_f32_16x16x32_bf16 v[218:221], v[130:133], v[80:83], v[44:47]
	v_mfma_f32_16x16x32_bf16 v[222:225], v[166:169], v[80:83], v[40:43]
	v_mfma_f32_16x16x32_bf16 v[130:133], v[130:133], v[88:91], v[36:39]
	v_mfma_f32_16x16x32_bf16 v[166:169], v[166:169], v[88:91], v[32:35]
	v_mfma_f32_16x16x32_bf16 v[32:35], v[162:165], v[68:71], v[60:63]
	v_mfma_f32_16x16x32_bf16 v[36:39], v[170:173], v[68:71], v[56:59]
	v_mfma_f32_16x16x32_bf16 v[40:43], v[162:165], v[76:79], v[52:55]
	v_mfma_f32_16x16x32_bf16 v[44:47], v[170:173], v[76:79], v[48:51]
	v_mfma_f32_16x16x32_bf16 v[48:51], v[162:165], v[84:87], v[218:221]
	v_mfma_f32_16x16x32_bf16 v[52:55], v[170:173], v[84:87], v[222:225]
	v_mfma_f32_16x16x32_bf16 v[56:59], v[162:165], v[92:95], v[130:133]
	v_mfma_f32_16x16x32_bf16 v[60:63], v[170:173], v[92:95], v[166:169]
	s_setprio 0
	s_setprio 1
	v_mfma_f32_16x16x32_bf16 v[28:31], v[206:209], v[64:67], v[28:31]
	v_mfma_f32_16x16x32_bf16 v[24:27], v[214:217], v[64:67], v[24:27]
	v_mfma_f32_16x16x32_bf16 v[20:23], v[206:209], v[72:75], v[20:23]
	v_mfma_f32_16x16x32_bf16 v[64:67], v[214:217], v[72:75], v[16:19]
	v_mfma_f32_16x16x32_bf16 v[72:75], v[206:209], v[80:83], v[12:15]
	v_mfma_f32_16x16x32_bf16 v[8:11], v[214:217], v[80:83], v[8:11]
	v_mfma_f32_16x16x32_bf16 v[80:83], v[206:209], v[88:91], v[4:7]
	v_mfma_f32_16x16x32_bf16 v[0:3], v[214:217], v[88:91], v[0:3]
	v_mfma_f32_16x16x32_bf16 v[4:7], v[210:213], v[68:71], v[28:31]
	v_mfma_f32_16x16x32_bf16 v[12:15], v[156:159], v[68:71], v[24:27]
	v_mfma_f32_16x16x32_bf16 v[16:19], v[210:213], v[76:79], v[20:23]
	v_mfma_f32_16x16x32_bf16 v[20:23], v[156:159], v[76:79], v[64:67]
	v_mfma_f32_16x16x32_bf16 v[24:27], v[210:213], v[84:87], v[72:75]
	v_mfma_f32_16x16x32_bf16 v[28:31], v[156:159], v[84:87], v[8:11]
	v_mfma_f32_16x16x32_bf16 v[64:67], v[210:213], v[92:95], v[80:83]
	v_mfma_f32_16x16x32_bf16 v[68:71], v[156:159], v[92:95], v[0:3]
	s_setprio 0
	s_barrier
	ds_read_b128 v[8:11], v154
	ds_read_b128 v[0:3], v154 offset:1024
	ds_read_b128 v[76:79], v154 offset:2048
	ds_read_b128 v[72:75], v154 offset:3072
	ds_read_b128 v[130:133], v152 offset:32768
	ds_read_b128 v[154:157], v152 offset:33792
	ds_read_b128 v[158:161], v151 offset:32768
	ds_read_b128 v[162:165], v151 offset:33792
	ds_read_b128 v[166:169], v150 offset:32768
	ds_read_b128 v[170:173], v150 offset:33792
	ds_read_b128 v[206:209], v149 offset:32768
	ds_read_b128 v[210:213], v149 offset:33792
	s_waitcnt vmcnt(2)
	s_barrier
	s_waitcnt lgkmcnt(0)
	s_setprio 1
	s_waitcnt lgkmcnt(0)
	v_mfma_f32_16x16x32_bf16 v[80:83], v[8:11], v[130:133], v[124:127]
	v_mfma_f32_16x16x32_bf16 v[84:87], v[76:79], v[130:133], v[120:123]
	v_mfma_f32_16x16x32_bf16 v[88:91], v[8:11], v[158:161], v[116:119]
	v_mfma_f32_16x16x32_bf16 v[92:95], v[76:79], v[158:161], v[112:115]
	v_mfma_f32_16x16x32_bf16 v[108:111], v[8:11], v[166:169], v[108:111]
	v_mfma_f32_16x16x32_bf16 v[104:107], v[76:79], v[166:169], v[104:107]
	v_mfma_f32_16x16x32_bf16 v[100:103], v[8:11], v[206:209], v[100:103]
	v_mfma_f32_16x16x32_bf16 v[96:99], v[76:79], v[206:209], v[96:99]
	v_mfma_f32_16x16x32_bf16 v[112:115], v[0:3], v[154:157], v[80:83]
	v_mfma_f32_16x16x32_bf16 v[116:119], v[72:75], v[154:157], v[84:87]
	v_mfma_f32_16x16x32_bf16 v[120:123], v[0:3], v[162:165], v[88:91]
	v_mfma_f32_16x16x32_bf16 v[124:127], v[72:75], v[162:165], v[92:95]
	v_mfma_f32_16x16x32_bf16 v[108:111], v[0:3], v[170:173], v[108:111]
	v_mfma_f32_16x16x32_bf16 v[104:107], v[72:75], v[170:173], v[104:107]
	v_mfma_f32_16x16x32_bf16 v[100:103], v[0:3], v[210:213], v[100:103]
	v_mfma_f32_16x16x32_bf16 v[96:99], v[72:75], v[210:213], v[96:99]
	s_setprio 0
	s_barrier
	ds_read_b128 v[88:91], v153
	ds_read_b128 v[80:83], v153 offset:1024
	ds_read_b128 v[92:95], v153 offset:2048
	ds_read_b128 v[84:87], v153 offset:3072
	s_waitcnt vmcnt(0)
	s_barrier
	s_waitcnt lgkmcnt(0)
	s_setprio 1
	s_waitcnt lgkmcnt(0)
	v_mfma_f32_16x16x32_bf16 v[174:177], v[88:91], v[130:133], v[174:177]
	v_mfma_f32_16x16x32_bf16 v[130:133], v[92:95], v[130:133], v[178:181]
	v_mfma_f32_16x16x32_bf16 v[178:181], v[88:91], v[158:161], v[182:185]
	v_mfma_f32_16x16x32_bf16 v[158:161], v[92:95], v[158:161], v[186:189]
	v_mfma_f32_16x16x32_bf16 v[182:185], v[88:91], v[166:169], v[190:193]
	v_mfma_f32_16x16x32_bf16 v[166:169], v[92:95], v[166:169], v[194:197]
	v_mfma_f32_16x16x32_bf16 v[186:189], v[88:91], v[206:209], v[198:201]
	v_mfma_f32_16x16x32_bf16 v[190:193], v[92:95], v[206:209], v[202:205]
	v_mfma_f32_16x16x32_bf16 v[174:177], v[80:83], v[154:157], v[174:177]
	v_mfma_f32_16x16x32_bf16 v[130:133], v[84:87], v[154:157], v[130:133]
	v_mfma_f32_16x16x32_bf16 v[154:157], v[80:83], v[162:165], v[178:181]
	v_mfma_f32_16x16x32_bf16 v[158:161], v[84:87], v[162:165], v[158:161]
	v_mfma_f32_16x16x32_bf16 v[162:165], v[80:83], v[170:173], v[182:185]
	v_mfma_f32_16x16x32_bf16 v[166:169], v[84:87], v[170:173], v[166:169]
	v_mfma_f32_16x16x32_bf16 v[170:173], v[80:83], v[210:213], v[186:189]
	v_mfma_f32_16x16x32_bf16 v[178:181], v[84:87], v[210:213], v[190:193]
	s_setprio 0
	s_barrier
	v_mbcnt_lo_u32_b32 v128, -1, 0
	v_mbcnt_hi_u32_b32 v128, -1, v128
	v_cvt_pk_bf16_f32 v112, v112, v113
	v_cvt_pk_bf16_f32 v113, v114, v115
	v_cvt_pk_bf16_f32 v114, v116, v117
	v_cvt_pk_bf16_f32 v115, v118, v119
	s_lshl_b32 s89, s66, 9
	v_add_u32_e32 v153, s74, v128
	v_ashrrev_i32_e32 v182, 6, v153
	v_and_b32_e32 v183, 15, v128
	v_and_b32_e32 v184, 48, v128
	v_mul_lo_u32 v185, v182, s79
	v_bfe_u32 v186, v128, 3, 3
	v_lshlrev_b32_e32 v128, 4, v128
	v_add_u32_e32 v185, 0x20000, v185
	v_lshrrev_b32_e32 v153, 2, v153
	v_and_b32_e32 v128, 0x70, v128
	v_mul_u32_u24_e32 v183, 0x90, v183
	v_and_b32_e32 v153, 64, v153
	v_add3_u32 v183, v185, v183, v184
	v_or_b32_e32 v184, v185, v128
	v_or3_b32 v153, s96, v153, v186
	v_mad_u32_u24 v184, v186, s81, v184
	ds_write_b128 v183, v[112:115]
	v_cvt_pk_bf16_f32 v112, v174, v175
	v_cvt_pk_bf16_f32 v113, v176, v177
	v_cvt_pk_bf16_f32 v114, v130, v131
	v_cvt_pk_bf16_f32 v115, v132, v133
	ds_write_b128 v183, v[112:115] offset:64
	v_lshlrev_b32_e32 v182, 7, v182
	ds_read_b128 v[112:115], v184
	v_lshlrev_b32_e32 v116, 12, v153
	v_and_or_b32 v116, v182, s82, v116
	v_or3_b32 v128, v116, s89, v128
	ds_read_b128 v[116:119], v184 offset:1152
	v_lshl_add_u64 v[130:131], s[0:1], 0, v[128:129]
	s_mov_b32 s20, 0x8000
	s_waitcnt lgkmcnt(0)
	global_store_dwordx4 v128, v[112:115], s[0:1]
	v_cvt_pk_bf16_f32 v108, v108, v109
	v_cvt_pk_bf16_f32 v109, v110, v111
	v_cvt_pk_bf16_f32 v110, v104, v105
	v_cvt_pk_bf16_f32 v111, v106, v107
	v_cvt_pk_bf16_f32 v104, v162, v163
	s_nop 1
	v_add_co_u32_e32 v112, vcc, s20, v130
	v_cvt_pk_bf16_f32 v114, v124, v125
	v_cvt_pk_bf16_f32 v115, v126, v127
	v_cvt_pk_bf16_f32 v105, v164, v165
	v_cvt_pk_bf16_f32 v106, v166, v167
	s_nop 1
	v_addc_co_u32_e32 v113, vcc, 0, v131, vcc
	global_store_dwordx4 v[112:113], v[116:119], off
	v_cvt_pk_bf16_f32 v112, v120, v121
	v_cvt_pk_bf16_f32 v113, v122, v123
	ds_write_b128 v183, v[112:115]
	v_cvt_pk_bf16_f32 v112, v154, v155
	v_cvt_pk_bf16_f32 v113, v156, v157
	v_cvt_pk_bf16_f32 v114, v158, v159
	v_cvt_pk_bf16_f32 v115, v160, v161
	ds_write_b128 v183, v[112:115] offset:64
	ds_read_b128 v[112:115], v184
	ds_read_b128 v[116:119], v184 offset:1152
	v_add_co_u32_e32 v120, vcc, s76, v130
	ds_write_b128 v183, v[108:111]
	v_cvt_pk_bf16_f32 v107, v168, v169
	ds_write_b128 v183, v[104:107] offset:64
	v_addc_co_u32_e32 v121, vcc, 0, v131, vcc
	ds_read_b128 v[104:107], v184
	ds_read_b128 v[108:111], v184 offset:1152
	s_waitcnt lgkmcnt(0)
	global_store_dwordx4 v[120:121], v[112:115], off
	v_cvt_pk_bf16_f32 v100, v100, v101
	v_cvt_pk_bf16_f32 v101, v102, v103
	v_cvt_pk_bf16_f32 v102, v96, v97
	v_cvt_pk_bf16_f32 v103, v98, v99
	ds_write_b128 v183, v[100:103]
	s_nop 0
	v_add_co_u32_e32 v112, vcc, s77, v130
	v_cvt_pk_bf16_f32 v96, v170, v171
	v_cvt_pk_bf16_f32 v97, v172, v173
	v_cvt_pk_bf16_f32 v98, v178, v179
	v_cvt_pk_bf16_f32 v99, v180, v181
	s_nop 1
	v_addc_co_u32_e32 v113, vcc, 0, v131, vcc
	global_store_dwordx4 v[112:113], v[116:119], off
	v_add_co_u32_e32 v112, vcc, s80, v130
	ds_write_b128 v183, v[96:99] offset:64
	s_nop 0
	v_addc_co_u32_e32 v113, vcc, 0, v131, vcc
	ds_read_b128 v[96:99], v184
	ds_read_b128 v[100:103], v184 offset:1152
	global_store_dwordx4 v[112:113], v[104:107], off
	s_nop 1
	v_add_co_u32_e32 v104, vcc, s83, v130
	s_nop 1
	v_addc_co_u32_e32 v105, vcc, 0, v131, vcc
	global_store_dwordx4 v[104:105], v[108:111], off
	v_add_co_u32_e32 v104, vcc, s85, v130
	s_nop 1
	v_addc_co_u32_e32 v105, vcc, 0, v131, vcc
	s_waitcnt lgkmcnt(0)
	global_store_dwordx4 v[104:105], v[96:99], off
	s_nop 1
	v_add_co_u32_e32 v96, vcc, s87, v130
	s_nop 1
	v_addc_co_u32_e32 v97, vcc, 0, v131, vcc
	global_store_dwordx4 v[96:97], v[100:103], off
	ds_read_b128 v[96:99], v152 offset:49152
	ds_read_b128 v[100:103], v152 offset:50176
	ds_read_b128 v[104:107], v151 offset:49152
	ds_read_b128 v[108:111], v151 offset:50176
	ds_read_b128 v[112:115], v150 offset:49152
	ds_read_b128 v[116:119], v150 offset:50176
	ds_read_b128 v[120:123], v149 offset:49152
	ds_read_b128 v[124:127], v149 offset:50176
	s_barrier
	s_waitcnt lgkmcnt(0)
	s_setprio 1
	s_waitcnt lgkmcnt(0)
	v_mfma_f32_16x16x32_bf16 v[32:35], v[8:11], v[96:99], v[32:35]
	v_mfma_f32_16x16x32_bf16 v[36:39], v[76:79], v[96:99], v[36:39]
	v_mfma_f32_16x16x32_bf16 v[40:43], v[8:11], v[104:107], v[40:43]
	v_mfma_f32_16x16x32_bf16 v[130:133], v[76:79], v[104:107], v[44:47]
	v_mfma_f32_16x16x32_bf16 v[150:153], v[8:11], v[112:115], v[48:51]
	v_mfma_f32_16x16x32_bf16 v[52:55], v[76:79], v[112:115], v[52:55]
	v_mfma_f32_16x16x32_bf16 v[8:11], v[8:11], v[120:123], v[56:59]
	v_mfma_f32_16x16x32_bf16 v[60:63], v[76:79], v[120:123], v[60:63]
	v_mfma_f32_16x16x32_bf16 v[56:59], v[0:3], v[100:103], v[32:35]
	v_mfma_f32_16x16x32_bf16 v[48:51], v[72:75], v[100:103], v[36:39]
	v_mfma_f32_16x16x32_bf16 v[44:47], v[0:3], v[108:111], v[40:43]
	v_mfma_f32_16x16x32_bf16 v[40:43], v[72:75], v[108:111], v[130:133]
	v_mfma_f32_16x16x32_bf16 v[36:39], v[0:3], v[116:119], v[150:153]
	v_mfma_f32_16x16x32_bf16 v[32:35], v[72:75], v[116:119], v[52:55]
	v_mfma_f32_16x16x32_bf16 v[8:11], v[0:3], v[124:127], v[8:11]
	v_mfma_f32_16x16x32_bf16 v[0:3], v[72:75], v[124:127], v[60:63]
	s_setprio 0
	s_setprio 1
	v_mfma_f32_16x16x32_bf16 v[4:7], v[88:91], v[96:99], v[4:7]
	v_mfma_f32_16x16x32_bf16 v[12:15], v[92:95], v[96:99], v[12:15]
	v_mfma_f32_16x16x32_bf16 v[16:19], v[88:91], v[104:107], v[16:19]
	v_mfma_f32_16x16x32_bf16 v[20:23], v[92:95], v[104:107], v[20:23]
	v_mfma_f32_16x16x32_bf16 v[72:75], v[88:91], v[112:115], v[24:27]
	v_mfma_f32_16x16x32_bf16 v[76:79], v[92:95], v[112:115], v[28:31]
	v_mfma_f32_16x16x32_bf16 v[64:67], v[88:91], v[120:123], v[64:67]
	v_mfma_f32_16x16x32_bf16 v[68:71], v[92:95], v[120:123], v[68:71]
	v_mfma_f32_16x16x32_bf16 v[60:63], v[80:83], v[100:103], v[4:7]
	v_mfma_f32_16x16x32_bf16 v[52:55], v[84:87], v[100:103], v[12:15]
	v_mfma_f32_16x16x32_bf16 v[28:31], v[80:83], v[108:111], v[16:19]
	v_mfma_f32_16x16x32_bf16 v[24:27], v[84:87], v[108:111], v[20:23]
	v_mfma_f32_16x16x32_bf16 v[20:23], v[80:83], v[116:119], v[72:75]
	v_mfma_f32_16x16x32_bf16 v[16:19], v[84:87], v[116:119], v[76:79]
	v_mfma_f32_16x16x32_bf16 v[12:15], v[80:83], v[124:127], v[64:67]
	v_mfma_f32_16x16x32_bf16 v[4:7], v[84:87], v[124:127], v[68:71]
	s_setprio 0
	v_cmp_gt_u32_e32 vcc, s88, v135
	s_barrier
	s_and_saveexec_b64 s[66:67], vcc
	s_cbranch_execz .LBB0_564
	s_barrier
